# K-loop back-edge rotation: loop-edge scalar work moved in front of the loop-back barrier in all six GEMM loops (on top of v17)
# baseline (speedup 1.0000x reference)
; #define PG8_STAGE(bufoff, gbase, voff) do { _Pragma("unroll") for (int _i = 0; _i < 2; ++_i) \
;         __builtin_amdgcn_global_load_lds((const unsigned*)((const char*)(gbase) + (voff)[_i]), (PG8_LAS unsigned*)(lds + (bufoff) + ldsw + _i * 8192), 16, 0, 0); } while (0)
; #define PG8_LDA(dst, b, h) do { _Pragma("unroll") for (int m = 0; m < 4; ++m) _Pragma("unroll") for (int k = 0; k < 2; ++k) dst[m][k] = *(const PG8_LAS bf16x8*)(lds + PG8_SA(b, h) + aoff + m * 2048 + k * 1024); } while (0)
; #define PG8_LDB(dst, b, h) do { _Pragma("unroll") for (int n = 0; n < 2; ++n) _Pragma("unroll") for (int k = 0; k < 2; ++k) dst[n][k] = *(const PG8_LAS bf16x8*)(lds + PG8_SB(b, h) + boff + n * 2048 + k * 1024); } while (0)
; #define PG8_WAIT_V(n) asm volatile("s_waitcnt vmcnt(" #n ")" ::: "memory")
; #define PG8_WAIT_L(n) asm volatile("s_waitcnt lgkmcnt(" #n ")" ::: "memory")
; #define PG8_BAR __builtin_amdgcn_s_barrier()
; #define PG8_SCHED __builtin_amdgcn_sched_barrier(0)
; template <class Epi, class Sched, bool ALIGN_EPI = false, bool SP2 = false>
; __device__ __forceinline__ void gemm_phase(PG8_LAS unsigned char* lds, const Gemm g, const Sched& S, const Epi& E) {
;     ...
;         const bool has_next = S.next(ui + 1, nxt);
;         const char* nA = has_next ? (const char*)g.A + (size_t)nxt.pm * tstep : cA; const char* nB = has_next ? (const char*)g.Bt + (size_t)nxt.pn * tstep : cB;
;         for (int t = 0; t < nt; t += 2) {
;             const bool last = (t == nt - 2);
;             const char* a1 = cA + (size_t)(t + 1) * kstep;
;             const char* a2 = last ? nA : cA + (size_t)(t + 2) * kstep; const char* b2 = last ? nB : cB + (size_t)(t + 2) * kstep;
;             const char* a3 = a2 + kstep; const char* b3 = b2 + kstep;
;             if (last && has_next) S.a_ready(nxt);
;             if constexpr (SP2) {
;             PG8_LDB(B0, 0, 0); PG8_LDB(B1, 0, 1); PG8_SCHED; PG8_LDA(At, 0, 0); PG8_STAGE(PG8_SA(1, 1), a1 + hstep, voffA);
;             PG8_WAIT_V(8); PG8_WAIT_L(0); PG8_BAR; PG8_MMA(0, 0, At, B0); PG8_MMA(0, 1, At, B1); PG8_BAR; PG8_SCHED;
;             PG8_LDA(At, 0, 1); PG8_STAGE(PG8_SB(0, 0), b2, voffB); PG8_STAGE(PG8_SB(0, 1), b2 + hstep, voffB); PG8_STAGE(PG8_SA(0, 0), a2, voffA);
;             PG8_WAIT_V(8); PG8_WAIT_L(0); PG8_BAR; PG8_MMA(1, 0, At, B0); PG8_MMA(1, 1, At, B1); PG8_BAR; PG8_SCHED;
.LBB0_224:
	s_ashr_i32 s15, s14, 31
	s_lshl_b64 s[16:17], s[14:15], 19
	s_add_u32 s16, s34, s16
	s_addc_u32 s17, s35, s17
	s_and_b64 s[18:19], s[2:3], exec
	s_cselect_b32 s5, s17, s23
	s_cselect_b32 s15, s16, s22
	s_ashr_i32 s13, s12, 31
	s_lshl_b64 s[18:19], s[12:13], 19
	s_add_u32 s18, s38, s18
	s_addc_u32 s19, s39, s19
	s_and_b64 s[26:27], s[2:3], exec
	s_cselect_b32 s13, s19, s25
	s_cselect_b32 s21, s18, s24
	s_add_u32 s22, s22, 0x40080
	s_addc_u32 s23, s23, 0
	s_add_u32 s49, s24, 0x100
	s_addc_u32 s50, s25, 0
	s_mov_b32 s51, -2
	s_add_u32 s24, s22, 0xfffc0080
	s_addc_u32 s25, s23, -1
	s_add_i32 s52, 0, 0x10000
	s_cmp_eq_u32 s51, 12
	s_cselect_b32 s27, s5, s25
	s_cselect_b32 s26, s15, s24
	v_add_u32_e32 v138, s52, v149
	s_cselect_b32 s25, s13, s50
	s_cselect_b32 s24, s21, s49
	s_add_i32 s55, 0, 0x14000
	ds_read_b128 v[144:147], v138
	ds_read_b128 v[154:157], v138 offset:1024
	ds_read_b128 v[158:161], v138 offset:2048
	ds_read_b128 v[162:165], v138 offset:3072
	v_add_u32_e32 v138, s55, v149
	ds_read_b128 v[166:169], v138
	ds_read_b128 v[170:173], v138 offset:1024
	ds_read_b128 v[174:177], v138 offset:2048
	ds_read_b128 v[178:181], v138 offset:3072
	v_lshl_add_u64 v[138:139], s[22:23], 0, v[136:137]
	s_add_i32 m0, s41, 0xc000
	ds_read_b128 v[182:185], v152
	ds_read_b128 v[186:189], v152 offset:1024
	ds_read_b128 v[190:193], v152 offset:2048
	ds_read_b128 v[194:197], v152 offset:3072
	ds_read_b128 v[198:201], v152 offset:4096
	ds_read_b128 v[202:205], v152 offset:5120
	ds_read_b128 v[224:227], v152 offset:6144
	ds_read_b128 v[228:231], v152 offset:7168
	global_load_lds_dwordx4 v[138:139], off
	v_lshl_add_u64 v[138:139], s[22:23], 0, v[142:143]
	s_add_i32 m0, s41, 0xe000
	s_nop 0
	global_load_lds_dwordx4 v[138:139], off
	s_waitcnt vmcnt(8)
	s_waitcnt lgkmcnt(0)
	s_barrier
	s_setprio 1
	s_waitcnt lgkmcnt(0)
	v_mfma_f32_16x16x32_bf16 v[126:129], v[144:147], v[182:185], 0
	v_mfma_f32_16x16x32_bf16 v[122:125], v[158:161], v[182:185], 0
	v_mfma_f32_16x16x32_bf16 v[110:113], v[144:147], v[190:193], 0
	v_mfma_f32_16x16x32_bf16 v[106:109], v[158:161], v[190:193], 0
	v_mfma_f32_16x16x32_bf16 v[94:97], v[144:147], v[198:201], 0
	v_mfma_f32_16x16x32_bf16 v[90:93], v[158:161], v[198:201], 0
	v_mfma_f32_16x16x32_bf16 v[78:81], v[144:147], v[224:227], 0
	v_mfma_f32_16x16x32_bf16 v[74:77], v[158:161], v[224:227], 0
	v_mfma_f32_16x16x32_bf16 v[126:129], v[154:157], v[186:189], v[126:129]
	v_mfma_f32_16x16x32_bf16 v[122:125], v[162:165], v[186:189], v[122:125]
	v_mfma_f32_16x16x32_bf16 v[110:113], v[154:157], v[194:197], v[110:113]
	v_mfma_f32_16x16x32_bf16 v[106:109], v[162:165], v[194:197], v[106:109]
	v_mfma_f32_16x16x32_bf16 v[94:97], v[154:157], v[202:205], v[94:97]
	v_mfma_f32_16x16x32_bf16 v[90:93], v[162:165], v[202:205], v[90:93]
	v_mfma_f32_16x16x32_bf16 v[78:81], v[154:157], v[228:231], v[78:81]
	v_mfma_f32_16x16x32_bf16 v[74:77], v[162:165], v[228:231], v[74:77]
	s_setprio 0
	s_setprio 1
	v_mfma_f32_16x16x32_bf16 v[118:121], v[166:169], v[182:185], 0
	v_mfma_f32_16x16x32_bf16 v[114:117], v[174:177], v[182:185], 0
	v_mfma_f32_16x16x32_bf16 v[102:105], v[166:169], v[190:193], 0
	v_mfma_f32_16x16x32_bf16 v[98:101], v[174:177], v[190:193], 0
	v_mfma_f32_16x16x32_bf16 v[86:89], v[166:169], v[198:201], 0
	v_mfma_f32_16x16x32_bf16 v[82:85], v[174:177], v[198:201], 0
	v_mfma_f32_16x16x32_bf16 v[70:73], v[166:169], v[224:227], 0
	v_mfma_f32_16x16x32_bf16 v[66:69], v[174:177], v[224:227], 0
	v_mfma_f32_16x16x32_bf16 v[118:121], v[170:173], v[186:189], v[118:121]
	v_mfma_f32_16x16x32_bf16 v[114:117], v[178:181], v[186:189], v[114:117]
	v_mfma_f32_16x16x32_bf16 v[102:105], v[170:173], v[194:197], v[102:105]
	v_mfma_f32_16x16x32_bf16 v[98:101], v[178:181], v[194:197], v[98:101]
	v_mfma_f32_16x16x32_bf16 v[86:89], v[170:173], v[202:205], v[86:89]
	v_mfma_f32_16x16x32_bf16 v[82:85], v[178:181], v[202:205], v[82:85]
	v_mfma_f32_16x16x32_bf16 v[70:73], v[170:173], v[228:231], v[70:73]
	v_mfma_f32_16x16x32_bf16 v[66:69], v[178:181], v[228:231], v[66:69]
	s_setprio 0
	s_barrier
	s_add_i32 s52, s52, s31
	v_lshl_add_u64 v[138:139], s[24:25], 0, v[0:1]
	s_mov_b32 m0, s52
	ds_read_b128 v[182:185], v152 offset:16384
	ds_read_b128 v[186:189], v152 offset:17408
	ds_read_b128 v[190:193], v152 offset:18432
	ds_read_b128 v[194:197], v152 offset:19456
	ds_read_b128 v[198:201], v152 offset:20480
	ds_read_b128 v[202:205], v152 offset:21504
	ds_read_b128 v[224:227], v152 offset:22528
	ds_read_b128 v[228:231], v152 offset:23552
	global_load_lds_dwordx4 v[138:139], off
	s_add_i32 m0, s52, 0x2000
	s_add_u32 s52, s24, 0x40000
	v_lshl_add_u64 v[140:141], s[24:25], 0, v[134:135]
	s_addc_u32 s53, s25, 0
	s_add_i32 s55, s55, s31
	global_load_lds_dwordx4 v[140:141], off
	v_lshl_add_u64 v[232:233], s[52:53], 0, v[0:1]
	s_mov_b32 m0, s55
	v_lshl_add_u64 v[234:235], s[26:27], 0, v[132:133]
	global_load_lds_dwordx4 v[232:233], off
	v_lshl_add_u64 v[232:233], s[52:53], 0, v[134:135]
	s_add_i32 m0, s55, 0x2000
	s_nop 0
	global_load_lds_dwordx4 v[232:233], off
	v_lshl_add_u64 v[232:233], s[26:27], 0, v[130:131]
	s_mov_b32 m0, s41
	s_nop 0
	global_load_lds_dwordx4 v[232:233], off
	s_mov_b32 m0, s42
	s_nop 0
	global_load_lds_dwordx4 v[234:235], off
	s_waitcnt vmcnt(8)
	s_waitcnt lgkmcnt(0)
	s_barrier
; #define PG8_STAGE(bufoff, gbase, voff) do { _Pragma("unroll") for (int _i = 0; _i < 2; ++_i) \
;         __builtin_amdgcn_global_load_lds((const unsigned*)((const char*)(gbase) + (voff)[_i]), (PG8_LAS unsigned*)(lds + (bufoff) + ldsw + _i * 8192), 16, 0, 0); } while (0)
; #define PG8_LDA(dst, b, h) do { _Pragma("unroll") for (int m = 0; m < 4; ++m) _Pragma("unroll") for (int k = 0; k < 2; ++k) dst[m][k] = *(const PG8_LAS bf16x8*)(lds + PG8_SA(b, h) + aoff + m * 2048 + k * 1024); } while (0)
; #define PG8_LDB(dst, b, h) do { _Pragma("unroll") for (int n = 0; n < 2; ++n) _Pragma("unroll") for (int k = 0; k < 2; ++k) dst[n][k] = *(const PG8_LAS bf16x8*)(lds + PG8_SB(b, h) + boff + n * 2048 + k * 1024); } while (0)
; #define PG8_MMA(ai, bj, At, Bt) do { __builtin_amdgcn_s_setprio(1); _Pragma("unroll") for (int m = 0; m < 4; ++m) _Pragma("unroll") for (int n = 0; n < 2; ++n) _Pragma("unroll") for (int k = 0; k < 2; ++k) \
;         acc[ai][bj][m][n] = __builtin_amdgcn_mfma_f32_16x16x32_bf16(Bt[n][k], At[m][k], acc[ai][bj][m][n], 0, 0, 0); __builtin_amdgcn_s_setprio(0); } while (0)
; #define PG8_WAIT_V(n) asm volatile("s_waitcnt vmcnt(" #n ")" ::: "memory")
; #define PG8_WAIT_L(n) asm volatile("s_waitcnt lgkmcnt(" #n ")" ::: "memory")
; #define PG8_BAR __builtin_amdgcn_s_barrier()
; #define PG8_SCHED __builtin_amdgcn_sched_barrier(0)
; template <class Epi, class Sched, bool ALIGN_EPI = false, bool SP2 = false>
; __device__ __forceinline__ void gemm_phase(PG8_LAS unsigned char* lds, const Gemm g, const Sched& S, const Epi& E) {
;     ...
;             PG8_WAIT_V(8); PG8_WAIT_L(0); PG8_BAR; PG8_MMA(1, 0, At, B0); PG8_MMA(1, 1, At, B1); PG8_BAR; PG8_SCHED;
;             PG8_LDB(B0, 1, 0); PG8_LDB(B1, 1, 1); PG8_SCHED; PG8_LDA(At, 1, 0); PG8_STAGE(PG8_SA(0, 1), a2 + hstep, voffA);
;             PG8_WAIT_V(8); PG8_WAIT_L(0); PG8_BAR; PG8_MMA(0, 0, At, B0); PG8_MMA(0, 1, At, B1); PG8_BAR; PG8_SCHED;
	s_setprio 1
	s_waitcnt lgkmcnt(0)
	v_mfma_f32_16x16x32_bf16 v[62:65], v[144:147], v[182:185], 0
	v_mfma_f32_16x16x32_bf16 v[58:61], v[158:161], v[182:185], 0
	v_mfma_f32_16x16x32_bf16 v[46:49], v[144:147], v[190:193], 0
	v_mfma_f32_16x16x32_bf16 v[42:45], v[158:161], v[190:193], 0
	v_mfma_f32_16x16x32_bf16 v[30:33], v[144:147], v[198:201], 0
	v_mfma_f32_16x16x32_bf16 v[26:29], v[158:161], v[198:201], 0
	v_mfma_f32_16x16x32_bf16 v[14:17], v[144:147], v[224:227], 0
	v_mfma_f32_16x16x32_bf16 v[10:13], v[158:161], v[224:227], 0
	v_mfma_f32_16x16x32_bf16 v[62:65], v[154:157], v[186:189], v[62:65]
	v_mfma_f32_16x16x32_bf16 v[58:61], v[162:165], v[186:189], v[58:61]
	v_mfma_f32_16x16x32_bf16 v[46:49], v[154:157], v[194:197], v[46:49]
	v_mfma_f32_16x16x32_bf16 v[42:45], v[162:165], v[194:197], v[42:45]
	v_mfma_f32_16x16x32_bf16 v[30:33], v[154:157], v[202:205], v[30:33]
	v_mfma_f32_16x16x32_bf16 v[26:29], v[162:165], v[202:205], v[26:29]
	v_mfma_f32_16x16x32_bf16 v[14:17], v[154:157], v[228:231], v[14:17]
	v_mfma_f32_16x16x32_bf16 v[10:13], v[162:165], v[228:231], v[10:13]
	s_setprio 0
	s_setprio 1
	v_mfma_f32_16x16x32_bf16 v[54:57], v[166:169], v[182:185], 0
	v_mfma_f32_16x16x32_bf16 v[50:53], v[174:177], v[182:185], 0
	v_mfma_f32_16x16x32_bf16 v[38:41], v[166:169], v[190:193], 0
	v_mfma_f32_16x16x32_bf16 v[34:37], v[174:177], v[190:193], 0
	v_mfma_f32_16x16x32_bf16 v[22:25], v[166:169], v[198:201], 0
	v_mfma_f32_16x16x32_bf16 v[18:21], v[174:177], v[198:201], 0
	v_mfma_f32_16x16x32_bf16 v[6:9], v[166:169], v[224:227], 0
	v_mfma_f32_16x16x32_bf16 v[2:5], v[174:177], v[224:227], 0
	v_mfma_f32_16x16x32_bf16 v[54:57], v[170:173], v[186:189], v[54:57]
	v_mfma_f32_16x16x32_bf16 v[50:53], v[178:181], v[186:189], v[50:53]
	v_mfma_f32_16x16x32_bf16 v[38:41], v[170:173], v[194:197], v[38:41]
	v_mfma_f32_16x16x32_bf16 v[34:37], v[178:181], v[194:197], v[34:37]
	v_mfma_f32_16x16x32_bf16 v[22:25], v[170:173], v[202:205], v[22:25]
	v_mfma_f32_16x16x32_bf16 v[18:21], v[178:181], v[202:205], v[18:21]
	v_mfma_f32_16x16x32_bf16 v[6:9], v[170:173], v[228:231], v[6:9]
	v_mfma_f32_16x16x32_bf16 v[2:5], v[178:181], v[228:231], v[2:5]
	s_setprio 0
	s_barrier
	s_add_i32 s52, 0, 0x18000
	v_add_u32_e32 v153, s52, v149
	s_add_i32 s53, 0, 0x1c000
	ds_read_b128 v[144:147], v153
	ds_read_b128 v[154:157], v153 offset:1024
	ds_read_b128 v[158:161], v153 offset:2048
	ds_read_b128 v[162:165], v153 offset:3072
	v_add_u32_e32 v153, s53, v149
	ds_read_b128 v[166:169], v153
	ds_read_b128 v[170:173], v153 offset:1024
	ds_read_b128 v[174:177], v153 offset:2048
	ds_read_b128 v[178:181], v153 offset:3072
	s_add_u32 s26, s26, 0x40000
	s_addc_u32 s27, s27, 0
	s_mov_b32 m0, s43
	v_lshl_add_u64 v[236:237], s[26:27], 0, v[130:131]
	ds_read_b128 v[182:185], v152 offset:32768
	ds_read_b128 v[186:189], v152 offset:33792
	ds_read_b128 v[190:193], v152 offset:34816
	ds_read_b128 v[194:197], v152 offset:35840
	ds_read_b128 v[198:201], v152 offset:36864
	ds_read_b128 v[202:205], v152 offset:37888
	ds_read_b128 v[224:227], v152 offset:38912
	ds_read_b128 v[228:231], v152 offset:39936
	global_load_lds_dwordx4 v[236:237], off
	v_lshl_add_u64 v[236:237], s[26:27], 0, v[132:133]
	s_mov_b32 m0, s44
	s_nop 0
	global_load_lds_dwordx4 v[236:237], off
	s_waitcnt vmcnt(8)
	s_waitcnt lgkmcnt(0)
	s_barrier
	s_setprio 1
	s_waitcnt lgkmcnt(0)
	v_mfma_f32_16x16x32_bf16 v[126:129], v[144:147], v[182:185], v[126:129]
	v_mfma_f32_16x16x32_bf16 v[122:125], v[158:161], v[182:185], v[122:125]
	v_mfma_f32_16x16x32_bf16 v[110:113], v[144:147], v[190:193], v[110:113]
	v_mfma_f32_16x16x32_bf16 v[106:109], v[158:161], v[190:193], v[106:109]
	v_mfma_f32_16x16x32_bf16 v[94:97], v[144:147], v[198:201], v[94:97]
	v_mfma_f32_16x16x32_bf16 v[90:93], v[158:161], v[198:201], v[90:93]
	v_mfma_f32_16x16x32_bf16 v[78:81], v[144:147], v[224:227], v[78:81]
	v_mfma_f32_16x16x32_bf16 v[74:77], v[158:161], v[224:227], v[74:77]
	v_mfma_f32_16x16x32_bf16 v[126:129], v[154:157], v[186:189], v[126:129]
	v_mfma_f32_16x16x32_bf16 v[122:125], v[162:165], v[186:189], v[122:125]
	v_mfma_f32_16x16x32_bf16 v[110:113], v[154:157], v[194:197], v[110:113]
	v_mfma_f32_16x16x32_bf16 v[106:109], v[162:165], v[194:197], v[106:109]
	v_mfma_f32_16x16x32_bf16 v[94:97], v[154:157], v[202:205], v[94:97]
	v_mfma_f32_16x16x32_bf16 v[90:93], v[162:165], v[202:205], v[90:93]
	v_mfma_f32_16x16x32_bf16 v[78:81], v[154:157], v[228:231], v[78:81]
	v_mfma_f32_16x16x32_bf16 v[74:77], v[162:165], v[228:231], v[74:77]
	s_setprio 0
	s_setprio 1
	v_mfma_f32_16x16x32_bf16 v[118:121], v[166:169], v[182:185], v[118:121]
	v_mfma_f32_16x16x32_bf16 v[114:117], v[174:177], v[182:185], v[114:117]
	v_mfma_f32_16x16x32_bf16 v[102:105], v[166:169], v[190:193], v[102:105]
	v_mfma_f32_16x16x32_bf16 v[98:101], v[174:177], v[190:193], v[98:101]
	v_mfma_f32_16x16x32_bf16 v[86:89], v[166:169], v[198:201], v[86:89]
	v_mfma_f32_16x16x32_bf16 v[82:85], v[174:177], v[198:201], v[82:85]
	v_mfma_f32_16x16x32_bf16 v[70:73], v[166:169], v[224:227], v[70:73]
	v_mfma_f32_16x16x32_bf16 v[66:69], v[174:177], v[224:227], v[66:69]
	v_mfma_f32_16x16x32_bf16 v[118:121], v[170:173], v[186:189], v[118:121]
	v_mfma_f32_16x16x32_bf16 v[114:117], v[178:181], v[186:189], v[114:117]
	v_mfma_f32_16x16x32_bf16 v[102:105], v[170:173], v[194:197], v[102:105]
	v_mfma_f32_16x16x32_bf16 v[98:101], v[178:181], v[194:197], v[98:101]
	v_mfma_f32_16x16x32_bf16 v[86:89], v[170:173], v[202:205], v[86:89]
	v_mfma_f32_16x16x32_bf16 v[82:85], v[178:181], v[202:205], v[82:85]
	v_mfma_f32_16x16x32_bf16 v[70:73], v[170:173], v[228:231], v[70:73]
	v_mfma_f32_16x16x32_bf16 v[66:69], v[178:181], v[228:231], v[66:69]
	s_setprio 0
	s_barrier
; #define PG8_STAGE(bufoff, gbase, voff) do { _Pragma("unroll") for (int _i = 0; _i < 2; ++_i) \
;         __builtin_amdgcn_global_load_lds((const unsigned*)((const char*)(gbase) + (voff)[_i]), (PG8_LAS unsigned*)(lds + (bufoff) + ldsw + _i * 8192), 16, 0, 0); } while (0)
; #define PG8_LDA(dst, b, h) do { _Pragma("unroll") for (int m = 0; m < 4; ++m) _Pragma("unroll") for (int k = 0; k < 2; ++k) dst[m][k] = *(const PG8_LAS bf16x8*)(lds + PG8_SA(b, h) + aoff + m * 2048 + k * 1024); } while (0)
; #define PG8_LDB(dst, b, h) do { _Pragma("unroll") for (int n = 0; n < 2; ++n) _Pragma("unroll") for (int k = 0; k < 2; ++k) dst[n][k] = *(const PG8_LAS bf16x8*)(lds + PG8_SB(b, h) + boff + n * 2048 + k * 1024); } while (0)
; template <class Epi, class Sched, bool ALIGN_EPI = false, bool SP2 = false>
; __device__ __forceinline__ void gemm_phase(PG8_LAS unsigned char* lds, const Gemm g, const Sched& S, const Epi& E) {
;     ...
;         for (int t = 0; t < nt; t += 2) {
;             const bool last = (t == nt - 2);
;             const char* a1 = cA + (size_t)(t + 1) * kstep;
;             const char* a2 = last ? nA : cA + (size_t)(t + 2) * kstep; const char* b2 = last ? nB : cB + (size_t)(t + 2) * kstep;
;             const char* a3 = a2 + kstep; const char* b3 = b2 + kstep;
;             if (last && has_next) S.a_ready(nxt);
;             if constexpr (SP2) {
;             PG8_LDB(B0, 0, 0); PG8_LDB(B1, 0, 1); PG8_SCHED; PG8_LDA(At, 0, 0); PG8_STAGE(PG8_SA(1, 1), a1 + hstep, voffA);
;             PG8_WAIT_V(8); PG8_WAIT_L(0); PG8_BAR; PG8_MMA(0, 0, At, B0); PG8_MMA(0, 1, At, B1); PG8_BAR; PG8_SCHED;
;             PG8_LDA(At, 0, 1); PG8_STAGE(PG8_SB(0, 0), b2, voffB); PG8_STAGE(PG8_SB(0, 1), b2 + hstep, voffB); PG8_STAGE(PG8_SA(0, 0), a2, voffA);
;             PG8_WAIT_V(8); PG8_WAIT_L(0); PG8_BAR; PG8_MMA(1, 0, At, B0); PG8_MMA(1, 1, At, B1); PG8_BAR; PG8_SCHED;
;             PG8_LDB(B0, 1, 0); PG8_LDB(B1, 1, 1); PG8_SCHED; PG8_LDA(At, 1, 0); PG8_STAGE(PG8_SA(0, 1), a2 + hstep, voffA);
;             PG8_WAIT_V(8); PG8_WAIT_L(0); PG8_BAR; PG8_MMA(0, 0, At, B0); PG8_MMA(0, 1, At, B1); PG8_BAR; PG8_SCHED;
;             PG8_LDA(At, 1, 1); PG8_STAGE(PG8_SB(1, 0), b3, voffB); PG8_STAGE(PG8_SB(1, 1), b3 + hstep, voffB); PG8_STAGE(PG8_SA(1, 0), a3, voffA);
;             PG8_WAIT_V(8); PG8_WAIT_L(0); PG8_BAR; PG8_MMA(1, 0, At, B0); PG8_MMA(1, 1, At, B1); PG8_BAR; PG8_SCHED;
	s_add_i32 s26, s52, s31
	v_lshl_add_u64 v[138:139], v[138:139], 0, s[86:87]
	s_mov_b32 m0, s26
	ds_read_b128 v[182:185], v152 offset:49152
	ds_read_b128 v[186:189], v152 offset:50176
	ds_read_b128 v[190:193], v152 offset:51200
	ds_read_b128 v[194:197], v152 offset:52224
	ds_read_b128 v[198:201], v152 offset:53248
	ds_read_b128 v[202:205], v152 offset:54272
	ds_read_b128 v[224:227], v152 offset:55296
	ds_read_b128 v[228:231], v152 offset:56320
	global_load_lds_dwordx4 v[138:139], off
	s_add_i32 m0, s26, 0x2000
	s_add_u32 s24, s24, 0x40080
	v_lshl_add_u64 v[138:139], v[140:141], 0, s[86:87]
	s_addc_u32 s25, s25, 0
	s_add_i32 s26, s53, s31
	global_load_lds_dwordx4 v[138:139], off
	v_lshl_add_u64 v[138:139], s[24:25], 0, v[0:1]
	s_mov_b32 m0, s26
	s_nop 0
	global_load_lds_dwordx4 v[138:139], off
	v_lshl_add_u64 v[138:139], s[24:25], 0, v[134:135]
	s_add_i32 m0, s26, 0x2000
	s_nop 0
	global_load_lds_dwordx4 v[138:139], off
	v_lshl_add_u64 v[138:139], v[232:233], 0, s[86:87]
	s_mov_b32 m0, s45
	s_nop 0
	global_load_lds_dwordx4 v[138:139], off
	v_lshl_add_u64 v[138:139], v[234:235], 0, s[86:87]
	s_mov_b32 m0, s46
	s_nop 0
	global_load_lds_dwordx4 v[138:139], off
	s_waitcnt vmcnt(8)
	s_waitcnt lgkmcnt(0)
	s_barrier
	s_setprio 1
	s_waitcnt lgkmcnt(0)
	v_mfma_f32_16x16x32_bf16 v[62:65], v[144:147], v[182:185], v[62:65]
	v_mfma_f32_16x16x32_bf16 v[58:61], v[158:161], v[182:185], v[58:61]
	v_mfma_f32_16x16x32_bf16 v[46:49], v[144:147], v[190:193], v[46:49]
	v_mfma_f32_16x16x32_bf16 v[42:45], v[158:161], v[190:193], v[42:45]
	v_mfma_f32_16x16x32_bf16 v[30:33], v[144:147], v[198:201], v[30:33]
	v_mfma_f32_16x16x32_bf16 v[26:29], v[158:161], v[198:201], v[26:29]
	v_mfma_f32_16x16x32_bf16 v[14:17], v[144:147], v[224:227], v[14:17]
	v_mfma_f32_16x16x32_bf16 v[10:13], v[158:161], v[224:227], v[10:13]
	v_mfma_f32_16x16x32_bf16 v[62:65], v[154:157], v[186:189], v[62:65]
	v_mfma_f32_16x16x32_bf16 v[58:61], v[162:165], v[186:189], v[58:61]
	v_mfma_f32_16x16x32_bf16 v[46:49], v[154:157], v[194:197], v[46:49]
	v_mfma_f32_16x16x32_bf16 v[42:45], v[162:165], v[194:197], v[42:45]
	v_mfma_f32_16x16x32_bf16 v[30:33], v[154:157], v[202:205], v[30:33]
	v_mfma_f32_16x16x32_bf16 v[26:29], v[162:165], v[202:205], v[26:29]
	v_mfma_f32_16x16x32_bf16 v[14:17], v[154:157], v[228:231], v[14:17]
	v_mfma_f32_16x16x32_bf16 v[10:13], v[162:165], v[228:231], v[10:13]
	s_setprio 0
	s_setprio 1
	v_mfma_f32_16x16x32_bf16 v[54:57], v[166:169], v[182:185], v[54:57]
	v_mfma_f32_16x16x32_bf16 v[50:53], v[174:177], v[182:185], v[50:53]
	v_mfma_f32_16x16x32_bf16 v[38:41], v[166:169], v[190:193], v[38:41]
	v_mfma_f32_16x16x32_bf16 v[34:37], v[174:177], v[190:193], v[34:37]
	v_mfma_f32_16x16x32_bf16 v[22:25], v[166:169], v[198:201], v[22:25]
	v_mfma_f32_16x16x32_bf16 v[18:21], v[174:177], v[198:201], v[18:21]
	v_mfma_f32_16x16x32_bf16 v[6:9], v[166:169], v[224:227], v[6:9]
	v_mfma_f32_16x16x32_bf16 v[2:5], v[174:177], v[224:227], v[2:5]
	v_mfma_f32_16x16x32_bf16 v[54:57], v[170:173], v[186:189], v[54:57]
	v_mfma_f32_16x16x32_bf16 v[50:53], v[178:181], v[186:189], v[50:53]
	v_mfma_f32_16x16x32_bf16 v[38:41], v[170:173], v[194:197], v[38:41]
	v_mfma_f32_16x16x32_bf16 v[34:37], v[178:181], v[194:197], v[34:37]
	v_mfma_f32_16x16x32_bf16 v[22:25], v[170:173], v[202:205], v[22:25]
	v_mfma_f32_16x16x32_bf16 v[18:21], v[178:181], v[202:205], v[18:21]
	v_mfma_f32_16x16x32_bf16 v[6:9], v[170:173], v[228:231], v[6:9]
	v_mfma_f32_16x16x32_bf16 v[2:5], v[178:181], v[228:231], v[2:5]
	s_setprio 0
	s_add_i32 s51, s51, 2
	s_add_u32 s22, s22, 0x100
	s_addc_u32 s23, s23, 0
	s_add_u32 s49, s49, 0x100
	s_addc_u32 s50, s50, 0
	s_add_u32 s24, s22, 0xfffc0080
	s_addc_u32 s25, s23, -1
	s_add_i32 s52, 0, 0x10000
	s_cmp_eq_u32 s51, 12
	s_cselect_b32 s27, s5, s25
	s_cselect_b32 s26, s15, s24
	v_add_u32_e32 v138, s52, v149
	s_cselect_b32 s25, s13, s50
	s_cselect_b32 s24, s21, s49
	s_add_i32 s55, 0, 0x14000
	s_cmp_gt_u32 s51, 13
	s_barrier
	s_cbranch_scc1 .Lpeel_exit_sw
.LBB0_225:
	ds_read_b128 v[144:147], v138
	ds_read_b128 v[154:157], v138 offset:1024
	ds_read_b128 v[158:161], v138 offset:2048
	ds_read_b128 v[162:165], v138 offset:3072
	v_add_u32_e32 v138, s55, v149
	ds_read_b128 v[166:169], v138
	ds_read_b128 v[170:173], v138 offset:1024
	ds_read_b128 v[174:177], v138 offset:2048
	ds_read_b128 v[178:181], v138 offset:3072
	v_lshl_add_u64 v[138:139], s[22:23], 0, v[136:137]
	s_add_i32 m0, s41, 0xc000
	ds_read_b128 v[182:185], v152
	ds_read_b128 v[186:189], v152 offset:1024
	ds_read_b128 v[190:193], v152 offset:2048
	ds_read_b128 v[194:197], v152 offset:3072
	ds_read_b128 v[198:201], v152 offset:4096
	ds_read_b128 v[202:205], v152 offset:5120
	ds_read_b128 v[224:227], v152 offset:6144
	ds_read_b128 v[228:231], v152 offset:7168
	global_load_lds_dwordx4 v[138:139], off
	v_lshl_add_u64 v[138:139], s[22:23], 0, v[142:143]
	s_add_i32 m0, s41, 0xe000
	s_nop 0
	global_load_lds_dwordx4 v[138:139], off
	s_waitcnt vmcnt(8)
	s_waitcnt lgkmcnt(0)
	s_barrier
; #define PG8_STAGE(bufoff, gbase, voff) do { _Pragma("unroll") for (int _i = 0; _i < 2; ++_i) \
;         __builtin_amdgcn_global_load_lds((const unsigned*)((const char*)(gbase) + (voff)[_i]), (PG8_LAS unsigned*)(lds + (bufoff) + ldsw + _i * 8192), 16, 0, 0); } while (0)
; #define PG8_LDA(dst, b, h) do { _Pragma("unroll") for (int m = 0; m < 4; ++m) _Pragma("unroll") for (int k = 0; k < 2; ++k) dst[m][k] = *(const PG8_LAS bf16x8*)(lds + PG8_SA(b, h) + aoff + m * 2048 + k * 1024); } while (0)
; #define PG8_MMA(ai, bj, At, Bt) do { __builtin_amdgcn_s_setprio(1); _Pragma("unroll") for (int m = 0; m < 4; ++m) _Pragma("unroll") for (int n = 0; n < 2; ++n) _Pragma("unroll") for (int k = 0; k < 2; ++k) \
;         acc[ai][bj][m][n] = __builtin_amdgcn_mfma_f32_16x16x32_bf16(Bt[n][k], At[m][k], acc[ai][bj][m][n], 0, 0, 0); __builtin_amdgcn_s_setprio(0); } while (0)
; #define PG8_WAIT_V(n) asm volatile("s_waitcnt vmcnt(" #n ")" ::: "memory")
; #define PG8_WAIT_L(n) asm volatile("s_waitcnt lgkmcnt(" #n ")" ::: "memory")
; #define PG8_BAR __builtin_amdgcn_s_barrier()
; #define PG8_SCHED __builtin_amdgcn_sched_barrier(0)
; template <class Epi, class Sched, bool ALIGN_EPI = false, bool SP2 = false>
; __device__ __forceinline__ void gemm_phase(PG8_LAS unsigned char* lds, const Gemm g, const Sched& S, const Epi& E) {
;     ...
;             PG8_WAIT_V(8); PG8_WAIT_L(0); PG8_BAR; PG8_MMA(0, 0, At, B0); PG8_MMA(0, 1, At, B1); PG8_BAR; PG8_SCHED;
;             PG8_LDA(At, 0, 1); PG8_STAGE(PG8_SB(0, 0), b2, voffB); PG8_STAGE(PG8_SB(0, 1), b2 + hstep, voffB); PG8_STAGE(PG8_SA(0, 0), a2, voffA);
;             PG8_WAIT_V(8); PG8_WAIT_L(0); PG8_BAR; PG8_MMA(1, 0, At, B0); PG8_MMA(1, 1, At, B1); PG8_BAR; PG8_SCHED;
	s_setprio 1
	s_waitcnt lgkmcnt(0)
	v_mfma_f32_16x16x32_bf16 v[126:129], v[144:147], v[182:185], v[126:129]
	v_mfma_f32_16x16x32_bf16 v[122:125], v[158:161], v[182:185], v[122:125]
	v_mfma_f32_16x16x32_bf16 v[110:113], v[144:147], v[190:193], v[110:113]
	v_mfma_f32_16x16x32_bf16 v[106:109], v[158:161], v[190:193], v[106:109]
	v_mfma_f32_16x16x32_bf16 v[94:97], v[144:147], v[198:201], v[94:97]
	v_mfma_f32_16x16x32_bf16 v[90:93], v[158:161], v[198:201], v[90:93]
	v_mfma_f32_16x16x32_bf16 v[78:81], v[144:147], v[224:227], v[78:81]
	v_mfma_f32_16x16x32_bf16 v[74:77], v[158:161], v[224:227], v[74:77]
	v_mfma_f32_16x16x32_bf16 v[126:129], v[154:157], v[186:189], v[126:129]
	v_mfma_f32_16x16x32_bf16 v[122:125], v[162:165], v[186:189], v[122:125]
	v_mfma_f32_16x16x32_bf16 v[110:113], v[154:157], v[194:197], v[110:113]
	v_mfma_f32_16x16x32_bf16 v[106:109], v[162:165], v[194:197], v[106:109]
	v_mfma_f32_16x16x32_bf16 v[94:97], v[154:157], v[202:205], v[94:97]
	v_mfma_f32_16x16x32_bf16 v[90:93], v[162:165], v[202:205], v[90:93]
	v_mfma_f32_16x16x32_bf16 v[78:81], v[154:157], v[228:231], v[78:81]
	v_mfma_f32_16x16x32_bf16 v[74:77], v[162:165], v[228:231], v[74:77]
	s_setprio 0
	s_setprio 1
	v_mfma_f32_16x16x32_bf16 v[118:121], v[166:169], v[182:185], v[118:121]
	v_mfma_f32_16x16x32_bf16 v[114:117], v[174:177], v[182:185], v[114:117]
	v_mfma_f32_16x16x32_bf16 v[102:105], v[166:169], v[190:193], v[102:105]
	v_mfma_f32_16x16x32_bf16 v[98:101], v[174:177], v[190:193], v[98:101]
	v_mfma_f32_16x16x32_bf16 v[86:89], v[166:169], v[198:201], v[86:89]
	v_mfma_f32_16x16x32_bf16 v[82:85], v[174:177], v[198:201], v[82:85]
	v_mfma_f32_16x16x32_bf16 v[70:73], v[166:169], v[224:227], v[70:73]
	v_mfma_f32_16x16x32_bf16 v[66:69], v[174:177], v[224:227], v[66:69]
	v_mfma_f32_16x16x32_bf16 v[118:121], v[170:173], v[186:189], v[118:121]
	v_mfma_f32_16x16x32_bf16 v[114:117], v[178:181], v[186:189], v[114:117]
	v_mfma_f32_16x16x32_bf16 v[102:105], v[170:173], v[194:197], v[102:105]
	v_mfma_f32_16x16x32_bf16 v[98:101], v[178:181], v[194:197], v[98:101]
	v_mfma_f32_16x16x32_bf16 v[86:89], v[170:173], v[202:205], v[86:89]
	v_mfma_f32_16x16x32_bf16 v[82:85], v[178:181], v[202:205], v[82:85]
	v_mfma_f32_16x16x32_bf16 v[70:73], v[170:173], v[228:231], v[70:73]
	v_mfma_f32_16x16x32_bf16 v[66:69], v[178:181], v[228:231], v[66:69]
	s_setprio 0
	s_barrier
	s_add_i32 s52, s52, s31
	v_lshl_add_u64 v[138:139], s[24:25], 0, v[0:1]
	s_mov_b32 m0, s52
	ds_read_b128 v[182:185], v152 offset:16384
	ds_read_b128 v[186:189], v152 offset:17408
	ds_read_b128 v[190:193], v152 offset:18432
	ds_read_b128 v[194:197], v152 offset:19456
	ds_read_b128 v[198:201], v152 offset:20480
	ds_read_b128 v[202:205], v152 offset:21504
	ds_read_b128 v[224:227], v152 offset:22528
	ds_read_b128 v[228:231], v152 offset:23552
	global_load_lds_dwordx4 v[138:139], off
	s_add_i32 m0, s52, 0x2000
	s_add_u32 s52, s24, 0x40000
	v_lshl_add_u64 v[140:141], s[24:25], 0, v[134:135]
	s_addc_u32 s53, s25, 0
	s_add_i32 s55, s55, s31
	global_load_lds_dwordx4 v[140:141], off
	v_lshl_add_u64 v[232:233], s[52:53], 0, v[0:1]
	s_mov_b32 m0, s55
	v_lshl_add_u64 v[234:235], s[26:27], 0, v[132:133]
	global_load_lds_dwordx4 v[232:233], off
	v_lshl_add_u64 v[232:233], s[52:53], 0, v[134:135]
	s_add_i32 m0, s55, 0x2000
	s_nop 0
	global_load_lds_dwordx4 v[232:233], off
	v_lshl_add_u64 v[232:233], s[26:27], 0, v[130:131]
	s_mov_b32 m0, s41
	s_nop 0
	global_load_lds_dwordx4 v[232:233], off
	s_mov_b32 m0, s42
	s_nop 0
	global_load_lds_dwordx4 v[234:235], off
	s_waitcnt vmcnt(8)
	s_waitcnt lgkmcnt(0)
	s_barrier
	s_setprio 1
	s_waitcnt lgkmcnt(0)
	v_mfma_f32_16x16x32_bf16 v[62:65], v[144:147], v[182:185], v[62:65]
	v_mfma_f32_16x16x32_bf16 v[58:61], v[158:161], v[182:185], v[58:61]
	v_mfma_f32_16x16x32_bf16 v[46:49], v[144:147], v[190:193], v[46:49]
	v_mfma_f32_16x16x32_bf16 v[42:45], v[158:161], v[190:193], v[42:45]
	v_mfma_f32_16x16x32_bf16 v[30:33], v[144:147], v[198:201], v[30:33]
	v_mfma_f32_16x16x32_bf16 v[26:29], v[158:161], v[198:201], v[26:29]
	v_mfma_f32_16x16x32_bf16 v[14:17], v[144:147], v[224:227], v[14:17]
	v_mfma_f32_16x16x32_bf16 v[10:13], v[158:161], v[224:227], v[10:13]
	v_mfma_f32_16x16x32_bf16 v[62:65], v[154:157], v[186:189], v[62:65]
	v_mfma_f32_16x16x32_bf16 v[58:61], v[162:165], v[186:189], v[58:61]
	v_mfma_f32_16x16x32_bf16 v[46:49], v[154:157], v[194:197], v[46:49]
	v_mfma_f32_16x16x32_bf16 v[42:45], v[162:165], v[194:197], v[42:45]
	v_mfma_f32_16x16x32_bf16 v[30:33], v[154:157], v[202:205], v[30:33]
	v_mfma_f32_16x16x32_bf16 v[26:29], v[162:165], v[202:205], v[26:29]
	v_mfma_f32_16x16x32_bf16 v[14:17], v[154:157], v[228:231], v[14:17]
	v_mfma_f32_16x16x32_bf16 v[10:13], v[162:165], v[228:231], v[10:13]
	s_setprio 0
	s_setprio 1
	v_mfma_f32_16x16x32_bf16 v[54:57], v[166:169], v[182:185], v[54:57]
	v_mfma_f32_16x16x32_bf16 v[50:53], v[174:177], v[182:185], v[50:53]
	v_mfma_f32_16x16x32_bf16 v[38:41], v[166:169], v[190:193], v[38:41]
	v_mfma_f32_16x16x32_bf16 v[34:37], v[174:177], v[190:193], v[34:37]
	v_mfma_f32_16x16x32_bf16 v[22:25], v[166:169], v[198:201], v[22:25]
	v_mfma_f32_16x16x32_bf16 v[18:21], v[174:177], v[198:201], v[18:21]
	v_mfma_f32_16x16x32_bf16 v[6:9], v[166:169], v[224:227], v[6:9]
	v_mfma_f32_16x16x32_bf16 v[2:5], v[174:177], v[224:227], v[2:5]
	v_mfma_f32_16x16x32_bf16 v[54:57], v[170:173], v[186:189], v[54:57]
	v_mfma_f32_16x16x32_bf16 v[50:53], v[178:181], v[186:189], v[50:53]
	v_mfma_f32_16x16x32_bf16 v[38:41], v[170:173], v[194:197], v[38:41]
	v_mfma_f32_16x16x32_bf16 v[34:37], v[178:181], v[194:197], v[34:37]
	v_mfma_f32_16x16x32_bf16 v[22:25], v[170:173], v[202:205], v[22:25]
	v_mfma_f32_16x16x32_bf16 v[18:21], v[178:181], v[202:205], v[18:21]
	v_mfma_f32_16x16x32_bf16 v[6:9], v[170:173], v[228:231], v[6:9]
	v_mfma_f32_16x16x32_bf16 v[2:5], v[178:181], v[228:231], v[2:5]
	s_setprio 0
	s_barrier
; #define PG8_STAGE(bufoff, gbase, voff) do { _Pragma("unroll") for (int _i = 0; _i < 2; ++_i) \
;         __builtin_amdgcn_global_load_lds((const unsigned*)((const char*)(gbase) + (voff)[_i]), (PG8_LAS unsigned*)(lds + (bufoff) + ldsw + _i * 8192), 16, 0, 0); } while (0)
; #define PG8_LDA(dst, b, h) do { _Pragma("unroll") for (int m = 0; m < 4; ++m) _Pragma("unroll") for (int k = 0; k < 2; ++k) dst[m][k] = *(const PG8_LAS bf16x8*)(lds + PG8_SA(b, h) + aoff + m * 2048 + k * 1024); } while (0)
; #define PG8_LDB(dst, b, h) do { _Pragma("unroll") for (int n = 0; n < 2; ++n) _Pragma("unroll") for (int k = 0; k < 2; ++k) dst[n][k] = *(const PG8_LAS bf16x8*)(lds + PG8_SB(b, h) + boff + n * 2048 + k * 1024); } while (0)
; #define PG8_MMA(ai, bj, At, Bt) do { __builtin_amdgcn_s_setprio(1); _Pragma("unroll") for (int m = 0; m < 4; ++m) _Pragma("unroll") for (int n = 0; n < 2; ++n) _Pragma("unroll") for (int k = 0; k < 2; ++k) \
;         acc[ai][bj][m][n] = __builtin_amdgcn_mfma_f32_16x16x32_bf16(Bt[n][k], At[m][k], acc[ai][bj][m][n], 0, 0, 0); __builtin_amdgcn_s_setprio(0); } while (0)
; #define PG8_WAIT_V(n) asm volatile("s_waitcnt vmcnt(" #n ")" ::: "memory")
; #define PG8_WAIT_L(n) asm volatile("s_waitcnt lgkmcnt(" #n ")" ::: "memory")
; #define PG8_BAR __builtin_amdgcn_s_barrier()
; #define PG8_SCHED __builtin_amdgcn_sched_barrier(0)
; template <class Epi, class Sched, bool ALIGN_EPI = false, bool SP2 = false>
; __device__ __forceinline__ void gemm_phase(PG8_LAS unsigned char* lds, const Gemm g, const Sched& S, const Epi& E) {
;     ...
;             PG8_LDB(B0, 1, 0); PG8_LDB(B1, 1, 1); PG8_SCHED; PG8_LDA(At, 1, 0); PG8_STAGE(PG8_SA(0, 1), a2 + hstep, voffA);
;             PG8_WAIT_V(8); PG8_WAIT_L(0); PG8_BAR; PG8_MMA(0, 0, At, B0); PG8_MMA(0, 1, At, B1); PG8_BAR; PG8_SCHED;
	s_add_i32 s52, 0, 0x18000
	v_add_u32_e32 v153, s52, v149
	s_add_i32 s53, 0, 0x1c000
	ds_read_b128 v[144:147], v153
	ds_read_b128 v[154:157], v153 offset:1024
	ds_read_b128 v[158:161], v153 offset:2048
	ds_read_b128 v[162:165], v153 offset:3072
	v_add_u32_e32 v153, s53, v149
	ds_read_b128 v[166:169], v153
	ds_read_b128 v[170:173], v153 offset:1024
	ds_read_b128 v[174:177], v153 offset:2048
	ds_read_b128 v[178:181], v153 offset:3072
	s_add_u32 s26, s26, 0x40000
	s_addc_u32 s27, s27, 0
	s_mov_b32 m0, s43
	v_lshl_add_u64 v[236:237], s[26:27], 0, v[130:131]
	ds_read_b128 v[182:185], v152 offset:32768
	ds_read_b128 v[186:189], v152 offset:33792
	ds_read_b128 v[190:193], v152 offset:34816
	ds_read_b128 v[194:197], v152 offset:35840
	ds_read_b128 v[198:201], v152 offset:36864
	ds_read_b128 v[202:205], v152 offset:37888
	ds_read_b128 v[224:227], v152 offset:38912
	ds_read_b128 v[228:231], v152 offset:39936
	global_load_lds_dwordx4 v[236:237], off
	v_lshl_add_u64 v[236:237], s[26:27], 0, v[132:133]
	s_mov_b32 m0, s44
	s_nop 0
	global_load_lds_dwordx4 v[236:237], off
	s_waitcnt vmcnt(8)
	s_waitcnt lgkmcnt(0)
	s_barrier
	s_setprio 1
	s_waitcnt lgkmcnt(0)
	v_mfma_f32_16x16x32_bf16 v[126:129], v[144:147], v[182:185], v[126:129]
	v_mfma_f32_16x16x32_bf16 v[122:125], v[158:161], v[182:185], v[122:125]
	v_mfma_f32_16x16x32_bf16 v[110:113], v[144:147], v[190:193], v[110:113]
	v_mfma_f32_16x16x32_bf16 v[106:109], v[158:161], v[190:193], v[106:109]
	v_mfma_f32_16x16x32_bf16 v[94:97], v[144:147], v[198:201], v[94:97]
	v_mfma_f32_16x16x32_bf16 v[90:93], v[158:161], v[198:201], v[90:93]
	v_mfma_f32_16x16x32_bf16 v[78:81], v[144:147], v[224:227], v[78:81]
	v_mfma_f32_16x16x32_bf16 v[74:77], v[158:161], v[224:227], v[74:77]
	v_mfma_f32_16x16x32_bf16 v[126:129], v[154:157], v[186:189], v[126:129]
	v_mfma_f32_16x16x32_bf16 v[122:125], v[162:165], v[186:189], v[122:125]
	v_mfma_f32_16x16x32_bf16 v[110:113], v[154:157], v[194:197], v[110:113]
	v_mfma_f32_16x16x32_bf16 v[106:109], v[162:165], v[194:197], v[106:109]
	v_mfma_f32_16x16x32_bf16 v[94:97], v[154:157], v[202:205], v[94:97]
	v_mfma_f32_16x16x32_bf16 v[90:93], v[162:165], v[202:205], v[90:93]
	v_mfma_f32_16x16x32_bf16 v[78:81], v[154:157], v[228:231], v[78:81]
	v_mfma_f32_16x16x32_bf16 v[74:77], v[162:165], v[228:231], v[74:77]
	s_setprio 0
	s_setprio 1
	v_mfma_f32_16x16x32_bf16 v[118:121], v[166:169], v[182:185], v[118:121]
	v_mfma_f32_16x16x32_bf16 v[114:117], v[174:177], v[182:185], v[114:117]
	v_mfma_f32_16x16x32_bf16 v[102:105], v[166:169], v[190:193], v[102:105]
	v_mfma_f32_16x16x32_bf16 v[98:101], v[174:177], v[190:193], v[98:101]
	v_mfma_f32_16x16x32_bf16 v[86:89], v[166:169], v[198:201], v[86:89]
	v_mfma_f32_16x16x32_bf16 v[82:85], v[174:177], v[198:201], v[82:85]
	v_mfma_f32_16x16x32_bf16 v[70:73], v[166:169], v[224:227], v[70:73]
	v_mfma_f32_16x16x32_bf16 v[66:69], v[174:177], v[224:227], v[66:69]
	v_mfma_f32_16x16x32_bf16 v[118:121], v[170:173], v[186:189], v[118:121]
	v_mfma_f32_16x16x32_bf16 v[114:117], v[178:181], v[186:189], v[114:117]
	v_mfma_f32_16x16x32_bf16 v[102:105], v[170:173], v[194:197], v[102:105]
	v_mfma_f32_16x16x32_bf16 v[98:101], v[178:181], v[194:197], v[98:101]
	v_mfma_f32_16x16x32_bf16 v[86:89], v[170:173], v[202:205], v[86:89]
	v_mfma_f32_16x16x32_bf16 v[82:85], v[178:181], v[202:205], v[82:85]
	v_mfma_f32_16x16x32_bf16 v[70:73], v[170:173], v[228:231], v[70:73]
	v_mfma_f32_16x16x32_bf16 v[66:69], v[178:181], v[228:231], v[66:69]
	s_setprio 0
	s_barrier
; #define PG8_STAGE(bufoff, gbase, voff) do { _Pragma("unroll") for (int _i = 0; _i < 2; ++_i) \
;         __builtin_amdgcn_global_load_lds((const unsigned*)((const char*)(gbase) + (voff)[_i]), (PG8_LAS unsigned*)(lds + (bufoff) + ldsw + _i * 8192), 16, 0, 0); } while (0)
; #define PG8_LDA(dst, b, h) do { _Pragma("unroll") for (int m = 0; m < 4; ++m) _Pragma("unroll") for (int k = 0; k < 2; ++k) dst[m][k] = *(const PG8_LAS bf16x8*)(lds + PG8_SA(b, h) + aoff + m * 2048 + k * 1024); } while (0)
; #define PG8_MMA(ai, bj, At, Bt) do { __builtin_amdgcn_s_setprio(1); _Pragma("unroll") for (int m = 0; m < 4; ++m) _Pragma("unroll") for (int n = 0; n < 2; ++n) _Pragma("unroll") for (int k = 0; k < 2; ++k) \
;         acc[ai][bj][m][n] = __builtin_amdgcn_mfma_f32_16x16x32_bf16(Bt[n][k], At[m][k], acc[ai][bj][m][n], 0, 0, 0); __builtin_amdgcn_s_setprio(0); } while (0)
; #define PG8_WAIT_V(n) asm volatile("s_waitcnt vmcnt(" #n ")" ::: "memory")
; #define PG8_WAIT_L(n) asm volatile("s_waitcnt lgkmcnt(" #n ")" ::: "memory")
; #define PG8_BAR __builtin_amdgcn_s_barrier()
; #define PG8_SCHED __builtin_amdgcn_sched_barrier(0)
; template <class Epi, class Sched, bool ALIGN_EPI = false, bool SP2 = false>
; __device__ __forceinline__ void gemm_phase(PG8_LAS unsigned char* lds, const Gemm g, const Sched& S, const Epi& E) {
;     ...
;         for (int t = 0; t < nt; t += 2) {
;             const bool last = (t == nt - 2);
;             const char* a1 = cA + (size_t)(t + 1) * kstep;
;             const char* a2 = last ? nA : cA + (size_t)(t + 2) * kstep; const char* b2 = last ? nB : cB + (size_t)(t + 2) * kstep;
;             const char* a3 = a2 + kstep; const char* b3 = b2 + kstep;
;     ...
;             PG8_LDA(At, 1, 1); PG8_STAGE(PG8_SB(1, 0), b3, voffB); PG8_STAGE(PG8_SB(1, 1), b3 + hstep, voffB); PG8_STAGE(PG8_SA(1, 0), a3, voffA);
;             PG8_WAIT_V(8); PG8_WAIT_L(0); PG8_BAR; PG8_MMA(1, 0, At, B0); PG8_MMA(1, 1, At, B1); PG8_BAR; PG8_SCHED;
	s_add_i32 s26, s52, s31
	v_lshl_add_u64 v[138:139], v[138:139], 0, s[86:87]
	s_mov_b32 m0, s26
	ds_read_b128 v[182:185], v152 offset:49152
	ds_read_b128 v[186:189], v152 offset:50176
	ds_read_b128 v[190:193], v152 offset:51200
	ds_read_b128 v[194:197], v152 offset:52224
	ds_read_b128 v[198:201], v152 offset:53248
	ds_read_b128 v[202:205], v152 offset:54272
	ds_read_b128 v[224:227], v152 offset:55296
	ds_read_b128 v[228:231], v152 offset:56320
	global_load_lds_dwordx4 v[138:139], off
	s_add_i32 m0, s26, 0x2000
	s_add_u32 s24, s24, 0x40080
	v_lshl_add_u64 v[138:139], v[140:141], 0, s[86:87]
	s_addc_u32 s25, s25, 0
	s_add_i32 s26, s53, s31
	global_load_lds_dwordx4 v[138:139], off
	v_lshl_add_u64 v[138:139], s[24:25], 0, v[0:1]
	s_mov_b32 m0, s26
	s_nop 0
	global_load_lds_dwordx4 v[138:139], off
	v_lshl_add_u64 v[138:139], s[24:25], 0, v[134:135]
	s_add_i32 m0, s26, 0x2000
	s_nop 0
	global_load_lds_dwordx4 v[138:139], off
	v_lshl_add_u64 v[138:139], v[232:233], 0, s[86:87]
	s_mov_b32 m0, s45
	s_nop 0
	global_load_lds_dwordx4 v[138:139], off
	v_lshl_add_u64 v[138:139], v[234:235], 0, s[86:87]
	s_mov_b32 m0, s46
	s_nop 0
	global_load_lds_dwordx4 v[138:139], off
	s_waitcnt vmcnt(8)
	s_waitcnt lgkmcnt(0)
	s_barrier
	s_setprio 1
	s_waitcnt lgkmcnt(0)
	v_mfma_f32_16x16x32_bf16 v[62:65], v[144:147], v[182:185], v[62:65]
	v_mfma_f32_16x16x32_bf16 v[58:61], v[158:161], v[182:185], v[58:61]
	v_mfma_f32_16x16x32_bf16 v[46:49], v[144:147], v[190:193], v[46:49]
	v_mfma_f32_16x16x32_bf16 v[42:45], v[158:161], v[190:193], v[42:45]
	v_mfma_f32_16x16x32_bf16 v[30:33], v[144:147], v[198:201], v[30:33]
	v_mfma_f32_16x16x32_bf16 v[26:29], v[158:161], v[198:201], v[26:29]
	v_mfma_f32_16x16x32_bf16 v[14:17], v[144:147], v[224:227], v[14:17]
	v_mfma_f32_16x16x32_bf16 v[10:13], v[158:161], v[224:227], v[10:13]
	v_mfma_f32_16x16x32_bf16 v[62:65], v[154:157], v[186:189], v[62:65]
	v_mfma_f32_16x16x32_bf16 v[58:61], v[162:165], v[186:189], v[58:61]
	v_mfma_f32_16x16x32_bf16 v[46:49], v[154:157], v[194:197], v[46:49]
	v_mfma_f32_16x16x32_bf16 v[42:45], v[162:165], v[194:197], v[42:45]
	v_mfma_f32_16x16x32_bf16 v[30:33], v[154:157], v[202:205], v[30:33]
	v_mfma_f32_16x16x32_bf16 v[26:29], v[162:165], v[202:205], v[26:29]
	v_mfma_f32_16x16x32_bf16 v[14:17], v[154:157], v[228:231], v[14:17]
	v_mfma_f32_16x16x32_bf16 v[10:13], v[162:165], v[228:231], v[10:13]
	s_setprio 0
	s_setprio 1
	v_mfma_f32_16x16x32_bf16 v[54:57], v[166:169], v[182:185], v[54:57]
	v_mfma_f32_16x16x32_bf16 v[50:53], v[174:177], v[182:185], v[50:53]
	v_mfma_f32_16x16x32_bf16 v[38:41], v[166:169], v[190:193], v[38:41]
	v_mfma_f32_16x16x32_bf16 v[34:37], v[174:177], v[190:193], v[34:37]
	v_mfma_f32_16x16x32_bf16 v[22:25], v[166:169], v[198:201], v[22:25]
	v_mfma_f32_16x16x32_bf16 v[18:21], v[174:177], v[198:201], v[18:21]
	v_mfma_f32_16x16x32_bf16 v[6:9], v[166:169], v[224:227], v[6:9]
	v_mfma_f32_16x16x32_bf16 v[2:5], v[174:177], v[224:227], v[2:5]
	v_mfma_f32_16x16x32_bf16 v[54:57], v[170:173], v[186:189], v[54:57]
	v_mfma_f32_16x16x32_bf16 v[50:53], v[178:181], v[186:189], v[50:53]
	v_mfma_f32_16x16x32_bf16 v[38:41], v[170:173], v[194:197], v[38:41]
	v_mfma_f32_16x16x32_bf16 v[34:37], v[178:181], v[194:197], v[34:37]
	v_mfma_f32_16x16x32_bf16 v[22:25], v[170:173], v[202:205], v[22:25]
	v_mfma_f32_16x16x32_bf16 v[18:21], v[178:181], v[202:205], v[18:21]
	v_mfma_f32_16x16x32_bf16 v[6:9], v[170:173], v[228:231], v[6:9]
	v_mfma_f32_16x16x32_bf16 v[2:5], v[178:181], v[228:231], v[2:5]
	s_setprio 0
	s_add_i32 s51, s51, 2
	s_add_u32 s22, s22, 0x100
	s_addc_u32 s23, s23, 0
	s_add_u32 s49, s49, 0x100
	s_addc_u32 s50, s50, 0
	s_add_u32 s24, s22, 0xfffc0080
	s_addc_u32 s25, s23, -1
	s_add_i32 s52, 0, 0x10000
	s_cmp_eq_u32 s51, 12
	s_cselect_b32 s27, s5, s25
	s_cselect_b32 s26, s15, s24
	v_add_u32_e32 v138, s52, v149
	s_cselect_b32 s25, s13, s50
	s_cselect_b32 s24, s21, s49
	s_add_i32 s55, 0, 0x14000
	s_cmp_gt_u32 s51, 13
	s_barrier
	s_cbranch_scc0 .LBB0_225

; #define PG8_STAGE(bufoff, gbase, voff) do { _Pragma("unroll") for (int _i = 0; _i < 2; ++_i) \
;         __builtin_amdgcn_global_load_lds((const unsigned*)((const char*)(gbase) + (voff)[_i]), (PG8_LAS unsigned*)(lds + (bufoff) + ldsw + _i * 8192), 16, 0, 0); } while (0)
; #define PG8_LDA(dst, b, h) do { _Pragma("unroll") for (int m = 0; m < 4; ++m) _Pragma("unroll") for (int k = 0; k < 2; ++k) dst[m][k] = *(const PG8_LAS bf16x8*)(lds + PG8_SA(b, h) + aoff + m * 2048 + k * 1024); } while (0)
; #define PG8_LDB(dst, b, h) do { _Pragma("unroll") for (int n = 0; n < 2; ++n) _Pragma("unroll") for (int k = 0; k < 2; ++k) dst[n][k] = *(const PG8_LAS bf16x8*)(lds + PG8_SB(b, h) + boff + n * 2048 + k * 1024); } while (0)
; #define PG8_MMA(ai, bj, At, Bt) do { __builtin_amdgcn_s_setprio(1); _Pragma("unroll") for (int m = 0; m < 4; ++m) _Pragma("unroll") for (int n = 0; n < 2; ++n) _Pragma("unroll") for (int k = 0; k < 2; ++k) \
;         acc[ai][bj][m][n] = __builtin_amdgcn_mfma_f32_16x16x32_bf16(Bt[n][k], At[m][k], acc[ai][bj][m][n], 0, 0, 0); __builtin_amdgcn_s_setprio(0); } while (0)
; #define PG8_WAIT_V(n) asm volatile("s_waitcnt vmcnt(" #n ")" ::: "memory")
; #define PG8_BAR __builtin_amdgcn_s_barrier()
; template <class Epi, class Sched, bool ALIGN_EPI = false, bool SP2 = false>
; __device__ __forceinline__ void gemm_phase(PG8_LAS unsigned char* lds, const Gemm g, const Sched& S, const Epi& E) {
;     ...
;         for (int t = 0; t < nt; t += 2) {
;             const bool last = (t == nt - 2);
;             const char* a1 = cA + (size_t)(t + 1) * kstep;
;             const char* a2 = last ? nA : cA + (size_t)(t + 2) * kstep; const char* b2 = last ? nB : cB + (size_t)(t + 2) * kstep;
;             const char* a3 = a2 + kstep; const char* b3 = b2 + kstep;
;             if (last && has_next) S.a_ready(nxt);
;             if constexpr (SP2) {
;             PG8_LDB(B0, 0, 0); PG8_LDB(B1, 0, 1); PG8_SCHED; PG8_LDA(At, 0, 0); PG8_STAGE(PG8_SA(1, 1), a1 + hstep, voffA);
;             PG8_WAIT_V(8); PG8_WAIT_L(0); PG8_BAR; PG8_MMA(0, 0, At, B0); PG8_MMA(0, 1, At, B1); PG8_BAR; PG8_SCHED;
;     ...
;         for (int a = 0; a < 2; ++a)
; #pragma unroll
;             for (int b = 0; b < 2; ++b)
; #pragma unroll
;                 for (int m = 0; m < 4; ++m)
; #pragma unroll
;                     for (int n = 0; n < 2; ++n) acc[a][b][m][n] = (f32x4){0.f, 0.f, 0.f, 0.f};
.LBB0_361:
	s_add_u32 s47, s16, 0x100
	v_mov_b32_e32 v2, 0
	s_addc_u32 s48, s17, 0
	s_mov_b32 s49, -2
	s_waitcnt lgkmcnt(0)
	v_mov_b32_e32 v3, v2
	v_mov_b32_e32 v4, v2
	v_mov_b32_e32 v5, v2
	v_mov_b32_e32 v6, v2
	v_mov_b32_e32 v7, v2
	v_mov_b32_e32 v8, v2
	v_mov_b32_e32 v9, v2
	v_mov_b32_e32 v18, v2
	v_mov_b32_e32 v19, v2
	v_mov_b32_e32 v20, v2
	v_mov_b32_e32 v21, v2
	v_mov_b32_e32 v22, v2
	v_mov_b32_e32 v23, v2
	v_mov_b32_e32 v24, v2
	v_mov_b32_e32 v25, v2
	v_mov_b32_e32 v34, v2
	v_mov_b32_e32 v35, v2
	v_mov_b32_e32 v36, v2
	v_mov_b32_e32 v37, v2
	v_mov_b32_e32 v38, v2
	v_mov_b32_e32 v39, v2
	v_mov_b32_e32 v40, v2
	v_mov_b32_e32 v41, v2
	v_mov_b32_e32 v50, v2
	v_mov_b32_e32 v51, v2
	v_mov_b32_e32 v52, v2
	v_mov_b32_e32 v53, v2
	v_mov_b32_e32 v54, v2
	v_mov_b32_e32 v55, v2
	v_mov_b32_e32 v56, v2
	v_mov_b32_e32 v57, v2
	v_mov_b32_e32 v10, v2
	v_mov_b32_e32 v11, v2
	v_mov_b32_e32 v12, v2
	v_mov_b32_e32 v13, v2
	v_mov_b32_e32 v14, v2
	v_mov_b32_e32 v15, v2
	v_mov_b32_e32 v16, v2
	v_mov_b32_e32 v17, v2
	v_mov_b32_e32 v26, v2
	v_mov_b32_e32 v27, v2
	v_mov_b32_e32 v28, v2
	v_mov_b32_e32 v29, v2
	v_mov_b32_e32 v30, v2
	v_mov_b32_e32 v31, v2
	v_mov_b32_e32 v32, v2
	v_mov_b32_e32 v33, v2
	v_mov_b32_e32 v42, v2
	v_mov_b32_e32 v43, v2
	v_mov_b32_e32 v44, v2
	v_mov_b32_e32 v45, v2
	v_mov_b32_e32 v46, v2
	v_mov_b32_e32 v47, v2
	v_mov_b32_e32 v48, v2
	v_mov_b32_e32 v49, v2
	v_mov_b32_e32 v58, v2
	v_mov_b32_e32 v59, v2
	v_mov_b32_e32 v60, v2
	v_mov_b32_e32 v61, v2
	v_mov_b32_e32 v62, v2
	v_mov_b32_e32 v63, v2
	v_mov_b32_e32 v64, v2
	v_mov_b32_e32 v65, v2
	v_mov_b32_e32 v66, v2
	v_mov_b32_e32 v67, v2
	v_mov_b32_e32 v68, v2
	v_mov_b32_e32 v69, v2
	v_mov_b32_e32 v70, v2
	v_mov_b32_e32 v71, v2
	v_mov_b32_e32 v72, v2
	v_mov_b32_e32 v73, v2
	v_mov_b32_e32 v82, v2
	v_mov_b32_e32 v83, v2
	v_mov_b32_e32 v84, v2
	v_mov_b32_e32 v85, v2
	v_mov_b32_e32 v86, v2
	v_mov_b32_e32 v87, v2
	v_mov_b32_e32 v88, v2
	v_mov_b32_e32 v89, v2
	v_mov_b32_e32 v98, v2
	v_mov_b32_e32 v99, v2
	v_mov_b32_e32 v100, v2
	v_mov_b32_e32 v101, v2
	v_mov_b32_e32 v102, v2
	v_mov_b32_e32 v103, v2
	v_mov_b32_e32 v104, v2
	v_mov_b32_e32 v105, v2
	v_mov_b32_e32 v114, v2
	v_mov_b32_e32 v115, v2
	v_mov_b32_e32 v116, v2
	v_mov_b32_e32 v117, v2
	v_mov_b32_e32 v118, v2
	v_mov_b32_e32 v119, v2
	v_mov_b32_e32 v120, v2
	v_mov_b32_e32 v121, v2
	v_mov_b32_e32 v74, v2
	v_mov_b32_e32 v75, v2
	v_mov_b32_e32 v76, v2
	v_mov_b32_e32 v77, v2
	v_mov_b32_e32 v78, v2
	v_mov_b32_e32 v79, v2
	v_mov_b32_e32 v80, v2
	v_mov_b32_e32 v81, v2
	v_mov_b32_e32 v90, v2
	v_mov_b32_e32 v91, v2
	v_mov_b32_e32 v92, v2
	v_mov_b32_e32 v93, v2
	v_mov_b32_e32 v94, v2
	v_mov_b32_e32 v95, v2
	v_mov_b32_e32 v96, v2
	v_mov_b32_e32 v97, v2
	v_mov_b32_e32 v106, v2
	v_mov_b32_e32 v107, v2
	v_mov_b32_e32 v108, v2
	v_mov_b32_e32 v109, v2
	v_mov_b32_e32 v110, v2
	v_mov_b32_e32 v111, v2
	v_mov_b32_e32 v112, v2
	v_mov_b32_e32 v113, v2
	v_mov_b32_e32 v122, v2
	v_mov_b32_e32 v123, v2
	v_mov_b32_e32 v124, v2
	v_mov_b32_e32 v125, v2
	v_mov_b32_e32 v126, v2
	v_mov_b32_e32 v127, v2
	v_mov_b32_e32 v128, v2
	v_mov_b32_e32 v129, v2
	s_add_u32 s16, s14, 0x100
	s_addc_u32 s17, s15, 0
	s_add_i32 s50, 0, 0x10000
	s_cmp_eq_u32 s49, 40
	s_cselect_b32 s21, s7, s17
	s_cselect_b32 s20, s6, s16
	v_add_u32_e32 v138, s50, v149
	s_cselect_b32 s19, s13, s48
	s_cselect_b32 s18, s12, s47
	s_add_i32 s51, 0, 0x14000
.LBB0_362:
	ds_read_b128 v[144:147], v138
	ds_read_b128 v[152:155], v138 offset:1024
	ds_read_b128 v[156:159], v138 offset:2048
	ds_read_b128 v[160:163], v138 offset:3072
	v_add_u32_e32 v138, s51, v149
	ds_read_b128 v[164:167], v138
	ds_read_b128 v[168:171], v138 offset:1024
	ds_read_b128 v[172:175], v138 offset:2048
	ds_read_b128 v[176:179], v138 offset:3072
	v_lshl_add_u64 v[138:139], s[14:15], 0, v[136:137]
	s_add_i32 m0, s26, 0xc000
	ds_read_b128 v[180:183], v151
	ds_read_b128 v[184:187], v151 offset:1024
	ds_read_b128 v[188:191], v151 offset:2048
	ds_read_b128 v[192:195], v151 offset:3072
	ds_read_b128 v[196:199], v151 offset:4096
	ds_read_b128 v[200:203], v151 offset:5120
	ds_read_b128 v[224:227], v151 offset:6144
	ds_read_b128 v[228:231], v151 offset:7168
	global_load_lds_dwordx4 v[138:139], off
	v_lshl_add_u64 v[138:139], s[14:15], 0, v[142:143]
	s_add_i32 m0, s26, 0xe000
	s_nop 0
	global_load_lds_dwordx4 v[138:139], off
	s_waitcnt vmcnt(8)
	s_waitcnt lgkmcnt(0)
	s_barrier
	s_setprio 1
	s_waitcnt lgkmcnt(0)
	v_mfma_f32_16x16x32_bf16 v[126:129], v[144:147], v[180:183], v[126:129]
	v_mfma_f32_16x16x32_bf16 v[122:125], v[156:159], v[180:183], v[122:125]
	v_mfma_f32_16x16x32_bf16 v[110:113], v[144:147], v[188:191], v[110:113]
	v_mfma_f32_16x16x32_bf16 v[106:109], v[156:159], v[188:191], v[106:109]
	v_mfma_f32_16x16x32_bf16 v[94:97], v[144:147], v[196:199], v[94:97]
	v_mfma_f32_16x16x32_bf16 v[90:93], v[156:159], v[196:199], v[90:93]
	v_mfma_f32_16x16x32_bf16 v[78:81], v[144:147], v[224:227], v[78:81]
	v_mfma_f32_16x16x32_bf16 v[74:77], v[156:159], v[224:227], v[74:77]
	v_mfma_f32_16x16x32_bf16 v[126:129], v[152:155], v[184:187], v[126:129]
	v_mfma_f32_16x16x32_bf16 v[122:125], v[160:163], v[184:187], v[122:125]
	v_mfma_f32_16x16x32_bf16 v[110:113], v[152:155], v[192:195], v[110:113]
	v_mfma_f32_16x16x32_bf16 v[106:109], v[160:163], v[192:195], v[106:109]
	v_mfma_f32_16x16x32_bf16 v[94:97], v[152:155], v[200:203], v[94:97]
	v_mfma_f32_16x16x32_bf16 v[90:93], v[160:163], v[200:203], v[90:93]
	v_mfma_f32_16x16x32_bf16 v[78:81], v[152:155], v[228:231], v[78:81]
	v_mfma_f32_16x16x32_bf16 v[74:77], v[160:163], v[228:231], v[74:77]
	s_setprio 0
	s_setprio 1
	v_mfma_f32_16x16x32_bf16 v[118:121], v[164:167], v[180:183], v[118:121]
	v_mfma_f32_16x16x32_bf16 v[114:117], v[172:175], v[180:183], v[114:117]
	v_mfma_f32_16x16x32_bf16 v[102:105], v[164:167], v[188:191], v[102:105]
	v_mfma_f32_16x16x32_bf16 v[98:101], v[172:175], v[188:191], v[98:101]
	v_mfma_f32_16x16x32_bf16 v[86:89], v[164:167], v[196:199], v[86:89]
	v_mfma_f32_16x16x32_bf16 v[82:85], v[172:175], v[196:199], v[82:85]
	v_mfma_f32_16x16x32_bf16 v[70:73], v[164:167], v[224:227], v[70:73]
	v_mfma_f32_16x16x32_bf16 v[66:69], v[172:175], v[224:227], v[66:69]
	v_mfma_f32_16x16x32_bf16 v[118:121], v[168:171], v[184:187], v[118:121]
	v_mfma_f32_16x16x32_bf16 v[114:117], v[176:179], v[184:187], v[114:117]
	v_mfma_f32_16x16x32_bf16 v[102:105], v[168:171], v[192:195], v[102:105]
	v_mfma_f32_16x16x32_bf16 v[98:101], v[176:179], v[192:195], v[98:101]
	v_mfma_f32_16x16x32_bf16 v[86:89], v[168:171], v[200:203], v[86:89]
	v_mfma_f32_16x16x32_bf16 v[82:85], v[176:179], v[200:203], v[82:85]
	v_mfma_f32_16x16x32_bf16 v[70:73], v[168:171], v[228:231], v[70:73]
	v_mfma_f32_16x16x32_bf16 v[66:69], v[176:179], v[228:231], v[66:69]
	s_setprio 0
	s_barrier
; #define PG8_STAGE(bufoff, gbase, voff) do { _Pragma("unroll") for (int _i = 0; _i < 2; ++_i) \
;         __builtin_amdgcn_global_load_lds((const unsigned*)((const char*)(gbase) + (voff)[_i]), (PG8_LAS unsigned*)(lds + (bufoff) + ldsw + _i * 8192), 16, 0, 0); } while (0)
; #define PG8_LDA(dst, b, h) do { _Pragma("unroll") for (int m = 0; m < 4; ++m) _Pragma("unroll") for (int k = 0; k < 2; ++k) dst[m][k] = *(const PG8_LAS bf16x8*)(lds + PG8_SA(b, h) + aoff + m * 2048 + k * 1024); } while (0)
; #define PG8_LDB(dst, b, h) do { _Pragma("unroll") for (int n = 0; n < 2; ++n) _Pragma("unroll") for (int k = 0; k < 2; ++k) dst[n][k] = *(const PG8_LAS bf16x8*)(lds + PG8_SB(b, h) + boff + n * 2048 + k * 1024); } while (0)
; #define PG8_MMA(ai, bj, At, Bt) do { __builtin_amdgcn_s_setprio(1); _Pragma("unroll") for (int m = 0; m < 4; ++m) _Pragma("unroll") for (int n = 0; n < 2; ++n) _Pragma("unroll") for (int k = 0; k < 2; ++k) \
;         acc[ai][bj][m][n] = __builtin_amdgcn_mfma_f32_16x16x32_bf16(Bt[n][k], At[m][k], acc[ai][bj][m][n], 0, 0, 0); __builtin_amdgcn_s_setprio(0); } while (0)
; #define PG8_WAIT_V(n) asm volatile("s_waitcnt vmcnt(" #n ")" ::: "memory")
; #define PG8_WAIT_L(n) asm volatile("s_waitcnt lgkmcnt(" #n ")" ::: "memory")
; #define PG8_BAR __builtin_amdgcn_s_barrier()
; #define PG8_SCHED __builtin_amdgcn_sched_barrier(0)
; template <class Epi, class Sched, bool ALIGN_EPI = false, bool SP2 = false>
; __device__ __forceinline__ void gemm_phase(PG8_LAS unsigned char* lds, const Gemm g, const Sched& S, const Epi& E) {
;     ...
;             PG8_LDA(At, 0, 1); PG8_STAGE(PG8_SB(0, 0), b2, voffB); PG8_STAGE(PG8_SB(0, 1), b2 + hstep, voffB); PG8_STAGE(PG8_SA(0, 0), a2, voffA);
;             PG8_WAIT_V(8); PG8_WAIT_L(0); PG8_BAR; PG8_MMA(1, 0, At, B0); PG8_MMA(1, 1, At, B1); PG8_BAR; PG8_SCHED;
;             PG8_LDB(B0, 1, 0); PG8_LDB(B1, 1, 1); PG8_SCHED; PG8_LDA(At, 1, 0); PG8_STAGE(PG8_SA(0, 1), a2 + hstep, voffA);
	s_add_i32 s14, s50, s23
	v_lshl_add_u64 v[138:139], s[18:19], 0, v[0:1]
	s_mov_b32 m0, s14
	ds_read_b128 v[180:183], v151 offset:16384
	ds_read_b128 v[184:187], v151 offset:17408
	ds_read_b128 v[188:191], v151 offset:18432
	ds_read_b128 v[192:195], v151 offset:19456
	ds_read_b128 v[196:199], v151 offset:20480
	ds_read_b128 v[200:203], v151 offset:21504
	ds_read_b128 v[224:227], v151 offset:22528
	ds_read_b128 v[228:231], v151 offset:23552
	global_load_lds_dwordx4 v[138:139], off
	s_add_i32 m0, s14, 0x2000
	s_add_u32 s14, s18, 0xb0000
	v_lshl_add_u64 v[140:141], s[18:19], 0, v[134:135]
	s_addc_u32 s15, s19, 0
	s_add_i32 s50, s51, s23
	global_load_lds_dwordx4 v[140:141], off
	v_lshl_add_u64 v[204:205], s[14:15], 0, v[0:1]
	s_mov_b32 m0, s50
	v_lshl_add_u64 v[232:233], s[20:21], 0, v[132:133]
	global_load_lds_dwordx4 v[204:205], off
	v_lshl_add_u64 v[204:205], s[14:15], 0, v[134:135]
	s_add_i32 m0, s50, 0x2000
	s_nop 0
	global_load_lds_dwordx4 v[204:205], off
	v_lshl_add_u64 v[204:205], s[20:21], 0, v[130:131]
	s_mov_b32 m0, s26
	s_nop 0
	global_load_lds_dwordx4 v[204:205], off
	s_mov_b32 m0, s27
	s_nop 0
	global_load_lds_dwordx4 v[232:233], off
	s_waitcnt vmcnt(8)
	s_waitcnt lgkmcnt(0)
	s_barrier
	s_setprio 1
	s_waitcnt lgkmcnt(0)
	v_mfma_f32_16x16x32_bf16 v[62:65], v[144:147], v[180:183], v[62:65]
	v_mfma_f32_16x16x32_bf16 v[58:61], v[156:159], v[180:183], v[58:61]
	v_mfma_f32_16x16x32_bf16 v[46:49], v[144:147], v[188:191], v[46:49]
	v_mfma_f32_16x16x32_bf16 v[42:45], v[156:159], v[188:191], v[42:45]
	v_mfma_f32_16x16x32_bf16 v[30:33], v[144:147], v[196:199], v[30:33]
	v_mfma_f32_16x16x32_bf16 v[26:29], v[156:159], v[196:199], v[26:29]
	v_mfma_f32_16x16x32_bf16 v[14:17], v[144:147], v[224:227], v[14:17]
	v_mfma_f32_16x16x32_bf16 v[10:13], v[156:159], v[224:227], v[10:13]
	v_mfma_f32_16x16x32_bf16 v[62:65], v[152:155], v[184:187], v[62:65]
	v_mfma_f32_16x16x32_bf16 v[58:61], v[160:163], v[184:187], v[58:61]
	v_mfma_f32_16x16x32_bf16 v[46:49], v[152:155], v[192:195], v[46:49]
	v_mfma_f32_16x16x32_bf16 v[42:45], v[160:163], v[192:195], v[42:45]
	v_mfma_f32_16x16x32_bf16 v[30:33], v[152:155], v[200:203], v[30:33]
	v_mfma_f32_16x16x32_bf16 v[26:29], v[160:163], v[200:203], v[26:29]
	v_mfma_f32_16x16x32_bf16 v[14:17], v[152:155], v[228:231], v[14:17]
	v_mfma_f32_16x16x32_bf16 v[10:13], v[160:163], v[228:231], v[10:13]
	s_setprio 0
	s_setprio 1
	v_mfma_f32_16x16x32_bf16 v[54:57], v[164:167], v[180:183], v[54:57]
	v_mfma_f32_16x16x32_bf16 v[50:53], v[172:175], v[180:183], v[50:53]
	v_mfma_f32_16x16x32_bf16 v[38:41], v[164:167], v[188:191], v[38:41]
	v_mfma_f32_16x16x32_bf16 v[34:37], v[172:175], v[188:191], v[34:37]
	v_mfma_f32_16x16x32_bf16 v[22:25], v[164:167], v[196:199], v[22:25]
	v_mfma_f32_16x16x32_bf16 v[18:21], v[172:175], v[196:199], v[18:21]
	v_mfma_f32_16x16x32_bf16 v[6:9], v[164:167], v[224:227], v[6:9]
	v_mfma_f32_16x16x32_bf16 v[2:5], v[172:175], v[224:227], v[2:5]
	v_mfma_f32_16x16x32_bf16 v[54:57], v[168:171], v[184:187], v[54:57]
	v_mfma_f32_16x16x32_bf16 v[50:53], v[176:179], v[184:187], v[50:53]
	v_mfma_f32_16x16x32_bf16 v[38:41], v[168:171], v[192:195], v[38:41]
	v_mfma_f32_16x16x32_bf16 v[34:37], v[176:179], v[192:195], v[34:37]
	v_mfma_f32_16x16x32_bf16 v[22:25], v[168:171], v[200:203], v[22:25]
	v_mfma_f32_16x16x32_bf16 v[18:21], v[176:179], v[200:203], v[18:21]
	v_mfma_f32_16x16x32_bf16 v[6:9], v[168:171], v[228:231], v[6:9]
	v_mfma_f32_16x16x32_bf16 v[2:5], v[176:179], v[228:231], v[2:5]
	s_setprio 0
	s_barrier
	s_add_i32 s50, 0, 0x18000
	s_add_i32 s51, 0, 0x1c000
	v_add_u32_e32 v160, s50, v149
	v_add_u32_e32 v176, s51, v149
	ds_read_b128 v[144:147], v160
	ds_read_b128 v[152:155], v160 offset:1024
	ds_read_b128 v[156:159], v160 offset:2048
	ds_read_b128 v[160:163], v160 offset:3072
	ds_read_b128 v[164:167], v176
	ds_read_b128 v[168:171], v176 offset:1024
	ds_read_b128 v[172:175], v176 offset:2048
	ds_read_b128 v[176:179], v176 offset:3072
	s_add_u32 s14, s20, 0xb0000
	s_addc_u32 s15, s21, 0
	s_mov_b32 m0, s29
	v_lshl_add_u64 v[234:235], s[14:15], 0, v[130:131]
	ds_read_b128 v[180:183], v151 offset:32768
	ds_read_b128 v[184:187], v151 offset:33792
	ds_read_b128 v[188:191], v151 offset:34816
	ds_read_b128 v[192:195], v151 offset:35840
	ds_read_b128 v[196:199], v151 offset:36864
	ds_read_b128 v[200:203], v151 offset:37888
	ds_read_b128 v[224:227], v151 offset:38912
	ds_read_b128 v[228:231], v151 offset:39936
	global_load_lds_dwordx4 v[234:235], off
	v_lshl_add_u64 v[234:235], s[14:15], 0, v[132:133]
	s_mov_b32 m0, s30
	s_nop 0
	global_load_lds_dwordx4 v[234:235], off
	s_waitcnt vmcnt(8)
	s_waitcnt lgkmcnt(0)
	s_barrier
; #define PG8_STAGE(bufoff, gbase, voff) do { _Pragma("unroll") for (int _i = 0; _i < 2; ++_i) \
;         __builtin_amdgcn_global_load_lds((const unsigned*)((const char*)(gbase) + (voff)[_i]), (PG8_LAS unsigned*)(lds + (bufoff) + ldsw + _i * 8192), 16, 0, 0); } while (0)
; #define PG8_LDA(dst, b, h) do { _Pragma("unroll") for (int m = 0; m < 4; ++m) _Pragma("unroll") for (int k = 0; k < 2; ++k) dst[m][k] = *(const PG8_LAS bf16x8*)(lds + PG8_SA(b, h) + aoff + m * 2048 + k * 1024); } while (0)
; #define PG8_MMA(ai, bj, At, Bt) do { __builtin_amdgcn_s_setprio(1); _Pragma("unroll") for (int m = 0; m < 4; ++m) _Pragma("unroll") for (int n = 0; n < 2; ++n) _Pragma("unroll") for (int k = 0; k < 2; ++k) \
;         acc[ai][bj][m][n] = __builtin_amdgcn_mfma_f32_16x16x32_bf16(Bt[n][k], At[m][k], acc[ai][bj][m][n], 0, 0, 0); __builtin_amdgcn_s_setprio(0); } while (0)
; #define PG8_WAIT_V(n) asm volatile("s_waitcnt vmcnt(" #n ")" ::: "memory")
; #define PG8_WAIT_L(n) asm volatile("s_waitcnt lgkmcnt(" #n ")" ::: "memory")
; #define PG8_BAR __builtin_amdgcn_s_barrier()
; #define PG8_SCHED __builtin_amdgcn_sched_barrier(0)
; template <class Epi, class Sched, bool ALIGN_EPI = false, bool SP2 = false>
; __device__ __forceinline__ void gemm_phase(PG8_LAS unsigned char* lds, const Gemm g, const Sched& S, const Epi& E) {
;     ...
;             PG8_WAIT_V(8); PG8_WAIT_L(0); PG8_BAR; PG8_MMA(0, 0, At, B0); PG8_MMA(0, 1, At, B1); PG8_BAR; PG8_SCHED;
;             PG8_LDA(At, 1, 1); PG8_STAGE(PG8_SB(1, 0), b3, voffB); PG8_STAGE(PG8_SB(1, 1), b3 + hstep, voffB); PG8_STAGE(PG8_SA(1, 0), a3, voffA);
	s_setprio 1
	s_waitcnt lgkmcnt(0)
	v_mfma_f32_16x16x32_bf16 v[126:129], v[144:147], v[180:183], v[126:129]
	v_mfma_f32_16x16x32_bf16 v[122:125], v[156:159], v[180:183], v[122:125]
	v_mfma_f32_16x16x32_bf16 v[110:113], v[144:147], v[188:191], v[110:113]
	v_mfma_f32_16x16x32_bf16 v[106:109], v[156:159], v[188:191], v[106:109]
	v_mfma_f32_16x16x32_bf16 v[94:97], v[144:147], v[196:199], v[94:97]
	v_mfma_f32_16x16x32_bf16 v[90:93], v[156:159], v[196:199], v[90:93]
	v_mfma_f32_16x16x32_bf16 v[78:81], v[144:147], v[224:227], v[78:81]
	v_mfma_f32_16x16x32_bf16 v[74:77], v[156:159], v[224:227], v[74:77]
	v_mfma_f32_16x16x32_bf16 v[126:129], v[152:155], v[184:187], v[126:129]
	v_mfma_f32_16x16x32_bf16 v[122:125], v[160:163], v[184:187], v[122:125]
	v_mfma_f32_16x16x32_bf16 v[110:113], v[152:155], v[192:195], v[110:113]
	v_mfma_f32_16x16x32_bf16 v[106:109], v[160:163], v[192:195], v[106:109]
	v_mfma_f32_16x16x32_bf16 v[94:97], v[152:155], v[200:203], v[94:97]
	v_mfma_f32_16x16x32_bf16 v[90:93], v[160:163], v[200:203], v[90:93]
	v_mfma_f32_16x16x32_bf16 v[78:81], v[152:155], v[228:231], v[78:81]
	v_mfma_f32_16x16x32_bf16 v[74:77], v[160:163], v[228:231], v[74:77]
	s_setprio 0
	s_setprio 1
	v_mfma_f32_16x16x32_bf16 v[118:121], v[164:167], v[180:183], v[118:121]
	v_mfma_f32_16x16x32_bf16 v[114:117], v[172:175], v[180:183], v[114:117]
	v_mfma_f32_16x16x32_bf16 v[102:105], v[164:167], v[188:191], v[102:105]
	v_mfma_f32_16x16x32_bf16 v[98:101], v[172:175], v[188:191], v[98:101]
	v_mfma_f32_16x16x32_bf16 v[86:89], v[164:167], v[196:199], v[86:89]
	v_mfma_f32_16x16x32_bf16 v[82:85], v[172:175], v[196:199], v[82:85]
	v_mfma_f32_16x16x32_bf16 v[70:73], v[164:167], v[224:227], v[70:73]
	v_mfma_f32_16x16x32_bf16 v[66:69], v[172:175], v[224:227], v[66:69]
	v_mfma_f32_16x16x32_bf16 v[118:121], v[168:171], v[184:187], v[118:121]
	v_mfma_f32_16x16x32_bf16 v[114:117], v[176:179], v[184:187], v[114:117]
	v_mfma_f32_16x16x32_bf16 v[102:105], v[168:171], v[192:195], v[102:105]
	v_mfma_f32_16x16x32_bf16 v[98:101], v[176:179], v[192:195], v[98:101]
	v_mfma_f32_16x16x32_bf16 v[86:89], v[168:171], v[200:203], v[86:89]
	v_mfma_f32_16x16x32_bf16 v[82:85], v[176:179], v[200:203], v[82:85]
	v_mfma_f32_16x16x32_bf16 v[70:73], v[168:171], v[228:231], v[70:73]
	v_mfma_f32_16x16x32_bf16 v[66:69], v[176:179], v[228:231], v[66:69]
	s_setprio 0
	s_barrier
	s_add_i32 s14, s50, s23
	v_lshl_add_u64 v[138:139], v[138:139], 0, s[86:87]
	s_mov_b32 m0, s14
	ds_read_b128 v[180:183], v151 offset:49152
	ds_read_b128 v[184:187], v151 offset:50176
	ds_read_b128 v[188:191], v151 offset:51200
	ds_read_b128 v[192:195], v151 offset:52224
	ds_read_b128 v[196:199], v151 offset:53248
	ds_read_b128 v[200:203], v151 offset:54272
	ds_read_b128 v[224:227], v151 offset:55296
	ds_read_b128 v[228:231], v151 offset:56320
	global_load_lds_dwordx4 v[138:139], off
	s_add_i32 m0, s14, 0x2000
	s_add_u32 s14, s18, 0xb0080
	v_lshl_add_u64 v[138:139], v[140:141], 0, s[86:87]
	s_addc_u32 s15, s19, 0
	s_add_i32 s18, s51, s23
	global_load_lds_dwordx4 v[138:139], off
	v_lshl_add_u64 v[138:139], s[14:15], 0, v[0:1]
	s_mov_b32 m0, s18
	s_nop 0
	global_load_lds_dwordx4 v[138:139], off
	v_lshl_add_u64 v[138:139], s[14:15], 0, v[134:135]
	s_add_i32 m0, s18, 0x2000
	s_nop 0
	global_load_lds_dwordx4 v[138:139], off
	v_lshl_add_u64 v[138:139], v[204:205], 0, s[86:87]
	s_mov_b32 m0, s38
	s_nop 0
	global_load_lds_dwordx4 v[138:139], off
	v_lshl_add_u64 v[138:139], v[232:233], 0, s[86:87]
	s_mov_b32 m0, s39
	s_nop 0
	global_load_lds_dwordx4 v[138:139], off
	s_waitcnt vmcnt(8)
	s_waitcnt lgkmcnt(0)
	s_barrier
; #define PG8_MMA(ai, bj, At, Bt) do { __builtin_amdgcn_s_setprio(1); _Pragma("unroll") for (int m = 0; m < 4; ++m) _Pragma("unroll") for (int n = 0; n < 2; ++n) _Pragma("unroll") for (int k = 0; k < 2; ++k) \
;         acc[ai][bj][m][n] = __builtin_amdgcn_mfma_f32_16x16x32_bf16(Bt[n][k], At[m][k], acc[ai][bj][m][n], 0, 0, 0); __builtin_amdgcn_s_setprio(0); } while (0)
; #define PG8_WAIT_V(n) asm volatile("s_waitcnt vmcnt(" #n ")" ::: "memory")
; #define PG8_WAIT_L(n) asm volatile("s_waitcnt lgkmcnt(" #n ")" ::: "memory")
; #define PG8_BAR __builtin_amdgcn_s_barrier()
; #define PG8_SCHED __builtin_amdgcn_sched_barrier(0)
; template <class Epi, class Sched, bool ALIGN_EPI = false, bool SP2 = false>
; __device__ __forceinline__ void gemm_phase(PG8_LAS unsigned char* lds, const Gemm g, const Sched& S, const Epi& E) {
;     ...
;         for (int t = 0; t < nt; t += 2) {
;             const bool last = (t == nt - 2);
;             const char* a1 = cA + (size_t)(t + 1) * kstep;
;             const char* a2 = last ? nA : cA + (size_t)(t + 2) * kstep; const char* b2 = last ? nB : cB + (size_t)(t + 2) * kstep;
;             const char* a3 = a2 + kstep; const char* b3 = b2 + kstep;
;     ...
;             PG8_WAIT_V(8); PG8_WAIT_L(0); PG8_BAR; PG8_MMA(1, 0, At, B0); PG8_MMA(1, 1, At, B1); PG8_BAR; PG8_SCHED;
;     __device__ __forceinline__ void operator()(const f32x4 (&acc)[2][2][4][2], const Unit& u, int wr, int wc, int fr, int fq) const {
;     ...
;                 const int row = row0 + ai * 128 + m * 16; float p = 0.f;
; #pragma unroll
;                 for (int bj = 0; bj < 2; ++bj) {
;                     const size_t off = (size_t)row * D + col0 + bj * 128;
;                     const u32x4 xx = *(const u32x4*)(xb + off);
	s_setprio 1
	s_waitcnt lgkmcnt(0)
	v_mfma_f32_16x16x32_bf16 v[62:65], v[144:147], v[180:183], v[62:65]
	v_mfma_f32_16x16x32_bf16 v[58:61], v[156:159], v[180:183], v[58:61]
	v_mfma_f32_16x16x32_bf16 v[46:49], v[144:147], v[188:191], v[46:49]
	v_mfma_f32_16x16x32_bf16 v[42:45], v[156:159], v[188:191], v[42:45]
	v_mfma_f32_16x16x32_bf16 v[30:33], v[144:147], v[196:199], v[30:33]
	v_mfma_f32_16x16x32_bf16 v[26:29], v[156:159], v[196:199], v[26:29]
	v_mfma_f32_16x16x32_bf16 v[14:17], v[144:147], v[224:227], v[14:17]
	v_mfma_f32_16x16x32_bf16 v[10:13], v[156:159], v[224:227], v[10:13]
	v_mfma_f32_16x16x32_bf16 v[62:65], v[152:155], v[184:187], v[62:65]
	v_mfma_f32_16x16x32_bf16 v[58:61], v[160:163], v[184:187], v[58:61]
	v_mfma_f32_16x16x32_bf16 v[46:49], v[152:155], v[192:195], v[46:49]
	v_mfma_f32_16x16x32_bf16 v[42:45], v[160:163], v[192:195], v[42:45]
	v_mfma_f32_16x16x32_bf16 v[30:33], v[152:155], v[200:203], v[30:33]
	v_mfma_f32_16x16x32_bf16 v[26:29], v[160:163], v[200:203], v[26:29]
	v_mfma_f32_16x16x32_bf16 v[14:17], v[152:155], v[228:231], v[14:17]
	v_mfma_f32_16x16x32_bf16 v[10:13], v[160:163], v[228:231], v[10:13]
	s_setprio 0
	s_setprio 1
	v_mfma_f32_16x16x32_bf16 v[54:57], v[164:167], v[180:183], v[54:57]
	v_mfma_f32_16x16x32_bf16 v[50:53], v[172:175], v[180:183], v[50:53]
	v_mfma_f32_16x16x32_bf16 v[38:41], v[164:167], v[188:191], v[38:41]
	v_mfma_f32_16x16x32_bf16 v[34:37], v[172:175], v[188:191], v[34:37]
	v_mfma_f32_16x16x32_bf16 v[22:25], v[164:167], v[196:199], v[22:25]
	v_mfma_f32_16x16x32_bf16 v[18:21], v[172:175], v[196:199], v[18:21]
	v_mfma_f32_16x16x32_bf16 v[6:9], v[164:167], v[224:227], v[6:9]
	v_mfma_f32_16x16x32_bf16 v[2:5], v[172:175], v[224:227], v[2:5]
	v_mfma_f32_16x16x32_bf16 v[54:57], v[168:171], v[184:187], v[54:57]
	v_mfma_f32_16x16x32_bf16 v[50:53], v[176:179], v[184:187], v[50:53]
	v_mfma_f32_16x16x32_bf16 v[38:41], v[168:171], v[192:195], v[38:41]
	v_mfma_f32_16x16x32_bf16 v[34:37], v[176:179], v[192:195], v[34:37]
	v_mfma_f32_16x16x32_bf16 v[22:25], v[168:171], v[200:203], v[22:25]
	v_mfma_f32_16x16x32_bf16 v[18:21], v[176:179], v[200:203], v[18:21]
	v_mfma_f32_16x16x32_bf16 v[6:9], v[168:171], v[228:231], v[6:9]
	v_mfma_f32_16x16x32_bf16 v[2:5], v[176:179], v[228:231], v[2:5]
	s_setprio 0
	s_add_i32 s49, s49, 2
	s_add_u32 s47, s47, 0x100
	s_addc_u32 s48, s48, 0
	s_mov_b64 s[14:15], s[16:17]
	s_add_u32 s16, s14, 0x100
	s_addc_u32 s17, s15, 0
	s_add_i32 s50, 0, 0x10000
	s_cmp_eq_u32 s49, 40
	s_cselect_b32 s21, s7, s17
	s_cselect_b32 s20, s6, s16
	v_add_u32_e32 v138, s50, v149
	s_cselect_b32 s19, s13, s48
	s_cselect_b32 s18, s12, s47
	s_add_i32 s51, 0, 0x14000
	s_cmp_gt_u32 s49, 41
	s_barrier
	s_cbranch_scc0 .LBB0_362
	v_lshl_add_u32 v138, s46, 8, v148
	v_lshl_or_b32 v139, s45, 8, v150
	v_lshlrev_b32_e32 v138, 11, v138
	v_lshl_add_u32 v138, v139, 1, v138
	global_load_dwordx4 v[152:155], v138, s[34:35]
	global_load_dwordx4 v[156:159], v138, s[34:35] offset:256
	v_add_u32_e32 v139, 0x8000, v138
	global_load_dwordx4 v[160:163], v139, s[34:35]
	global_load_dwordx4 v[164:167], v139, s[34:35] offset:256
	v_add_u32_e32 v139, 0x10000, v138
	global_load_dwordx4 v[168:171], v139, s[34:35]
	global_load_dwordx4 v[172:175], v139, s[34:35] offset:256
	v_add_u32_e32 v139, 0x18000, v138
	global_load_dwordx4 v[176:179], v139, s[34:35]
	global_load_dwordx4 v[180:183], v139, s[34:35] offset:256
	v_add_u32_e32 v139, 0x40000, v138
	global_load_dwordx4 v[184:187], v139, s[34:35]
	global_load_dwordx4 v[188:191], v139, s[34:35] offset:256
	v_add_u32_e32 v139, 0x48000, v138
	global_load_dwordx4 v[192:195], v139, s[34:35]
	global_load_dwordx4 v[196:199], v139, s[34:35] offset:256
	v_add_u32_e32 v139, 0x50000, v138
	global_load_dwordx4 v[200:203], v139, s[34:35]
	global_load_dwordx4 v[224:227], v139, s[34:35] offset:256
	v_add_u32_e32 v139, 0x58000, v138
	global_load_dwordx4 v[228:231], v139, s[34:35]
	global_load_dwordx4 v[232:235], v139, s[34:35] offset:256
	s_and_b64 vcc, exec, s[10:11]
	s_cbranch_vccz .LBB0_365
	s_barrier

; #define PG8_STAGE(bufoff, gbase, voff) do { _Pragma("unroll") for (int _i = 0; _i < 2; ++_i) \
;         __builtin_amdgcn_global_load_lds((const unsigned*)((const char*)(gbase) + (voff)[_i]), (PG8_LAS unsigned*)(lds + (bufoff) + ldsw + _i * 8192), 16, 0, 0); } while (0)
; #define PG8_LDA(dst, b, h) do { _Pragma("unroll") for (int m = 0; m < 4; ++m) _Pragma("unroll") for (int k = 0; k < 2; ++k) dst[m][k] = *(const PG8_LAS bf16x8*)(lds + PG8_SA(b, h) + aoff + m * 2048 + k * 1024); } while (0)
; #define PG8_LDB(dst, b, h) do { _Pragma("unroll") for (int n = 0; n < 2; ++n) _Pragma("unroll") for (int k = 0; k < 2; ++k) dst[n][k] = *(const PG8_LAS bf16x8*)(lds + PG8_SB(b, h) + boff + n * 2048 + k * 1024); } while (0)
; #define PG8_WAIT_V(n) asm volatile("s_waitcnt vmcnt(" #n ")" ::: "memory")
; #define PG8_WAIT_L(n) asm volatile("s_waitcnt lgkmcnt(" #n ")" ::: "memory")
; #define PG8_BAR __builtin_amdgcn_s_barrier()
; #define PG8_SCHED __builtin_amdgcn_sched_barrier(0)
; template <class Epi, class Sched, bool ALIGN_EPI = false, bool SP2 = false>
; __device__ __forceinline__ void gemm_phase(PG8_LAS unsigned char* lds, const Gemm g, const Sched& S, const Epi& E) {
;     ...
;         const bool has_next = S.next(ui + 1, nxt);
;         const char* nA = has_next ? (const char*)g.A + (size_t)nxt.pm * tstep : cA; const char* nB = has_next ? (const char*)g.Bt + (size_t)nxt.pn * tstep : cB;
;         for (int t = 0; t < nt; t += 2) {
;             const bool last = (t == nt - 2);
;             const char* a1 = cA + (size_t)(t + 1) * kstep;
;             const char* a2 = last ? nA : cA + (size_t)(t + 2) * kstep; const char* b2 = last ? nB : cB + (size_t)(t + 2) * kstep;
;             const char* a3 = a2 + kstep; const char* b3 = b2 + kstep;
;             if (last && has_next) S.a_ready(nxt);
;             if constexpr (SP2) {
;             PG8_LDB(B0, 0, 0); PG8_LDB(B1, 0, 1); PG8_SCHED; PG8_LDA(At, 0, 0); PG8_STAGE(PG8_SA(1, 1), a1 + hstep, voffA);
;             PG8_WAIT_V(8); PG8_WAIT_L(0); PG8_BAR; PG8_MMA(0, 0, At, B0); PG8_MMA(0, 1, At, B1); PG8_BAR; PG8_SCHED;
;             PG8_LDA(At, 0, 1); PG8_STAGE(PG8_SB(0, 0), b2, voffB); PG8_STAGE(PG8_SB(0, 1), b2 + hstep, voffB); PG8_STAGE(PG8_SA(0, 0), a2, voffA);
;             PG8_WAIT_V(8); PG8_WAIT_L(0); PG8_BAR; PG8_MMA(1, 0, At, B0); PG8_MMA(1, 1, At, B1); PG8_BAR; PG8_SCHED;
.LBB0_491:
	s_ashr_i32 s15, s14, 31
	s_lshl_b64 s[16:17], s[14:15], 19
	s_add_u32 s16, s34, s16
	s_addc_u32 s17, s35, s17
	s_and_b64 s[18:19], s[2:3], exec
	s_cselect_b32 s5, s17, s9
	s_cselect_b32 s7, s16, s8
	s_ashr_i32 s13, s12, 31
	s_lshl_b64 s[18:19], s[12:13], 19
	s_add_u32 s18, s27, s18
	s_addc_u32 s19, s29, s19
	s_and_b64 s[22:23], s[2:3], exec
	s_cselect_b32 s13, s19, s21
	s_cselect_b32 s15, s18, s20
	s_add_u32 s8, s8, 0x40080
	s_addc_u32 s9, s9, 0
	s_add_u32 s45, s20, 0x100
	s_addc_u32 s46, s21, 0
	s_mov_b32 s47, -2
	s_add_u32 s20, s8, 0xfffc0080
	s_addc_u32 s21, s9, -1
	s_add_i32 s48, 0, 0x10000
	s_cmp_eq_u32 s47, 12
	s_cselect_b32 s23, s5, s21
	s_cselect_b32 s22, s7, s20
	v_add_u32_e32 v138, s48, v161
	s_cselect_b32 s21, s13, s46
	s_cselect_b32 s20, s15, s45
	s_add_i32 s50, 0, 0x14000
	ds_read_b128 v[144:147], v138
	ds_read_b128 v[148:151], v138 offset:1024
	ds_read_b128 v[152:155], v138 offset:2048
	ds_read_b128 v[156:159], v138 offset:3072
	v_add_u32_e32 v138, s50, v161
	ds_read_b128 v[166:169], v138
	ds_read_b128 v[170:173], v138 offset:1024
	ds_read_b128 v[174:177], v138 offset:2048
	ds_read_b128 v[178:181], v138 offset:3072
	v_lshl_add_u64 v[138:139], s[8:9], 0, v[136:137]
	s_add_i32 m0, s30, 0xc000
	ds_read_b128 v[182:185], v164
	ds_read_b128 v[186:189], v164 offset:1024
	ds_read_b128 v[190:193], v164 offset:2048
	ds_read_b128 v[194:197], v164 offset:3072
	ds_read_b128 v[198:201], v164 offset:4096
	ds_read_b128 v[202:205], v164 offset:5120
	ds_read_b128 v[224:227], v164 offset:6144
	ds_read_b128 v[228:231], v164 offset:7168
	global_load_lds_dwordx4 v[138:139], off
	v_lshl_add_u64 v[138:139], s[8:9], 0, v[142:143]
	s_add_i32 m0, s30, 0xe000
	s_nop 0
	global_load_lds_dwordx4 v[138:139], off
	s_waitcnt vmcnt(8)
	s_waitcnt lgkmcnt(0)
	s_barrier
	s_setprio 1
	s_waitcnt lgkmcnt(0)
	v_mfma_f32_16x16x32_bf16 v[126:129], v[144:147], v[182:185], 0
	v_mfma_f32_16x16x32_bf16 v[122:125], v[152:155], v[182:185], 0
	v_mfma_f32_16x16x32_bf16 v[110:113], v[144:147], v[190:193], 0
	v_mfma_f32_16x16x32_bf16 v[106:109], v[152:155], v[190:193], 0
	v_mfma_f32_16x16x32_bf16 v[94:97], v[144:147], v[198:201], 0
	v_mfma_f32_16x16x32_bf16 v[90:93], v[152:155], v[198:201], 0
	v_mfma_f32_16x16x32_bf16 v[78:81], v[144:147], v[224:227], 0
	v_mfma_f32_16x16x32_bf16 v[74:77], v[152:155], v[224:227], 0
	v_mfma_f32_16x16x32_bf16 v[126:129], v[148:151], v[186:189], v[126:129]
	v_mfma_f32_16x16x32_bf16 v[122:125], v[156:159], v[186:189], v[122:125]
	v_mfma_f32_16x16x32_bf16 v[110:113], v[148:151], v[194:197], v[110:113]
	v_mfma_f32_16x16x32_bf16 v[106:109], v[156:159], v[194:197], v[106:109]
	v_mfma_f32_16x16x32_bf16 v[94:97], v[148:151], v[202:205], v[94:97]
	v_mfma_f32_16x16x32_bf16 v[90:93], v[156:159], v[202:205], v[90:93]
	v_mfma_f32_16x16x32_bf16 v[78:81], v[148:151], v[228:231], v[78:81]
	v_mfma_f32_16x16x32_bf16 v[74:77], v[156:159], v[228:231], v[74:77]
	s_setprio 0
	s_setprio 1
	v_mfma_f32_16x16x32_bf16 v[118:121], v[166:169], v[182:185], 0
	v_mfma_f32_16x16x32_bf16 v[114:117], v[174:177], v[182:185], 0
	v_mfma_f32_16x16x32_bf16 v[102:105], v[166:169], v[190:193], 0
	v_mfma_f32_16x16x32_bf16 v[98:101], v[174:177], v[190:193], 0
	v_mfma_f32_16x16x32_bf16 v[86:89], v[166:169], v[198:201], 0
	v_mfma_f32_16x16x32_bf16 v[82:85], v[174:177], v[198:201], 0
	v_mfma_f32_16x16x32_bf16 v[70:73], v[166:169], v[224:227], 0
	v_mfma_f32_16x16x32_bf16 v[66:69], v[174:177], v[224:227], 0
	v_mfma_f32_16x16x32_bf16 v[118:121], v[170:173], v[186:189], v[118:121]
	v_mfma_f32_16x16x32_bf16 v[114:117], v[178:181], v[186:189], v[114:117]
	v_mfma_f32_16x16x32_bf16 v[102:105], v[170:173], v[194:197], v[102:105]
	v_mfma_f32_16x16x32_bf16 v[98:101], v[178:181], v[194:197], v[98:101]
	v_mfma_f32_16x16x32_bf16 v[86:89], v[170:173], v[202:205], v[86:89]
	v_mfma_f32_16x16x32_bf16 v[82:85], v[178:181], v[202:205], v[82:85]
	v_mfma_f32_16x16x32_bf16 v[70:73], v[170:173], v[228:231], v[70:73]
	v_mfma_f32_16x16x32_bf16 v[66:69], v[178:181], v[228:231], v[66:69]
	s_setprio 0
	s_barrier
	s_add_i32 s48, s48, s26
	v_lshl_add_u64 v[138:139], s[20:21], 0, v[0:1]
	s_mov_b32 m0, s48
	ds_read_b128 v[182:185], v164 offset:16384
	ds_read_b128 v[186:189], v164 offset:17408
	ds_read_b128 v[190:193], v164 offset:18432
	ds_read_b128 v[194:197], v164 offset:19456
	ds_read_b128 v[198:201], v164 offset:20480
	ds_read_b128 v[202:205], v164 offset:21504
	ds_read_b128 v[224:227], v164 offset:22528
	ds_read_b128 v[228:231], v164 offset:23552
	global_load_lds_dwordx4 v[138:139], off
	s_add_i32 m0, s48, 0x2000
	s_add_u32 s48, s20, 0x40000
	v_lshl_add_u64 v[140:141], s[20:21], 0, v[134:135]
	s_addc_u32 s49, s21, 0
	s_add_i32 s50, s50, s26
	global_load_lds_dwordx4 v[140:141], off
	v_lshl_add_u64 v[232:233], s[48:49], 0, v[0:1]
	s_mov_b32 m0, s50
	v_lshl_add_u64 v[234:235], s[22:23], 0, v[132:133]
	global_load_lds_dwordx4 v[232:233], off
	v_lshl_add_u64 v[232:233], s[48:49], 0, v[134:135]
	s_add_i32 m0, s50, 0x2000
	s_nop 0
	global_load_lds_dwordx4 v[232:233], off
	v_lshl_add_u64 v[232:233], s[22:23], 0, v[130:131]
	s_mov_b32 m0, s30
	s_nop 0
	global_load_lds_dwordx4 v[232:233], off
	s_mov_b32 m0, s31
	s_nop 0
	global_load_lds_dwordx4 v[234:235], off
	s_waitcnt vmcnt(8)
	s_waitcnt lgkmcnt(0)
	s_barrier
; #define PG8_STAGE(bufoff, gbase, voff) do { _Pragma("unroll") for (int _i = 0; _i < 2; ++_i) \
;         __builtin_amdgcn_global_load_lds((const unsigned*)((const char*)(gbase) + (voff)[_i]), (PG8_LAS unsigned*)(lds + (bufoff) + ldsw + _i * 8192), 16, 0, 0); } while (0)
; #define PG8_LDA(dst, b, h) do { _Pragma("unroll") for (int m = 0; m < 4; ++m) _Pragma("unroll") for (int k = 0; k < 2; ++k) dst[m][k] = *(const PG8_LAS bf16x8*)(lds + PG8_SA(b, h) + aoff + m * 2048 + k * 1024); } while (0)
; #define PG8_LDB(dst, b, h) do { _Pragma("unroll") for (int n = 0; n < 2; ++n) _Pragma("unroll") for (int k = 0; k < 2; ++k) dst[n][k] = *(const PG8_LAS bf16x8*)(lds + PG8_SB(b, h) + boff + n * 2048 + k * 1024); } while (0)
; #define PG8_MMA(ai, bj, At, Bt) do { __builtin_amdgcn_s_setprio(1); _Pragma("unroll") for (int m = 0; m < 4; ++m) _Pragma("unroll") for (int n = 0; n < 2; ++n) _Pragma("unroll") for (int k = 0; k < 2; ++k) \
;         acc[ai][bj][m][n] = __builtin_amdgcn_mfma_f32_16x16x32_bf16(Bt[n][k], At[m][k], acc[ai][bj][m][n], 0, 0, 0); __builtin_amdgcn_s_setprio(0); } while (0)
; #define PG8_WAIT_V(n) asm volatile("s_waitcnt vmcnt(" #n ")" ::: "memory")
; #define PG8_WAIT_L(n) asm volatile("s_waitcnt lgkmcnt(" #n ")" ::: "memory")
; #define PG8_BAR __builtin_amdgcn_s_barrier()
; #define PG8_SCHED __builtin_amdgcn_sched_barrier(0)
; template <class Epi, class Sched, bool ALIGN_EPI = false, bool SP2 = false>
; __device__ __forceinline__ void gemm_phase(PG8_LAS unsigned char* lds, const Gemm g, const Sched& S, const Epi& E) {
;     ...
;             PG8_WAIT_V(8); PG8_WAIT_L(0); PG8_BAR; PG8_MMA(1, 0, At, B0); PG8_MMA(1, 1, At, B1); PG8_BAR; PG8_SCHED;
;             PG8_LDB(B0, 1, 0); PG8_LDB(B1, 1, 1); PG8_SCHED; PG8_LDA(At, 1, 0); PG8_STAGE(PG8_SA(0, 1), a2 + hstep, voffA);
;             PG8_WAIT_V(8); PG8_WAIT_L(0); PG8_BAR; PG8_MMA(0, 0, At, B0); PG8_MMA(0, 1, At, B1); PG8_BAR; PG8_SCHED;
	s_setprio 1
	s_waitcnt lgkmcnt(0)
	v_mfma_f32_16x16x32_bf16 v[62:65], v[144:147], v[182:185], 0
	v_mfma_f32_16x16x32_bf16 v[58:61], v[152:155], v[182:185], 0
	v_mfma_f32_16x16x32_bf16 v[46:49], v[144:147], v[190:193], 0
	v_mfma_f32_16x16x32_bf16 v[42:45], v[152:155], v[190:193], 0
	v_mfma_f32_16x16x32_bf16 v[30:33], v[144:147], v[198:201], 0
	v_mfma_f32_16x16x32_bf16 v[26:29], v[152:155], v[198:201], 0
	v_mfma_f32_16x16x32_bf16 v[14:17], v[144:147], v[224:227], 0
	v_mfma_f32_16x16x32_bf16 v[10:13], v[152:155], v[224:227], 0
	v_mfma_f32_16x16x32_bf16 v[62:65], v[148:151], v[186:189], v[62:65]
	v_mfma_f32_16x16x32_bf16 v[58:61], v[156:159], v[186:189], v[58:61]
	v_mfma_f32_16x16x32_bf16 v[46:49], v[148:151], v[194:197], v[46:49]
	v_mfma_f32_16x16x32_bf16 v[42:45], v[156:159], v[194:197], v[42:45]
	v_mfma_f32_16x16x32_bf16 v[30:33], v[148:151], v[202:205], v[30:33]
	v_mfma_f32_16x16x32_bf16 v[26:29], v[156:159], v[202:205], v[26:29]
	v_mfma_f32_16x16x32_bf16 v[14:17], v[148:151], v[228:231], v[14:17]
	v_mfma_f32_16x16x32_bf16 v[10:13], v[156:159], v[228:231], v[10:13]
	s_setprio 0
	s_setprio 1
	v_mfma_f32_16x16x32_bf16 v[54:57], v[166:169], v[182:185], 0
	v_mfma_f32_16x16x32_bf16 v[50:53], v[174:177], v[182:185], 0
	v_mfma_f32_16x16x32_bf16 v[38:41], v[166:169], v[190:193], 0
	v_mfma_f32_16x16x32_bf16 v[34:37], v[174:177], v[190:193], 0
	v_mfma_f32_16x16x32_bf16 v[22:25], v[166:169], v[198:201], 0
	v_mfma_f32_16x16x32_bf16 v[18:21], v[174:177], v[198:201], 0
	v_mfma_f32_16x16x32_bf16 v[6:9], v[166:169], v[224:227], 0
	v_mfma_f32_16x16x32_bf16 v[2:5], v[174:177], v[224:227], 0
	v_mfma_f32_16x16x32_bf16 v[54:57], v[170:173], v[186:189], v[54:57]
	v_mfma_f32_16x16x32_bf16 v[50:53], v[178:181], v[186:189], v[50:53]
	v_mfma_f32_16x16x32_bf16 v[38:41], v[170:173], v[194:197], v[38:41]
	v_mfma_f32_16x16x32_bf16 v[34:37], v[178:181], v[194:197], v[34:37]
	v_mfma_f32_16x16x32_bf16 v[22:25], v[170:173], v[202:205], v[22:25]
	v_mfma_f32_16x16x32_bf16 v[18:21], v[178:181], v[202:205], v[18:21]
	v_mfma_f32_16x16x32_bf16 v[6:9], v[170:173], v[228:231], v[6:9]
	v_mfma_f32_16x16x32_bf16 v[2:5], v[178:181], v[228:231], v[2:5]
	s_setprio 0
	s_barrier
	s_add_i32 s48, 0, 0x18000
	s_add_i32 s49, 0, 0x1c000
	v_add_u32_e32 v156, s48, v161
	v_add_u32_e32 v165, s49, v161
	ds_read_b128 v[144:147], v156
	ds_read_b128 v[148:151], v156 offset:1024
	ds_read_b128 v[152:155], v156 offset:2048
	ds_read_b128 v[156:159], v156 offset:3072
	ds_read_b128 v[166:169], v165
	ds_read_b128 v[170:173], v165 offset:1024
	ds_read_b128 v[174:177], v165 offset:2048
	ds_read_b128 v[178:181], v165 offset:3072
	s_add_u32 s22, s22, 0x40000
	s_addc_u32 s23, s23, 0
	s_mov_b32 m0, s38
	v_lshl_add_u64 v[236:237], s[22:23], 0, v[130:131]
	ds_read_b128 v[182:185], v164 offset:32768
	ds_read_b128 v[186:189], v164 offset:33792
	ds_read_b128 v[190:193], v164 offset:34816
	ds_read_b128 v[194:197], v164 offset:35840
	ds_read_b128 v[198:201], v164 offset:36864
	ds_read_b128 v[202:205], v164 offset:37888
	ds_read_b128 v[224:227], v164 offset:38912
	ds_read_b128 v[228:231], v164 offset:39936
	global_load_lds_dwordx4 v[236:237], off
	v_lshl_add_u64 v[236:237], s[22:23], 0, v[132:133]
	s_mov_b32 m0, s39
	s_nop 0
	global_load_lds_dwordx4 v[236:237], off
	s_waitcnt vmcnt(8)
	s_waitcnt lgkmcnt(0)
	s_barrier
	s_setprio 1
	s_waitcnt lgkmcnt(0)
	v_mfma_f32_16x16x32_bf16 v[126:129], v[144:147], v[182:185], v[126:129]
	v_mfma_f32_16x16x32_bf16 v[122:125], v[152:155], v[182:185], v[122:125]
	v_mfma_f32_16x16x32_bf16 v[110:113], v[144:147], v[190:193], v[110:113]
	v_mfma_f32_16x16x32_bf16 v[106:109], v[152:155], v[190:193], v[106:109]
	v_mfma_f32_16x16x32_bf16 v[94:97], v[144:147], v[198:201], v[94:97]
	v_mfma_f32_16x16x32_bf16 v[90:93], v[152:155], v[198:201], v[90:93]
	v_mfma_f32_16x16x32_bf16 v[78:81], v[144:147], v[224:227], v[78:81]
	v_mfma_f32_16x16x32_bf16 v[74:77], v[152:155], v[224:227], v[74:77]
	v_mfma_f32_16x16x32_bf16 v[126:129], v[148:151], v[186:189], v[126:129]
	v_mfma_f32_16x16x32_bf16 v[122:125], v[156:159], v[186:189], v[122:125]
	v_mfma_f32_16x16x32_bf16 v[110:113], v[148:151], v[194:197], v[110:113]
	v_mfma_f32_16x16x32_bf16 v[106:109], v[156:159], v[194:197], v[106:109]
	v_mfma_f32_16x16x32_bf16 v[94:97], v[148:151], v[202:205], v[94:97]
	v_mfma_f32_16x16x32_bf16 v[90:93], v[156:159], v[202:205], v[90:93]
	v_mfma_f32_16x16x32_bf16 v[78:81], v[148:151], v[228:231], v[78:81]
	v_mfma_f32_16x16x32_bf16 v[74:77], v[156:159], v[228:231], v[74:77]
	s_setprio 0
	s_setprio 1
	v_mfma_f32_16x16x32_bf16 v[118:121], v[166:169], v[182:185], v[118:121]
	v_mfma_f32_16x16x32_bf16 v[114:117], v[174:177], v[182:185], v[114:117]
	v_mfma_f32_16x16x32_bf16 v[102:105], v[166:169], v[190:193], v[102:105]
	v_mfma_f32_16x16x32_bf16 v[98:101], v[174:177], v[190:193], v[98:101]
	v_mfma_f32_16x16x32_bf16 v[86:89], v[166:169], v[198:201], v[86:89]
	v_mfma_f32_16x16x32_bf16 v[82:85], v[174:177], v[198:201], v[82:85]
	v_mfma_f32_16x16x32_bf16 v[70:73], v[166:169], v[224:227], v[70:73]
	v_mfma_f32_16x16x32_bf16 v[66:69], v[174:177], v[224:227], v[66:69]
	v_mfma_f32_16x16x32_bf16 v[118:121], v[170:173], v[186:189], v[118:121]
	v_mfma_f32_16x16x32_bf16 v[114:117], v[178:181], v[186:189], v[114:117]
	v_mfma_f32_16x16x32_bf16 v[102:105], v[170:173], v[194:197], v[102:105]
	v_mfma_f32_16x16x32_bf16 v[98:101], v[178:181], v[194:197], v[98:101]
	v_mfma_f32_16x16x32_bf16 v[86:89], v[170:173], v[202:205], v[86:89]
	v_mfma_f32_16x16x32_bf16 v[82:85], v[178:181], v[202:205], v[82:85]
	v_mfma_f32_16x16x32_bf16 v[70:73], v[170:173], v[228:231], v[70:73]
	v_mfma_f32_16x16x32_bf16 v[66:69], v[178:181], v[228:231], v[66:69]
	s_setprio 0
	s_barrier
; #define PG8_STAGE(bufoff, gbase, voff) do { _Pragma("unroll") for (int _i = 0; _i < 2; ++_i) \
;         __builtin_amdgcn_global_load_lds((const unsigned*)((const char*)(gbase) + (voff)[_i]), (PG8_LAS unsigned*)(lds + (bufoff) + ldsw + _i * 8192), 16, 0, 0); } while (0)
; #define PG8_LDA(dst, b, h) do { _Pragma("unroll") for (int m = 0; m < 4; ++m) _Pragma("unroll") for (int k = 0; k < 2; ++k) dst[m][k] = *(const PG8_LAS bf16x8*)(lds + PG8_SA(b, h) + aoff + m * 2048 + k * 1024); } while (0)
; #define PG8_LDB(dst, b, h) do { _Pragma("unroll") for (int n = 0; n < 2; ++n) _Pragma("unroll") for (int k = 0; k < 2; ++k) dst[n][k] = *(const PG8_LAS bf16x8*)(lds + PG8_SB(b, h) + boff + n * 2048 + k * 1024); } while (0)
; template <class Epi, class Sched, bool ALIGN_EPI = false, bool SP2 = false>
; __device__ __forceinline__ void gemm_phase(PG8_LAS unsigned char* lds, const Gemm g, const Sched& S, const Epi& E) {
;     ...
;         for (int t = 0; t < nt; t += 2) {
;             const bool last = (t == nt - 2);
;             const char* a1 = cA + (size_t)(t + 1) * kstep;
;             const char* a2 = last ? nA : cA + (size_t)(t + 2) * kstep; const char* b2 = last ? nB : cB + (size_t)(t + 2) * kstep;
;             const char* a3 = a2 + kstep; const char* b3 = b2 + kstep;
;             if (last && has_next) S.a_ready(nxt);
;             if constexpr (SP2) {
;             PG8_LDB(B0, 0, 0); PG8_LDB(B1, 0, 1); PG8_SCHED; PG8_LDA(At, 0, 0); PG8_STAGE(PG8_SA(1, 1), a1 + hstep, voffA);
;             PG8_WAIT_V(8); PG8_WAIT_L(0); PG8_BAR; PG8_MMA(0, 0, At, B0); PG8_MMA(0, 1, At, B1); PG8_BAR; PG8_SCHED;
;             PG8_LDA(At, 0, 1); PG8_STAGE(PG8_SB(0, 0), b2, voffB); PG8_STAGE(PG8_SB(0, 1), b2 + hstep, voffB); PG8_STAGE(PG8_SA(0, 0), a2, voffA);
;             PG8_WAIT_V(8); PG8_WAIT_L(0); PG8_BAR; PG8_MMA(1, 0, At, B0); PG8_MMA(1, 1, At, B1); PG8_BAR; PG8_SCHED;
;             PG8_LDB(B0, 1, 0); PG8_LDB(B1, 1, 1); PG8_SCHED; PG8_LDA(At, 1, 0); PG8_STAGE(PG8_SA(0, 1), a2 + hstep, voffA);
;             PG8_WAIT_V(8); PG8_WAIT_L(0); PG8_BAR; PG8_MMA(0, 0, At, B0); PG8_MMA(0, 1, At, B1); PG8_BAR; PG8_SCHED;
;             PG8_LDA(At, 1, 1); PG8_STAGE(PG8_SB(1, 0), b3, voffB); PG8_STAGE(PG8_SB(1, 1), b3 + hstep, voffB); PG8_STAGE(PG8_SA(1, 0), a3, voffA);
;             PG8_WAIT_V(8); PG8_WAIT_L(0); PG8_BAR; PG8_MMA(1, 0, At, B0); PG8_MMA(1, 1, At, B1); PG8_BAR; PG8_SCHED;
	s_add_i32 s22, s48, s26
	v_lshl_add_u64 v[138:139], v[138:139], 0, s[86:87]
	s_mov_b32 m0, s22
	ds_read_b128 v[182:185], v164 offset:49152
	ds_read_b128 v[186:189], v164 offset:50176
	ds_read_b128 v[190:193], v164 offset:51200
	ds_read_b128 v[194:197], v164 offset:52224
	ds_read_b128 v[198:201], v164 offset:53248
	ds_read_b128 v[202:205], v164 offset:54272
	ds_read_b128 v[224:227], v164 offset:55296
	ds_read_b128 v[228:231], v164 offset:56320
	global_load_lds_dwordx4 v[138:139], off
	s_add_i32 m0, s22, 0x2000
	s_add_u32 s20, s20, 0x40080
	v_lshl_add_u64 v[138:139], v[140:141], 0, s[86:87]
	s_addc_u32 s21, s21, 0
	s_add_i32 s22, s49, s26
	global_load_lds_dwordx4 v[138:139], off
	v_lshl_add_u64 v[138:139], s[20:21], 0, v[0:1]
	s_mov_b32 m0, s22
	s_nop 0
	global_load_lds_dwordx4 v[138:139], off
	v_lshl_add_u64 v[138:139], s[20:21], 0, v[134:135]
	s_add_i32 m0, s22, 0x2000
	s_nop 0
	global_load_lds_dwordx4 v[138:139], off
	v_lshl_add_u64 v[138:139], v[232:233], 0, s[86:87]
	s_mov_b32 m0, s41
	s_nop 0
	global_load_lds_dwordx4 v[138:139], off
	v_lshl_add_u64 v[138:139], v[234:235], 0, s[86:87]
	s_mov_b32 m0, s42
	s_nop 0
	global_load_lds_dwordx4 v[138:139], off
	s_waitcnt vmcnt(8)
	s_waitcnt lgkmcnt(0)
	s_barrier
	s_setprio 1
	s_waitcnt lgkmcnt(0)
	v_mfma_f32_16x16x32_bf16 v[62:65], v[144:147], v[182:185], v[62:65]
	v_mfma_f32_16x16x32_bf16 v[58:61], v[152:155], v[182:185], v[58:61]
	v_mfma_f32_16x16x32_bf16 v[46:49], v[144:147], v[190:193], v[46:49]
	v_mfma_f32_16x16x32_bf16 v[42:45], v[152:155], v[190:193], v[42:45]
	v_mfma_f32_16x16x32_bf16 v[30:33], v[144:147], v[198:201], v[30:33]
	v_mfma_f32_16x16x32_bf16 v[26:29], v[152:155], v[198:201], v[26:29]
	v_mfma_f32_16x16x32_bf16 v[14:17], v[144:147], v[224:227], v[14:17]
	v_mfma_f32_16x16x32_bf16 v[10:13], v[152:155], v[224:227], v[10:13]
	v_mfma_f32_16x16x32_bf16 v[62:65], v[148:151], v[186:189], v[62:65]
	v_mfma_f32_16x16x32_bf16 v[58:61], v[156:159], v[186:189], v[58:61]
	v_mfma_f32_16x16x32_bf16 v[46:49], v[148:151], v[194:197], v[46:49]
	v_mfma_f32_16x16x32_bf16 v[42:45], v[156:159], v[194:197], v[42:45]
	v_mfma_f32_16x16x32_bf16 v[30:33], v[148:151], v[202:205], v[30:33]
	v_mfma_f32_16x16x32_bf16 v[26:29], v[156:159], v[202:205], v[26:29]
	v_mfma_f32_16x16x32_bf16 v[14:17], v[148:151], v[228:231], v[14:17]
	v_mfma_f32_16x16x32_bf16 v[10:13], v[156:159], v[228:231], v[10:13]
	s_setprio 0
	s_setprio 1
	v_mfma_f32_16x16x32_bf16 v[54:57], v[166:169], v[182:185], v[54:57]
	v_mfma_f32_16x16x32_bf16 v[50:53], v[174:177], v[182:185], v[50:53]
	v_mfma_f32_16x16x32_bf16 v[38:41], v[166:169], v[190:193], v[38:41]
	v_mfma_f32_16x16x32_bf16 v[34:37], v[174:177], v[190:193], v[34:37]
	v_mfma_f32_16x16x32_bf16 v[22:25], v[166:169], v[198:201], v[22:25]
	v_mfma_f32_16x16x32_bf16 v[18:21], v[174:177], v[198:201], v[18:21]
	v_mfma_f32_16x16x32_bf16 v[6:9], v[166:169], v[224:227], v[6:9]
	v_mfma_f32_16x16x32_bf16 v[2:5], v[174:177], v[224:227], v[2:5]
	v_mfma_f32_16x16x32_bf16 v[54:57], v[170:173], v[186:189], v[54:57]
	v_mfma_f32_16x16x32_bf16 v[50:53], v[178:181], v[186:189], v[50:53]
	v_mfma_f32_16x16x32_bf16 v[38:41], v[170:173], v[194:197], v[38:41]
	v_mfma_f32_16x16x32_bf16 v[34:37], v[178:181], v[194:197], v[34:37]
	v_mfma_f32_16x16x32_bf16 v[22:25], v[170:173], v[202:205], v[22:25]
	v_mfma_f32_16x16x32_bf16 v[18:21], v[178:181], v[202:205], v[18:21]
	v_mfma_f32_16x16x32_bf16 v[6:9], v[170:173], v[228:231], v[6:9]
	v_mfma_f32_16x16x32_bf16 v[2:5], v[178:181], v[228:231], v[2:5]
	s_setprio 0
	s_add_i32 s47, s47, 2
	s_add_u32 s8, s8, 0x100
	s_addc_u32 s9, s9, 0
	s_add_u32 s45, s45, 0x100
	s_addc_u32 s46, s46, 0
	s_add_u32 s20, s8, 0xfffc0080
	s_addc_u32 s21, s9, -1
	s_add_i32 s48, 0, 0x10000
	s_cmp_eq_u32 s47, 12
	s_cselect_b32 s23, s5, s21
	s_cselect_b32 s22, s7, s20
	v_add_u32_e32 v138, s48, v161
	s_cselect_b32 s21, s13, s46
	s_cselect_b32 s20, s15, s45
	s_add_i32 s50, 0, 0x14000
	s_cmp_gt_u32 s47, 13
	s_barrier
	s_cbranch_scc1 .Lpeel_exit_pj
.LBB0_492:
	ds_read_b128 v[144:147], v138
	ds_read_b128 v[148:151], v138 offset:1024
	ds_read_b128 v[152:155], v138 offset:2048
	ds_read_b128 v[156:159], v138 offset:3072
	v_add_u32_e32 v138, s50, v161
	ds_read_b128 v[166:169], v138
	ds_read_b128 v[170:173], v138 offset:1024
	ds_read_b128 v[174:177], v138 offset:2048
	ds_read_b128 v[178:181], v138 offset:3072
	v_lshl_add_u64 v[138:139], s[8:9], 0, v[136:137]
	s_add_i32 m0, s30, 0xc000
	ds_read_b128 v[182:185], v164
	ds_read_b128 v[186:189], v164 offset:1024
	ds_read_b128 v[190:193], v164 offset:2048
	ds_read_b128 v[194:197], v164 offset:3072
	ds_read_b128 v[198:201], v164 offset:4096
	ds_read_b128 v[202:205], v164 offset:5120
	ds_read_b128 v[224:227], v164 offset:6144
	ds_read_b128 v[228:231], v164 offset:7168
	global_load_lds_dwordx4 v[138:139], off
	v_lshl_add_u64 v[138:139], s[8:9], 0, v[142:143]
	s_add_i32 m0, s30, 0xe000
	s_nop 0
	global_load_lds_dwordx4 v[138:139], off
	s_waitcnt vmcnt(8)
	s_waitcnt lgkmcnt(0)
	s_barrier
; #define PG8_STAGE(bufoff, gbase, voff) do { _Pragma("unroll") for (int _i = 0; _i < 2; ++_i) \
;         __builtin_amdgcn_global_load_lds((const unsigned*)((const char*)(gbase) + (voff)[_i]), (PG8_LAS unsigned*)(lds + (bufoff) + ldsw + _i * 8192), 16, 0, 0); } while (0)
; #define PG8_LDA(dst, b, h) do { _Pragma("unroll") for (int m = 0; m < 4; ++m) _Pragma("unroll") for (int k = 0; k < 2; ++k) dst[m][k] = *(const PG8_LAS bf16x8*)(lds + PG8_SA(b, h) + aoff + m * 2048 + k * 1024); } while (0)
; #define PG8_MMA(ai, bj, At, Bt) do { __builtin_amdgcn_s_setprio(1); _Pragma("unroll") for (int m = 0; m < 4; ++m) _Pragma("unroll") for (int n = 0; n < 2; ++n) _Pragma("unroll") for (int k = 0; k < 2; ++k) \
;         acc[ai][bj][m][n] = __builtin_amdgcn_mfma_f32_16x16x32_bf16(Bt[n][k], At[m][k], acc[ai][bj][m][n], 0, 0, 0); __builtin_amdgcn_s_setprio(0); } while (0)
; #define PG8_WAIT_V(n) asm volatile("s_waitcnt vmcnt(" #n ")" ::: "memory")
; #define PG8_WAIT_L(n) asm volatile("s_waitcnt lgkmcnt(" #n ")" ::: "memory")
; #define PG8_BAR __builtin_amdgcn_s_barrier()
; #define PG8_SCHED __builtin_amdgcn_sched_barrier(0)
; template <class Epi, class Sched, bool ALIGN_EPI = false, bool SP2 = false>
; __device__ __forceinline__ void gemm_phase(PG8_LAS unsigned char* lds, const Gemm g, const Sched& S, const Epi& E) {
;     ...
;             PG8_WAIT_V(8); PG8_WAIT_L(0); PG8_BAR; PG8_MMA(0, 0, At, B0); PG8_MMA(0, 1, At, B1); PG8_BAR; PG8_SCHED;
;             PG8_LDA(At, 0, 1); PG8_STAGE(PG8_SB(0, 0), b2, voffB); PG8_STAGE(PG8_SB(0, 1), b2 + hstep, voffB); PG8_STAGE(PG8_SA(0, 0), a2, voffA);
;             PG8_WAIT_V(8); PG8_WAIT_L(0); PG8_BAR; PG8_MMA(1, 0, At, B0); PG8_MMA(1, 1, At, B1); PG8_BAR; PG8_SCHED;
	s_setprio 1
	s_waitcnt lgkmcnt(0)
	v_mfma_f32_16x16x32_bf16 v[126:129], v[144:147], v[182:185], v[126:129]
	v_mfma_f32_16x16x32_bf16 v[122:125], v[152:155], v[182:185], v[122:125]
	v_mfma_f32_16x16x32_bf16 v[110:113], v[144:147], v[190:193], v[110:113]
	v_mfma_f32_16x16x32_bf16 v[106:109], v[152:155], v[190:193], v[106:109]
	v_mfma_f32_16x16x32_bf16 v[94:97], v[144:147], v[198:201], v[94:97]
	v_mfma_f32_16x16x32_bf16 v[90:93], v[152:155], v[198:201], v[90:93]
	v_mfma_f32_16x16x32_bf16 v[78:81], v[144:147], v[224:227], v[78:81]
	v_mfma_f32_16x16x32_bf16 v[74:77], v[152:155], v[224:227], v[74:77]
	v_mfma_f32_16x16x32_bf16 v[126:129], v[148:151], v[186:189], v[126:129]
	v_mfma_f32_16x16x32_bf16 v[122:125], v[156:159], v[186:189], v[122:125]
	v_mfma_f32_16x16x32_bf16 v[110:113], v[148:151], v[194:197], v[110:113]
	v_mfma_f32_16x16x32_bf16 v[106:109], v[156:159], v[194:197], v[106:109]
	v_mfma_f32_16x16x32_bf16 v[94:97], v[148:151], v[202:205], v[94:97]
	v_mfma_f32_16x16x32_bf16 v[90:93], v[156:159], v[202:205], v[90:93]
	v_mfma_f32_16x16x32_bf16 v[78:81], v[148:151], v[228:231], v[78:81]
	v_mfma_f32_16x16x32_bf16 v[74:77], v[156:159], v[228:231], v[74:77]
	s_setprio 0
	s_setprio 1
	v_mfma_f32_16x16x32_bf16 v[118:121], v[166:169], v[182:185], v[118:121]
	v_mfma_f32_16x16x32_bf16 v[114:117], v[174:177], v[182:185], v[114:117]
	v_mfma_f32_16x16x32_bf16 v[102:105], v[166:169], v[190:193], v[102:105]
	v_mfma_f32_16x16x32_bf16 v[98:101], v[174:177], v[190:193], v[98:101]
	v_mfma_f32_16x16x32_bf16 v[86:89], v[166:169], v[198:201], v[86:89]
	v_mfma_f32_16x16x32_bf16 v[82:85], v[174:177], v[198:201], v[82:85]
	v_mfma_f32_16x16x32_bf16 v[70:73], v[166:169], v[224:227], v[70:73]
	v_mfma_f32_16x16x32_bf16 v[66:69], v[174:177], v[224:227], v[66:69]
	v_mfma_f32_16x16x32_bf16 v[118:121], v[170:173], v[186:189], v[118:121]
	v_mfma_f32_16x16x32_bf16 v[114:117], v[178:181], v[186:189], v[114:117]
	v_mfma_f32_16x16x32_bf16 v[102:105], v[170:173], v[194:197], v[102:105]
	v_mfma_f32_16x16x32_bf16 v[98:101], v[178:181], v[194:197], v[98:101]
	v_mfma_f32_16x16x32_bf16 v[86:89], v[170:173], v[202:205], v[86:89]
	v_mfma_f32_16x16x32_bf16 v[82:85], v[178:181], v[202:205], v[82:85]
	v_mfma_f32_16x16x32_bf16 v[70:73], v[170:173], v[228:231], v[70:73]
	v_mfma_f32_16x16x32_bf16 v[66:69], v[178:181], v[228:231], v[66:69]
	s_setprio 0
	s_barrier
	s_add_i32 s48, s48, s26
	v_lshl_add_u64 v[138:139], s[20:21], 0, v[0:1]
	s_mov_b32 m0, s48
	ds_read_b128 v[182:185], v164 offset:16384
	ds_read_b128 v[186:189], v164 offset:17408
	ds_read_b128 v[190:193], v164 offset:18432
	ds_read_b128 v[194:197], v164 offset:19456
	ds_read_b128 v[198:201], v164 offset:20480
	ds_read_b128 v[202:205], v164 offset:21504
	ds_read_b128 v[224:227], v164 offset:22528
	ds_read_b128 v[228:231], v164 offset:23552
	global_load_lds_dwordx4 v[138:139], off
	s_add_i32 m0, s48, 0x2000
	s_add_u32 s48, s20, 0x40000
	v_lshl_add_u64 v[140:141], s[20:21], 0, v[134:135]
	s_addc_u32 s49, s21, 0
	s_add_i32 s50, s50, s26
	global_load_lds_dwordx4 v[140:141], off
	v_lshl_add_u64 v[232:233], s[48:49], 0, v[0:1]
	s_mov_b32 m0, s50
	v_lshl_add_u64 v[234:235], s[22:23], 0, v[132:133]
	global_load_lds_dwordx4 v[232:233], off
	v_lshl_add_u64 v[232:233], s[48:49], 0, v[134:135]
	s_add_i32 m0, s50, 0x2000
	s_nop 0
	global_load_lds_dwordx4 v[232:233], off
	v_lshl_add_u64 v[232:233], s[22:23], 0, v[130:131]
	s_mov_b32 m0, s30
	s_nop 0
	global_load_lds_dwordx4 v[232:233], off
	s_mov_b32 m0, s31
	s_nop 0
	global_load_lds_dwordx4 v[234:235], off
	s_waitcnt vmcnt(8)
	s_waitcnt lgkmcnt(0)
	s_barrier
	s_setprio 1
	s_waitcnt lgkmcnt(0)
	v_mfma_f32_16x16x32_bf16 v[62:65], v[144:147], v[182:185], v[62:65]
	v_mfma_f32_16x16x32_bf16 v[58:61], v[152:155], v[182:185], v[58:61]
	v_mfma_f32_16x16x32_bf16 v[46:49], v[144:147], v[190:193], v[46:49]
	v_mfma_f32_16x16x32_bf16 v[42:45], v[152:155], v[190:193], v[42:45]
	v_mfma_f32_16x16x32_bf16 v[30:33], v[144:147], v[198:201], v[30:33]
	v_mfma_f32_16x16x32_bf16 v[26:29], v[152:155], v[198:201], v[26:29]
	v_mfma_f32_16x16x32_bf16 v[14:17], v[144:147], v[224:227], v[14:17]
	v_mfma_f32_16x16x32_bf16 v[10:13], v[152:155], v[224:227], v[10:13]
	v_mfma_f32_16x16x32_bf16 v[62:65], v[148:151], v[186:189], v[62:65]
	v_mfma_f32_16x16x32_bf16 v[58:61], v[156:159], v[186:189], v[58:61]
	v_mfma_f32_16x16x32_bf16 v[46:49], v[148:151], v[194:197], v[46:49]
	v_mfma_f32_16x16x32_bf16 v[42:45], v[156:159], v[194:197], v[42:45]
	v_mfma_f32_16x16x32_bf16 v[30:33], v[148:151], v[202:205], v[30:33]
	v_mfma_f32_16x16x32_bf16 v[26:29], v[156:159], v[202:205], v[26:29]
	v_mfma_f32_16x16x32_bf16 v[14:17], v[148:151], v[228:231], v[14:17]
	v_mfma_f32_16x16x32_bf16 v[10:13], v[156:159], v[228:231], v[10:13]
	s_setprio 0
	s_setprio 1
	v_mfma_f32_16x16x32_bf16 v[54:57], v[166:169], v[182:185], v[54:57]
	v_mfma_f32_16x16x32_bf16 v[50:53], v[174:177], v[182:185], v[50:53]
	v_mfma_f32_16x16x32_bf16 v[38:41], v[166:169], v[190:193], v[38:41]
	v_mfma_f32_16x16x32_bf16 v[34:37], v[174:177], v[190:193], v[34:37]
	v_mfma_f32_16x16x32_bf16 v[22:25], v[166:169], v[198:201], v[22:25]
	v_mfma_f32_16x16x32_bf16 v[18:21], v[174:177], v[198:201], v[18:21]
	v_mfma_f32_16x16x32_bf16 v[6:9], v[166:169], v[224:227], v[6:9]
	v_mfma_f32_16x16x32_bf16 v[2:5], v[174:177], v[224:227], v[2:5]
	v_mfma_f32_16x16x32_bf16 v[54:57], v[170:173], v[186:189], v[54:57]
	v_mfma_f32_16x16x32_bf16 v[50:53], v[178:181], v[186:189], v[50:53]
	v_mfma_f32_16x16x32_bf16 v[38:41], v[170:173], v[194:197], v[38:41]
	v_mfma_f32_16x16x32_bf16 v[34:37], v[178:181], v[194:197], v[34:37]
	v_mfma_f32_16x16x32_bf16 v[22:25], v[170:173], v[202:205], v[22:25]
	v_mfma_f32_16x16x32_bf16 v[18:21], v[178:181], v[202:205], v[18:21]
	v_mfma_f32_16x16x32_bf16 v[6:9], v[170:173], v[228:231], v[6:9]
	v_mfma_f32_16x16x32_bf16 v[2:5], v[178:181], v[228:231], v[2:5]
	s_setprio 0
	s_barrier
; #define PG8_STAGE(bufoff, gbase, voff) do { _Pragma("unroll") for (int _i = 0; _i < 2; ++_i) \
;         __builtin_amdgcn_global_load_lds((const unsigned*)((const char*)(gbase) + (voff)[_i]), (PG8_LAS unsigned*)(lds + (bufoff) + ldsw + _i * 8192), 16, 0, 0); } while (0)
; #define PG8_LDA(dst, b, h) do { _Pragma("unroll") for (int m = 0; m < 4; ++m) _Pragma("unroll") for (int k = 0; k < 2; ++k) dst[m][k] = *(const PG8_LAS bf16x8*)(lds + PG8_SA(b, h) + aoff + m * 2048 + k * 1024); } while (0)
; #define PG8_LDB(dst, b, h) do { _Pragma("unroll") for (int n = 0; n < 2; ++n) _Pragma("unroll") for (int k = 0; k < 2; ++k) dst[n][k] = *(const PG8_LAS bf16x8*)(lds + PG8_SB(b, h) + boff + n * 2048 + k * 1024); } while (0)
; #define PG8_MMA(ai, bj, At, Bt) do { __builtin_amdgcn_s_setprio(1); _Pragma("unroll") for (int m = 0; m < 4; ++m) _Pragma("unroll") for (int n = 0; n < 2; ++n) _Pragma("unroll") for (int k = 0; k < 2; ++k) \
;         acc[ai][bj][m][n] = __builtin_amdgcn_mfma_f32_16x16x32_bf16(Bt[n][k], At[m][k], acc[ai][bj][m][n], 0, 0, 0); __builtin_amdgcn_s_setprio(0); } while (0)
; #define PG8_WAIT_V(n) asm volatile("s_waitcnt vmcnt(" #n ")" ::: "memory")
; #define PG8_WAIT_L(n) asm volatile("s_waitcnt lgkmcnt(" #n ")" ::: "memory")
; #define PG8_BAR __builtin_amdgcn_s_barrier()
; #define PG8_SCHED __builtin_amdgcn_sched_barrier(0)
; template <class Epi, class Sched, bool ALIGN_EPI = false, bool SP2 = false>
; __device__ __forceinline__ void gemm_phase(PG8_LAS unsigned char* lds, const Gemm g, const Sched& S, const Epi& E) {
;     ...
;             PG8_LDB(B0, 1, 0); PG8_LDB(B1, 1, 1); PG8_SCHED; PG8_LDA(At, 1, 0); PG8_STAGE(PG8_SA(0, 1), a2 + hstep, voffA);
;             PG8_WAIT_V(8); PG8_WAIT_L(0); PG8_BAR; PG8_MMA(0, 0, At, B0); PG8_MMA(0, 1, At, B1); PG8_BAR; PG8_SCHED;
;             PG8_LDA(At, 1, 1); PG8_STAGE(PG8_SB(1, 0), b3, voffB); PG8_STAGE(PG8_SB(1, 1), b3 + hstep, voffB); PG8_STAGE(PG8_SA(1, 0), a3, voffA);
	s_add_i32 s48, 0, 0x18000
	s_add_i32 s49, 0, 0x1c000
	v_add_u32_e32 v156, s48, v161
	v_add_u32_e32 v165, s49, v161
	ds_read_b128 v[144:147], v156
	ds_read_b128 v[148:151], v156 offset:1024
	ds_read_b128 v[152:155], v156 offset:2048
	ds_read_b128 v[156:159], v156 offset:3072
	ds_read_b128 v[166:169], v165
	ds_read_b128 v[170:173], v165 offset:1024
	ds_read_b128 v[174:177], v165 offset:2048
	ds_read_b128 v[178:181], v165 offset:3072
	s_add_u32 s22, s22, 0x40000
	s_addc_u32 s23, s23, 0
	s_mov_b32 m0, s38
	v_lshl_add_u64 v[236:237], s[22:23], 0, v[130:131]
	ds_read_b128 v[182:185], v164 offset:32768
	ds_read_b128 v[186:189], v164 offset:33792
	ds_read_b128 v[190:193], v164 offset:34816
	ds_read_b128 v[194:197], v164 offset:35840
	ds_read_b128 v[198:201], v164 offset:36864
	ds_read_b128 v[202:205], v164 offset:37888
	ds_read_b128 v[224:227], v164 offset:38912
	ds_read_b128 v[228:231], v164 offset:39936
	global_load_lds_dwordx4 v[236:237], off
	v_lshl_add_u64 v[236:237], s[22:23], 0, v[132:133]
	s_mov_b32 m0, s39
	s_nop 0
	global_load_lds_dwordx4 v[236:237], off
	s_waitcnt vmcnt(8)
	s_waitcnt lgkmcnt(0)
	s_barrier
	s_setprio 1
	s_waitcnt lgkmcnt(0)
	v_mfma_f32_16x16x32_bf16 v[126:129], v[144:147], v[182:185], v[126:129]
	v_mfma_f32_16x16x32_bf16 v[122:125], v[152:155], v[182:185], v[122:125]
	v_mfma_f32_16x16x32_bf16 v[110:113], v[144:147], v[190:193], v[110:113]
	v_mfma_f32_16x16x32_bf16 v[106:109], v[152:155], v[190:193], v[106:109]
	v_mfma_f32_16x16x32_bf16 v[94:97], v[144:147], v[198:201], v[94:97]
	v_mfma_f32_16x16x32_bf16 v[90:93], v[152:155], v[198:201], v[90:93]
	v_mfma_f32_16x16x32_bf16 v[78:81], v[144:147], v[224:227], v[78:81]
	v_mfma_f32_16x16x32_bf16 v[74:77], v[152:155], v[224:227], v[74:77]
	v_mfma_f32_16x16x32_bf16 v[126:129], v[148:151], v[186:189], v[126:129]
	v_mfma_f32_16x16x32_bf16 v[122:125], v[156:159], v[186:189], v[122:125]
	v_mfma_f32_16x16x32_bf16 v[110:113], v[148:151], v[194:197], v[110:113]
	v_mfma_f32_16x16x32_bf16 v[106:109], v[156:159], v[194:197], v[106:109]
	v_mfma_f32_16x16x32_bf16 v[94:97], v[148:151], v[202:205], v[94:97]
	v_mfma_f32_16x16x32_bf16 v[90:93], v[156:159], v[202:205], v[90:93]
	v_mfma_f32_16x16x32_bf16 v[78:81], v[148:151], v[228:231], v[78:81]
	v_mfma_f32_16x16x32_bf16 v[74:77], v[156:159], v[228:231], v[74:77]
	s_setprio 0
	s_setprio 1
	v_mfma_f32_16x16x32_bf16 v[118:121], v[166:169], v[182:185], v[118:121]
	v_mfma_f32_16x16x32_bf16 v[114:117], v[174:177], v[182:185], v[114:117]
	v_mfma_f32_16x16x32_bf16 v[102:105], v[166:169], v[190:193], v[102:105]
	v_mfma_f32_16x16x32_bf16 v[98:101], v[174:177], v[190:193], v[98:101]
	v_mfma_f32_16x16x32_bf16 v[86:89], v[166:169], v[198:201], v[86:89]
	v_mfma_f32_16x16x32_bf16 v[82:85], v[174:177], v[198:201], v[82:85]
	v_mfma_f32_16x16x32_bf16 v[70:73], v[166:169], v[224:227], v[70:73]
	v_mfma_f32_16x16x32_bf16 v[66:69], v[174:177], v[224:227], v[66:69]
	v_mfma_f32_16x16x32_bf16 v[118:121], v[170:173], v[186:189], v[118:121]
	v_mfma_f32_16x16x32_bf16 v[114:117], v[178:181], v[186:189], v[114:117]
	v_mfma_f32_16x16x32_bf16 v[102:105], v[170:173], v[194:197], v[102:105]
	v_mfma_f32_16x16x32_bf16 v[98:101], v[178:181], v[194:197], v[98:101]
	v_mfma_f32_16x16x32_bf16 v[86:89], v[170:173], v[202:205], v[86:89]
	v_mfma_f32_16x16x32_bf16 v[82:85], v[178:181], v[202:205], v[82:85]
	v_mfma_f32_16x16x32_bf16 v[70:73], v[170:173], v[228:231], v[70:73]
	v_mfma_f32_16x16x32_bf16 v[66:69], v[178:181], v[228:231], v[66:69]
	s_setprio 0
	s_barrier
; #define PG8_STAGE(bufoff, gbase, voff) do { _Pragma("unroll") for (int _i = 0; _i < 2; ++_i) \
;         __builtin_amdgcn_global_load_lds((const unsigned*)((const char*)(gbase) + (voff)[_i]), (PG8_LAS unsigned*)(lds + (bufoff) + ldsw + _i * 8192), 16, 0, 0); } while (0)
; #define PG8_LDA(dst, b, h) do { _Pragma("unroll") for (int m = 0; m < 4; ++m) _Pragma("unroll") for (int k = 0; k < 2; ++k) dst[m][k] = *(const PG8_LAS bf16x8*)(lds + PG8_SA(b, h) + aoff + m * 2048 + k * 1024); } while (0)
; #define PG8_MMA(ai, bj, At, Bt) do { __builtin_amdgcn_s_setprio(1); _Pragma("unroll") for (int m = 0; m < 4; ++m) _Pragma("unroll") for (int n = 0; n < 2; ++n) _Pragma("unroll") for (int k = 0; k < 2; ++k) \
;         acc[ai][bj][m][n] = __builtin_amdgcn_mfma_f32_16x16x32_bf16(Bt[n][k], At[m][k], acc[ai][bj][m][n], 0, 0, 0); __builtin_amdgcn_s_setprio(0); } while (0)
; #define PG8_WAIT_V(n) asm volatile("s_waitcnt vmcnt(" #n ")" ::: "memory")
; #define PG8_WAIT_L(n) asm volatile("s_waitcnt lgkmcnt(" #n ")" ::: "memory")
; #define PG8_BAR __builtin_amdgcn_s_barrier()
; #define PG8_SCHED __builtin_amdgcn_sched_barrier(0)
; template <class Epi, class Sched, bool ALIGN_EPI = false, bool SP2 = false>
; __device__ __forceinline__ void gemm_phase(PG8_LAS unsigned char* lds, const Gemm g, const Sched& S, const Epi& E) {
;     ...
;             const bool last = (t == nt - 2);
;             const char* a1 = cA + (size_t)(t + 1) * kstep;
;             const char* a2 = last ? nA : cA + (size_t)(t + 2) * kstep; const char* b2 = last ? nB : cB + (size_t)(t + 2) * kstep;
;             const char* a3 = a2 + kstep; const char* b3 = b2 + kstep;
;     ...
;             PG8_LDA(At, 1, 1); PG8_STAGE(PG8_SB(1, 0), b3, voffB); PG8_STAGE(PG8_SB(1, 1), b3 + hstep, voffB); PG8_STAGE(PG8_SA(1, 0), a3, voffA);
;             PG8_WAIT_V(8); PG8_WAIT_L(0); PG8_BAR; PG8_MMA(1, 0, At, B0); PG8_MMA(1, 1, At, B1); PG8_BAR; PG8_SCHED;
	s_add_i32 s22, s48, s26
	v_lshl_add_u64 v[138:139], v[138:139], 0, s[86:87]
	s_mov_b32 m0, s22
	ds_read_b128 v[182:185], v164 offset:49152
	ds_read_b128 v[186:189], v164 offset:50176
	ds_read_b128 v[190:193], v164 offset:51200
	ds_read_b128 v[194:197], v164 offset:52224
	ds_read_b128 v[198:201], v164 offset:53248
	ds_read_b128 v[202:205], v164 offset:54272
	ds_read_b128 v[224:227], v164 offset:55296
	ds_read_b128 v[228:231], v164 offset:56320
	global_load_lds_dwordx4 v[138:139], off
	s_add_i32 m0, s22, 0x2000
	s_add_u32 s20, s20, 0x40080
	v_lshl_add_u64 v[138:139], v[140:141], 0, s[86:87]
	s_addc_u32 s21, s21, 0
	s_add_i32 s22, s49, s26
	global_load_lds_dwordx4 v[138:139], off
	v_lshl_add_u64 v[138:139], s[20:21], 0, v[0:1]
	s_mov_b32 m0, s22
	s_nop 0
	global_load_lds_dwordx4 v[138:139], off
	v_lshl_add_u64 v[138:139], s[20:21], 0, v[134:135]
	s_add_i32 m0, s22, 0x2000
	s_nop 0
	global_load_lds_dwordx4 v[138:139], off
	v_lshl_add_u64 v[138:139], v[232:233], 0, s[86:87]
	s_mov_b32 m0, s41
	s_nop 0
	global_load_lds_dwordx4 v[138:139], off
	v_lshl_add_u64 v[138:139], v[234:235], 0, s[86:87]
	s_mov_b32 m0, s42
	s_nop 0
	global_load_lds_dwordx4 v[138:139], off
	s_waitcnt vmcnt(8)
	s_waitcnt lgkmcnt(0)
	s_barrier
	s_setprio 1
	s_waitcnt lgkmcnt(0)
	v_mfma_f32_16x16x32_bf16 v[62:65], v[144:147], v[182:185], v[62:65]
	v_mfma_f32_16x16x32_bf16 v[58:61], v[152:155], v[182:185], v[58:61]
	v_mfma_f32_16x16x32_bf16 v[46:49], v[144:147], v[190:193], v[46:49]
	v_mfma_f32_16x16x32_bf16 v[42:45], v[152:155], v[190:193], v[42:45]
	v_mfma_f32_16x16x32_bf16 v[30:33], v[144:147], v[198:201], v[30:33]
	v_mfma_f32_16x16x32_bf16 v[26:29], v[152:155], v[198:201], v[26:29]
	v_mfma_f32_16x16x32_bf16 v[14:17], v[144:147], v[224:227], v[14:17]
	v_mfma_f32_16x16x32_bf16 v[10:13], v[152:155], v[224:227], v[10:13]
	v_mfma_f32_16x16x32_bf16 v[62:65], v[148:151], v[186:189], v[62:65]
	v_mfma_f32_16x16x32_bf16 v[58:61], v[156:159], v[186:189], v[58:61]
	v_mfma_f32_16x16x32_bf16 v[46:49], v[148:151], v[194:197], v[46:49]
	v_mfma_f32_16x16x32_bf16 v[42:45], v[156:159], v[194:197], v[42:45]
	v_mfma_f32_16x16x32_bf16 v[30:33], v[148:151], v[202:205], v[30:33]
	v_mfma_f32_16x16x32_bf16 v[26:29], v[156:159], v[202:205], v[26:29]
	v_mfma_f32_16x16x32_bf16 v[14:17], v[148:151], v[228:231], v[14:17]
	v_mfma_f32_16x16x32_bf16 v[10:13], v[156:159], v[228:231], v[10:13]
	s_setprio 0
	s_setprio 1
	v_mfma_f32_16x16x32_bf16 v[54:57], v[166:169], v[182:185], v[54:57]
	v_mfma_f32_16x16x32_bf16 v[50:53], v[174:177], v[182:185], v[50:53]
	v_mfma_f32_16x16x32_bf16 v[38:41], v[166:169], v[190:193], v[38:41]
	v_mfma_f32_16x16x32_bf16 v[34:37], v[174:177], v[190:193], v[34:37]
	v_mfma_f32_16x16x32_bf16 v[22:25], v[166:169], v[198:201], v[22:25]
	v_mfma_f32_16x16x32_bf16 v[18:21], v[174:177], v[198:201], v[18:21]
	v_mfma_f32_16x16x32_bf16 v[6:9], v[166:169], v[224:227], v[6:9]
	v_mfma_f32_16x16x32_bf16 v[2:5], v[174:177], v[224:227], v[2:5]
	v_mfma_f32_16x16x32_bf16 v[54:57], v[170:173], v[186:189], v[54:57]
	v_mfma_f32_16x16x32_bf16 v[50:53], v[178:181], v[186:189], v[50:53]
	v_mfma_f32_16x16x32_bf16 v[38:41], v[170:173], v[194:197], v[38:41]
	v_mfma_f32_16x16x32_bf16 v[34:37], v[178:181], v[194:197], v[34:37]
	v_mfma_f32_16x16x32_bf16 v[22:25], v[170:173], v[202:205], v[22:25]
	v_mfma_f32_16x16x32_bf16 v[18:21], v[178:181], v[202:205], v[18:21]
	v_mfma_f32_16x16x32_bf16 v[6:9], v[170:173], v[228:231], v[6:9]
	v_mfma_f32_16x16x32_bf16 v[2:5], v[178:181], v[228:231], v[2:5]
	s_setprio 0
	s_add_i32 s47, s47, 2
	s_add_u32 s8, s8, 0x100
	s_addc_u32 s9, s9, 0
	s_add_u32 s45, s45, 0x100
	s_addc_u32 s46, s46, 0
	s_add_u32 s20, s8, 0xfffc0080
	s_addc_u32 s21, s9, -1
	s_add_i32 s48, 0, 0x10000
	s_cmp_eq_u32 s47, 12
	s_cselect_b32 s23, s5, s21
	s_cselect_b32 s22, s7, s20
	v_add_u32_e32 v138, s48, v161
	s_cselect_b32 s21, s13, s46
	s_cselect_b32 s20, s15, s45
	s_add_i32 s50, 0, 0x14000
	s_cmp_gt_u32 s47, 13
	s_barrier
	s_cbranch_scc0 .LBB0_492

; #define PG8_STAGE(bufoff, gbase, voff) do { _Pragma("unroll") for (int _i = 0; _i < 2; ++_i) \
;         __builtin_amdgcn_global_load_lds((const unsigned*)((const char*)(gbase) + (voff)[_i]), (PG8_LAS unsigned*)(lds + (bufoff) + ldsw + _i * 8192), 16, 0, 0); } while (0)
; #define PG8_LDA(dst, b, h) do { _Pragma("unroll") for (int m = 0; m < 4; ++m) _Pragma("unroll") for (int k = 0; k < 2; ++k) dst[m][k] = *(const PG8_LAS bf16x8*)(lds + PG8_SA(b, h) + aoff + m * 2048 + k * 1024); } while (0)
; #define PG8_LDB(dst, b, h) do { _Pragma("unroll") for (int n = 0; n < 2; ++n) _Pragma("unroll") for (int k = 0; k < 2; ++k) dst[n][k] = *(const PG8_LAS bf16x8*)(lds + PG8_SB(b, h) + boff + n * 2048 + k * 1024); } while (0)
; #define PG8_SCHED __builtin_amdgcn_sched_barrier(0)
; template <class Epi, class Sched, bool ALIGN_EPI = false, bool SP2 = false>
; __device__ __forceinline__ void gemm_phase(PG8_LAS unsigned char* lds, const Gemm g, const Sched& S, const Epi& E) {
;     ...
;         const bool has_next = S.next(ui + 1, nxt);
;         const char* nA = has_next ? (const char*)g.A + (size_t)nxt.pm * tstep : cA; const char* nB = has_next ? (const char*)g.Bt + (size_t)nxt.pn * tstep : cB;
;         for (int t = 0; t < nt; t += 2) {
;             const bool last = (t == nt - 2);
;             const char* a1 = cA + (size_t)(t + 1) * kstep;
;             const char* a2 = last ? nA : cA + (size_t)(t + 2) * kstep; const char* b2 = last ? nB : cB + (size_t)(t + 2) * kstep;
;             const char* a3 = a2 + kstep; const char* b3 = b2 + kstep;
;             if (last && has_next) S.a_ready(nxt);
;             if constexpr (SP2) {
;             PG8_LDB(B0, 0, 0); PG8_LDB(B1, 0, 1); PG8_SCHED; PG8_LDA(At, 0, 0); PG8_STAGE(PG8_SA(1, 1), a1 + hstep, voffA);
;     ...
; #pragma unroll
;         for (int a = 0; a < 2; ++a)
; #pragma unroll
;             for (int b = 0; b < 2; ++b)
; #pragma unroll
;                 for (int m = 0; m < 4; ++m)
; #pragma unroll
;                     for (int n = 0; n < 2; ++n) acc[a][b][m][n] = (f32x4){0.f, 0.f, 0.f, 0.f};
;         cur = nxt; cA = nA; cB = nB; ++ui;
.LBB0_890:
	s_ashr_i32 s9, s8, 31
	s_lshl_b64 s[10:11], s[8:9], 18
	s_add_u32 s10, s58, s10
	s_addc_u32 s11, s59, s11
	s_and_b64 s[12:13], s[2:3], exec
	s_cselect_b32 s9, s11, s17
	s_cselect_b32 s41, s10, s16
	s_ashr_i32 s7, s6, 31
	s_lshl_b64 s[12:13], s[6:7], 18
	s_add_u32 s12, s24, s12
	s_addc_u32 s13, s25, s13
	s_and_b64 s[20:21], s[2:3], exec
	s_cselect_b32 s7, s13, s19
	s_cselect_b32 s42, s12, s18
	s_add_u32 s16, s16, 0x20080
	s_addc_u32 s17, s17, 0
	s_add_u32 s43, s18, 0x100
	v_mov_b32_e32 v2, 0
	s_addc_u32 s44, s19, 0
	s_mov_b32 s45, -2
	v_mov_b32_e32 v3, v2
	v_mov_b32_e32 v4, v2
	v_mov_b32_e32 v5, v2
	v_mov_b32_e32 v6, v2
	v_mov_b32_e32 v7, v2
	v_mov_b32_e32 v8, v2
	v_mov_b32_e32 v9, v2
	v_mov_b32_e32 v18, v2
	v_mov_b32_e32 v19, v2
	v_mov_b32_e32 v20, v2
	v_mov_b32_e32 v21, v2
	v_mov_b32_e32 v22, v2
	v_mov_b32_e32 v23, v2
	v_mov_b32_e32 v24, v2
	v_mov_b32_e32 v25, v2
	v_mov_b32_e32 v34, v2
	v_mov_b32_e32 v35, v2
	v_mov_b32_e32 v36, v2
	v_mov_b32_e32 v37, v2
	v_mov_b32_e32 v38, v2
	v_mov_b32_e32 v39, v2
	v_mov_b32_e32 v40, v2
	v_mov_b32_e32 v41, v2
	v_mov_b32_e32 v50, v2
	v_mov_b32_e32 v51, v2
	v_mov_b32_e32 v52, v2
	v_mov_b32_e32 v53, v2
	v_mov_b32_e32 v54, v2
	v_mov_b32_e32 v55, v2
	v_mov_b32_e32 v56, v2
	v_mov_b32_e32 v57, v2
	v_mov_b32_e32 v10, v2
	v_mov_b32_e32 v11, v2
	v_mov_b32_e32 v12, v2
	v_mov_b32_e32 v13, v2
	v_mov_b32_e32 v14, v2
	v_mov_b32_e32 v15, v2
	v_mov_b32_e32 v16, v2
	v_mov_b32_e32 v17, v2
	v_mov_b32_e32 v26, v2
	v_mov_b32_e32 v27, v2
	v_mov_b32_e32 v28, v2
	v_mov_b32_e32 v29, v2
	v_mov_b32_e32 v30, v2
	v_mov_b32_e32 v31, v2
	v_mov_b32_e32 v32, v2
	v_mov_b32_e32 v33, v2
	v_mov_b32_e32 v42, v2
	v_mov_b32_e32 v43, v2
	v_mov_b32_e32 v44, v2
	v_mov_b32_e32 v45, v2
	v_mov_b32_e32 v46, v2
	v_mov_b32_e32 v47, v2
	v_mov_b32_e32 v48, v2
	v_mov_b32_e32 v49, v2
	v_mov_b32_e32 v58, v2
	v_mov_b32_e32 v59, v2
	v_mov_b32_e32 v60, v2
	v_mov_b32_e32 v61, v2
	v_mov_b32_e32 v62, v2
	v_mov_b32_e32 v63, v2
	v_mov_b32_e32 v64, v2
	v_mov_b32_e32 v65, v2
	v_mov_b32_e32 v66, v2
	v_mov_b32_e32 v67, v2
	v_mov_b32_e32 v68, v2
	v_mov_b32_e32 v69, v2
	v_mov_b32_e32 v70, v2
	v_mov_b32_e32 v71, v2
	v_mov_b32_e32 v72, v2
	v_mov_b32_e32 v73, v2
	v_mov_b32_e32 v82, v2
	v_mov_b32_e32 v83, v2
	v_mov_b32_e32 v84, v2
	v_mov_b32_e32 v85, v2
	v_mov_b32_e32 v86, v2
	v_mov_b32_e32 v87, v2
	v_mov_b32_e32 v88, v2
	v_mov_b32_e32 v89, v2
	v_mov_b32_e32 v98, v2
	v_mov_b32_e32 v99, v2
	v_mov_b32_e32 v100, v2
	v_mov_b32_e32 v101, v2
	v_mov_b32_e32 v102, v2
	v_mov_b32_e32 v103, v2
	v_mov_b32_e32 v104, v2
	v_mov_b32_e32 v105, v2
	v_mov_b32_e32 v114, v2
	v_mov_b32_e32 v115, v2
	v_mov_b32_e32 v116, v2
	v_mov_b32_e32 v117, v2
	v_mov_b32_e32 v118, v2
	v_mov_b32_e32 v119, v2
	v_mov_b32_e32 v120, v2
	v_mov_b32_e32 v121, v2
	v_mov_b32_e32 v74, v2
	v_mov_b32_e32 v75, v2
	v_mov_b32_e32 v76, v2
	v_mov_b32_e32 v77, v2
	v_mov_b32_e32 v78, v2
	v_mov_b32_e32 v79, v2
	v_mov_b32_e32 v80, v2
	v_mov_b32_e32 v81, v2
	v_mov_b32_e32 v90, v2
	v_mov_b32_e32 v91, v2
	v_mov_b32_e32 v92, v2
	v_mov_b32_e32 v93, v2
	v_mov_b32_e32 v94, v2
	v_mov_b32_e32 v95, v2
	v_mov_b32_e32 v96, v2
	v_mov_b32_e32 v97, v2
	v_mov_b32_e32 v106, v2
	v_mov_b32_e32 v107, v2
	v_mov_b32_e32 v108, v2
	v_mov_b32_e32 v109, v2
	v_mov_b32_e32 v110, v2
	v_mov_b32_e32 v111, v2
	v_mov_b32_e32 v112, v2
	v_mov_b32_e32 v113, v2
	v_mov_b32_e32 v122, v2
	v_mov_b32_e32 v123, v2
	v_mov_b32_e32 v124, v2
	v_mov_b32_e32 v125, v2
	v_mov_b32_e32 v126, v2
	v_mov_b32_e32 v127, v2
	v_mov_b32_e32 v128, v2
	v_mov_b32_e32 v129, v2
	s_add_u32 s18, s16, 0xfffe0080
	s_addc_u32 s19, s17, -1
	s_add_i32 s46, 0, 0x10000
	s_cmp_eq_u32 s45, 4
	s_cselect_b32 s21, s9, s19
	s_cselect_b32 s20, s41, s18
	v_add_u32_e32 v148, s46, v151
	s_cselect_b32 s19, s7, s44
	s_cselect_b32 s18, s42, s43
	s_add_i32 s48, 0, 0x14000
.LBB0_891:
	ds_read_b128 v[138:141], v148
	ds_read_b128 v[144:147], v148 offset:1024
	ds_read_b128 v[154:157], v148 offset:2048
	ds_read_b128 v[158:161], v148 offset:3072
	v_add_u32_e32 v148, s48, v151
	ds_read_b128 v[162:165], v148
	ds_read_b128 v[166:169], v148 offset:1024
	ds_read_b128 v[170:173], v148 offset:2048
	ds_read_b128 v[174:177], v148 offset:3072
	v_lshl_add_u64 v[148:149], s[16:17], 0, v[136:137]
	s_add_i32 m0, s27, 0xc000
	ds_read_b128 v[178:181], v153
	ds_read_b128 v[182:185], v153 offset:1024
	ds_read_b128 v[186:189], v153 offset:2048
	ds_read_b128 v[190:193], v153 offset:3072
	ds_read_b128 v[194:197], v153 offset:4096
	ds_read_b128 v[198:201], v153 offset:5120
	ds_read_b128 v[202:205], v153 offset:6144
	ds_read_b128 v[224:227], v153 offset:7168
	global_load_lds_dwordx4 v[148:149], off
	v_lshl_add_u64 v[148:149], s[16:17], 0, v[142:143]
	s_add_i32 m0, s27, 0xe000
	s_nop 0
	global_load_lds_dwordx4 v[148:149], off
	s_waitcnt vmcnt(8)
	s_waitcnt lgkmcnt(0)
	s_barrier
; #define PG8_STAGE(bufoff, gbase, voff) do { _Pragma("unroll") for (int _i = 0; _i < 2; ++_i) \
;         __builtin_amdgcn_global_load_lds((const unsigned*)((const char*)(gbase) + (voff)[_i]), (PG8_LAS unsigned*)(lds + (bufoff) + ldsw + _i * 8192), 16, 0, 0); } while (0)
; #define PG8_LDA(dst, b, h) do { _Pragma("unroll") for (int m = 0; m < 4; ++m) _Pragma("unroll") for (int k = 0; k < 2; ++k) dst[m][k] = *(const PG8_LAS bf16x8*)(lds + PG8_SA(b, h) + aoff + m * 2048 + k * 1024); } while (0)
; #define PG8_MMA(ai, bj, At, Bt) do { __builtin_amdgcn_s_setprio(1); _Pragma("unroll") for (int m = 0; m < 4; ++m) _Pragma("unroll") for (int n = 0; n < 2; ++n) _Pragma("unroll") for (int k = 0; k < 2; ++k) \
;         acc[ai][bj][m][n] = __builtin_amdgcn_mfma_f32_16x16x32_bf16(Bt[n][k], At[m][k], acc[ai][bj][m][n], 0, 0, 0); __builtin_amdgcn_s_setprio(0); } while (0)
; #define PG8_WAIT_V(n) asm volatile("s_waitcnt vmcnt(" #n ")" ::: "memory")
; #define PG8_WAIT_L(n) asm volatile("s_waitcnt lgkmcnt(" #n ")" ::: "memory")
; #define PG8_BAR __builtin_amdgcn_s_barrier()
; #define PG8_SCHED __builtin_amdgcn_sched_barrier(0)
; template <class Epi, class Sched, bool ALIGN_EPI = false, bool SP2 = false>
; __device__ __forceinline__ void gemm_phase(PG8_LAS unsigned char* lds, const Gemm g, const Sched& S, const Epi& E) {
;     ...
;             PG8_WAIT_V(8); PG8_WAIT_L(0); PG8_BAR; PG8_MMA(0, 0, At, B0); PG8_MMA(0, 1, At, B1); PG8_BAR; PG8_SCHED;
;             PG8_LDA(At, 0, 1); PG8_STAGE(PG8_SB(0, 0), b2, voffB); PG8_STAGE(PG8_SB(0, 1), b2 + hstep, voffB); PG8_STAGE(PG8_SA(0, 0), a2, voffA);
;             PG8_WAIT_V(8); PG8_WAIT_L(0); PG8_BAR; PG8_MMA(1, 0, At, B0); PG8_MMA(1, 1, At, B1); PG8_BAR; PG8_SCHED;
	s_setprio 1
	s_waitcnt lgkmcnt(0)
	v_mfma_f32_16x16x32_bf16 v[126:129], v[138:141], v[178:181], v[126:129]
	v_mfma_f32_16x16x32_bf16 v[122:125], v[154:157], v[178:181], v[122:125]
	v_mfma_f32_16x16x32_bf16 v[110:113], v[138:141], v[186:189], v[110:113]
	v_mfma_f32_16x16x32_bf16 v[106:109], v[154:157], v[186:189], v[106:109]
	v_mfma_f32_16x16x32_bf16 v[94:97], v[138:141], v[194:197], v[94:97]
	v_mfma_f32_16x16x32_bf16 v[90:93], v[154:157], v[194:197], v[90:93]
	v_mfma_f32_16x16x32_bf16 v[78:81], v[138:141], v[202:205], v[78:81]
	v_mfma_f32_16x16x32_bf16 v[74:77], v[154:157], v[202:205], v[74:77]
	v_mfma_f32_16x16x32_bf16 v[126:129], v[144:147], v[182:185], v[126:129]
	v_mfma_f32_16x16x32_bf16 v[122:125], v[158:161], v[182:185], v[122:125]
	v_mfma_f32_16x16x32_bf16 v[110:113], v[144:147], v[190:193], v[110:113]
	v_mfma_f32_16x16x32_bf16 v[106:109], v[158:161], v[190:193], v[106:109]
	v_mfma_f32_16x16x32_bf16 v[94:97], v[144:147], v[198:201], v[94:97]
	v_mfma_f32_16x16x32_bf16 v[90:93], v[158:161], v[198:201], v[90:93]
	v_mfma_f32_16x16x32_bf16 v[78:81], v[144:147], v[224:227], v[78:81]
	v_mfma_f32_16x16x32_bf16 v[74:77], v[158:161], v[224:227], v[74:77]
	s_setprio 0
	s_setprio 1
	v_mfma_f32_16x16x32_bf16 v[118:121], v[162:165], v[178:181], v[118:121]
	v_mfma_f32_16x16x32_bf16 v[114:117], v[170:173], v[178:181], v[114:117]
	v_mfma_f32_16x16x32_bf16 v[102:105], v[162:165], v[186:189], v[102:105]
	v_mfma_f32_16x16x32_bf16 v[98:101], v[170:173], v[186:189], v[98:101]
	v_mfma_f32_16x16x32_bf16 v[86:89], v[162:165], v[194:197], v[86:89]
	v_mfma_f32_16x16x32_bf16 v[82:85], v[170:173], v[194:197], v[82:85]
	v_mfma_f32_16x16x32_bf16 v[70:73], v[162:165], v[202:205], v[70:73]
	v_mfma_f32_16x16x32_bf16 v[66:69], v[170:173], v[202:205], v[66:69]
	v_mfma_f32_16x16x32_bf16 v[118:121], v[166:169], v[182:185], v[118:121]
	v_mfma_f32_16x16x32_bf16 v[114:117], v[174:177], v[182:185], v[114:117]
	v_mfma_f32_16x16x32_bf16 v[102:105], v[166:169], v[190:193], v[102:105]
	v_mfma_f32_16x16x32_bf16 v[98:101], v[174:177], v[190:193], v[98:101]
	v_mfma_f32_16x16x32_bf16 v[86:89], v[166:169], v[198:201], v[86:89]
	v_mfma_f32_16x16x32_bf16 v[82:85], v[174:177], v[198:201], v[82:85]
	v_mfma_f32_16x16x32_bf16 v[70:73], v[166:169], v[224:227], v[70:73]
	v_mfma_f32_16x16x32_bf16 v[66:69], v[174:177], v[224:227], v[66:69]
	s_setprio 0
	s_barrier
	s_add_i32 s46, s46, s26
	v_lshl_add_u64 v[148:149], s[18:19], 0, v[0:1]
	s_mov_b32 m0, s46
	ds_read_b128 v[178:181], v153 offset:16384
	ds_read_b128 v[182:185], v153 offset:17408
	ds_read_b128 v[186:189], v153 offset:18432
	ds_read_b128 v[190:193], v153 offset:19456
	ds_read_b128 v[194:197], v153 offset:20480
	ds_read_b128 v[198:201], v153 offset:21504
	ds_read_b128 v[202:205], v153 offset:22528
	ds_read_b128 v[224:227], v153 offset:23552
	global_load_lds_dwordx4 v[148:149], off
	s_add_i32 m0, s46, 0x2000
	s_add_u32 s46, s18, 0x20000
	v_lshl_add_u64 v[228:229], s[18:19], 0, v[134:135]
	s_addc_u32 s47, s19, 0
	s_add_i32 s48, s48, s26
	global_load_lds_dwordx4 v[228:229], off
	v_lshl_add_u64 v[230:231], s[46:47], 0, v[0:1]
	s_mov_b32 m0, s48
	v_lshl_add_u64 v[232:233], s[20:21], 0, v[132:133]
	global_load_lds_dwordx4 v[230:231], off
	v_lshl_add_u64 v[230:231], s[46:47], 0, v[134:135]
	s_add_i32 m0, s48, 0x2000
	s_nop 0
	global_load_lds_dwordx4 v[230:231], off
	v_lshl_add_u64 v[230:231], s[20:21], 0, v[130:131]
	s_mov_b32 m0, s27
	s_nop 0
	global_load_lds_dwordx4 v[230:231], off
	s_mov_b32 m0, s28
	s_nop 0
	global_load_lds_dwordx4 v[232:233], off
	s_waitcnt vmcnt(8)
	s_waitcnt lgkmcnt(0)
	s_barrier
	s_setprio 1
	s_waitcnt lgkmcnt(0)
	v_mfma_f32_16x16x32_bf16 v[62:65], v[138:141], v[178:181], v[62:65]
	v_mfma_f32_16x16x32_bf16 v[58:61], v[154:157], v[178:181], v[58:61]
	v_mfma_f32_16x16x32_bf16 v[46:49], v[138:141], v[186:189], v[46:49]
	v_mfma_f32_16x16x32_bf16 v[42:45], v[154:157], v[186:189], v[42:45]
	v_mfma_f32_16x16x32_bf16 v[30:33], v[138:141], v[194:197], v[30:33]
	v_mfma_f32_16x16x32_bf16 v[26:29], v[154:157], v[194:197], v[26:29]
	v_mfma_f32_16x16x32_bf16 v[14:17], v[138:141], v[202:205], v[14:17]
	v_mfma_f32_16x16x32_bf16 v[10:13], v[154:157], v[202:205], v[10:13]
	v_mfma_f32_16x16x32_bf16 v[62:65], v[144:147], v[182:185], v[62:65]
	v_mfma_f32_16x16x32_bf16 v[58:61], v[158:161], v[182:185], v[58:61]
	v_mfma_f32_16x16x32_bf16 v[46:49], v[144:147], v[190:193], v[46:49]
	v_mfma_f32_16x16x32_bf16 v[42:45], v[158:161], v[190:193], v[42:45]
	v_mfma_f32_16x16x32_bf16 v[30:33], v[144:147], v[198:201], v[30:33]
	v_mfma_f32_16x16x32_bf16 v[26:29], v[158:161], v[198:201], v[26:29]
	v_mfma_f32_16x16x32_bf16 v[14:17], v[144:147], v[224:227], v[14:17]
	v_mfma_f32_16x16x32_bf16 v[10:13], v[158:161], v[224:227], v[10:13]
	s_setprio 0
	s_setprio 1
	v_mfma_f32_16x16x32_bf16 v[54:57], v[162:165], v[178:181], v[54:57]
	v_mfma_f32_16x16x32_bf16 v[50:53], v[170:173], v[178:181], v[50:53]
	v_mfma_f32_16x16x32_bf16 v[38:41], v[162:165], v[186:189], v[38:41]
	v_mfma_f32_16x16x32_bf16 v[34:37], v[170:173], v[186:189], v[34:37]
	v_mfma_f32_16x16x32_bf16 v[22:25], v[162:165], v[194:197], v[22:25]
	v_mfma_f32_16x16x32_bf16 v[18:21], v[170:173], v[194:197], v[18:21]
	v_mfma_f32_16x16x32_bf16 v[6:9], v[162:165], v[202:205], v[6:9]
	v_mfma_f32_16x16x32_bf16 v[2:5], v[170:173], v[202:205], v[2:5]
	v_mfma_f32_16x16x32_bf16 v[54:57], v[166:169], v[182:185], v[54:57]
	v_mfma_f32_16x16x32_bf16 v[50:53], v[174:177], v[182:185], v[50:53]
	v_mfma_f32_16x16x32_bf16 v[38:41], v[166:169], v[190:193], v[38:41]
	v_mfma_f32_16x16x32_bf16 v[34:37], v[174:177], v[190:193], v[34:37]
	v_mfma_f32_16x16x32_bf16 v[22:25], v[166:169], v[198:201], v[22:25]
	v_mfma_f32_16x16x32_bf16 v[18:21], v[174:177], v[198:201], v[18:21]
	v_mfma_f32_16x16x32_bf16 v[6:9], v[166:169], v[224:227], v[6:9]
	v_mfma_f32_16x16x32_bf16 v[2:5], v[174:177], v[224:227], v[2:5]
	s_setprio 0
	s_barrier
; #define PG8_STAGE(bufoff, gbase, voff) do { _Pragma("unroll") for (int _i = 0; _i < 2; ++_i) \
;         __builtin_amdgcn_global_load_lds((const unsigned*)((const char*)(gbase) + (voff)[_i]), (PG8_LAS unsigned*)(lds + (bufoff) + ldsw + _i * 8192), 16, 0, 0); } while (0)
; #define PG8_LDA(dst, b, h) do { _Pragma("unroll") for (int m = 0; m < 4; ++m) _Pragma("unroll") for (int k = 0; k < 2; ++k) dst[m][k] = *(const PG8_LAS bf16x8*)(lds + PG8_SA(b, h) + aoff + m * 2048 + k * 1024); } while (0)
; #define PG8_LDB(dst, b, h) do { _Pragma("unroll") for (int n = 0; n < 2; ++n) _Pragma("unroll") for (int k = 0; k < 2; ++k) dst[n][k] = *(const PG8_LAS bf16x8*)(lds + PG8_SB(b, h) + boff + n * 2048 + k * 1024); } while (0)
; #define PG8_MMA(ai, bj, At, Bt) do { __builtin_amdgcn_s_setprio(1); _Pragma("unroll") for (int m = 0; m < 4; ++m) _Pragma("unroll") for (int n = 0; n < 2; ++n) _Pragma("unroll") for (int k = 0; k < 2; ++k) \
;         acc[ai][bj][m][n] = __builtin_amdgcn_mfma_f32_16x16x32_bf16(Bt[n][k], At[m][k], acc[ai][bj][m][n], 0, 0, 0); __builtin_amdgcn_s_setprio(0); } while (0)
; #define PG8_WAIT_V(n) asm volatile("s_waitcnt vmcnt(" #n ")" ::: "memory")
; #define PG8_WAIT_L(n) asm volatile("s_waitcnt lgkmcnt(" #n ")" ::: "memory")
; #define PG8_BAR __builtin_amdgcn_s_barrier()
; #define PG8_SCHED __builtin_amdgcn_sched_barrier(0)
; template <class Epi, class Sched, bool ALIGN_EPI = false, bool SP2 = false>
; __device__ __forceinline__ void gemm_phase(PG8_LAS unsigned char* lds, const Gemm g, const Sched& S, const Epi& E) {
;     ...
;             PG8_LDB(B0, 1, 0); PG8_LDB(B1, 1, 1); PG8_SCHED; PG8_LDA(At, 1, 0); PG8_STAGE(PG8_SA(0, 1), a2 + hstep, voffA);
;             PG8_WAIT_V(8); PG8_WAIT_L(0); PG8_BAR; PG8_MMA(0, 0, At, B0); PG8_MMA(0, 1, At, B1); PG8_BAR; PG8_SCHED;
;             PG8_LDA(At, 1, 1); PG8_STAGE(PG8_SB(1, 0), b3, voffB); PG8_STAGE(PG8_SB(1, 1), b3 + hstep, voffB); PG8_STAGE(PG8_SA(1, 0), a3, voffA);
	s_add_i32 s46, 0, 0x18000
	s_add_i32 s47, 0, 0x1c000
	v_add_u32_e32 v158, s46, v151
	v_add_u32_e32 v174, s47, v151
	ds_read_b128 v[138:141], v158
	ds_read_b128 v[144:147], v158 offset:1024
	ds_read_b128 v[154:157], v158 offset:2048
	ds_read_b128 v[158:161], v158 offset:3072
	ds_read_b128 v[162:165], v174
	ds_read_b128 v[166:169], v174 offset:1024
	ds_read_b128 v[170:173], v174 offset:2048
	ds_read_b128 v[174:177], v174 offset:3072
	s_add_u32 s20, s20, 0x20000
	s_addc_u32 s21, s21, 0
	s_mov_b32 m0, s29
	v_lshl_add_u64 v[234:235], s[20:21], 0, v[130:131]
	ds_read_b128 v[178:181], v153 offset:32768
	ds_read_b128 v[182:185], v153 offset:33792
	ds_read_b128 v[186:189], v153 offset:34816
	ds_read_b128 v[190:193], v153 offset:35840
	ds_read_b128 v[194:197], v153 offset:36864
	ds_read_b128 v[198:201], v153 offset:37888
	ds_read_b128 v[202:205], v153 offset:38912
	ds_read_b128 v[224:227], v153 offset:39936
	global_load_lds_dwordx4 v[234:235], off
	v_lshl_add_u64 v[234:235], s[20:21], 0, v[132:133]
	s_mov_b32 m0, s30
	s_nop 0
	global_load_lds_dwordx4 v[234:235], off
	s_waitcnt vmcnt(8)
	s_waitcnt lgkmcnt(0)
	s_barrier
	s_setprio 1
	s_waitcnt lgkmcnt(0)
	v_mfma_f32_16x16x32_bf16 v[126:129], v[138:141], v[178:181], v[126:129]
	v_mfma_f32_16x16x32_bf16 v[122:125], v[154:157], v[178:181], v[122:125]
	v_mfma_f32_16x16x32_bf16 v[110:113], v[138:141], v[186:189], v[110:113]
	v_mfma_f32_16x16x32_bf16 v[106:109], v[154:157], v[186:189], v[106:109]
	v_mfma_f32_16x16x32_bf16 v[94:97], v[138:141], v[194:197], v[94:97]
	v_mfma_f32_16x16x32_bf16 v[90:93], v[154:157], v[194:197], v[90:93]
	v_mfma_f32_16x16x32_bf16 v[78:81], v[138:141], v[202:205], v[78:81]
	v_mfma_f32_16x16x32_bf16 v[74:77], v[154:157], v[202:205], v[74:77]
	v_mfma_f32_16x16x32_bf16 v[126:129], v[144:147], v[182:185], v[126:129]
	v_mfma_f32_16x16x32_bf16 v[122:125], v[158:161], v[182:185], v[122:125]
	v_mfma_f32_16x16x32_bf16 v[110:113], v[144:147], v[190:193], v[110:113]
	v_mfma_f32_16x16x32_bf16 v[106:109], v[158:161], v[190:193], v[106:109]
	v_mfma_f32_16x16x32_bf16 v[94:97], v[144:147], v[198:201], v[94:97]
	v_mfma_f32_16x16x32_bf16 v[90:93], v[158:161], v[198:201], v[90:93]
	v_mfma_f32_16x16x32_bf16 v[78:81], v[144:147], v[224:227], v[78:81]
	v_mfma_f32_16x16x32_bf16 v[74:77], v[158:161], v[224:227], v[74:77]
	s_setprio 0
	s_setprio 1
	v_mfma_f32_16x16x32_bf16 v[118:121], v[162:165], v[178:181], v[118:121]
	v_mfma_f32_16x16x32_bf16 v[114:117], v[170:173], v[178:181], v[114:117]
	v_mfma_f32_16x16x32_bf16 v[102:105], v[162:165], v[186:189], v[102:105]
	v_mfma_f32_16x16x32_bf16 v[98:101], v[170:173], v[186:189], v[98:101]
	v_mfma_f32_16x16x32_bf16 v[86:89], v[162:165], v[194:197], v[86:89]
	v_mfma_f32_16x16x32_bf16 v[82:85], v[170:173], v[194:197], v[82:85]
	v_mfma_f32_16x16x32_bf16 v[70:73], v[162:165], v[202:205], v[70:73]
	v_mfma_f32_16x16x32_bf16 v[66:69], v[170:173], v[202:205], v[66:69]
	v_mfma_f32_16x16x32_bf16 v[118:121], v[166:169], v[182:185], v[118:121]
	v_mfma_f32_16x16x32_bf16 v[114:117], v[174:177], v[182:185], v[114:117]
	v_mfma_f32_16x16x32_bf16 v[102:105], v[166:169], v[190:193], v[102:105]
	v_mfma_f32_16x16x32_bf16 v[98:101], v[174:177], v[190:193], v[98:101]
	v_mfma_f32_16x16x32_bf16 v[86:89], v[166:169], v[198:201], v[86:89]
	v_mfma_f32_16x16x32_bf16 v[82:85], v[174:177], v[198:201], v[82:85]
	v_mfma_f32_16x16x32_bf16 v[70:73], v[166:169], v[224:227], v[70:73]
	v_mfma_f32_16x16x32_bf16 v[66:69], v[174:177], v[224:227], v[66:69]
	s_setprio 0
	s_barrier
	s_add_i32 s20, s46, s26
	v_lshl_add_u64 v[148:149], v[148:149], 0, s[86:87]
	s_mov_b32 m0, s20
	ds_read_b128 v[178:181], v153 offset:49152
	ds_read_b128 v[182:185], v153 offset:50176
	ds_read_b128 v[186:189], v153 offset:51200
	ds_read_b128 v[190:193], v153 offset:52224
	ds_read_b128 v[194:197], v153 offset:53248
	ds_read_b128 v[198:201], v153 offset:54272
	ds_read_b128 v[202:205], v153 offset:55296
	ds_read_b128 v[224:227], v153 offset:56320
	global_load_lds_dwordx4 v[148:149], off
	s_add_i32 m0, s20, 0x2000
	s_add_u32 s18, s18, 0x20080
	v_lshl_add_u64 v[148:149], v[228:229], 0, s[86:87]
	s_addc_u32 s19, s19, 0
	s_add_i32 s20, s47, s26
	global_load_lds_dwordx4 v[148:149], off
	v_lshl_add_u64 v[148:149], s[18:19], 0, v[0:1]
	s_mov_b32 m0, s20
	s_nop 0
	global_load_lds_dwordx4 v[148:149], off
	v_lshl_add_u64 v[148:149], s[18:19], 0, v[134:135]
	s_add_i32 m0, s20, 0x2000
	s_nop 0
	global_load_lds_dwordx4 v[148:149], off
	v_lshl_add_u64 v[148:149], v[230:231], 0, s[86:87]
	s_mov_b32 m0, s31
	s_nop 0
	global_load_lds_dwordx4 v[148:149], off
	v_lshl_add_u64 v[148:149], v[232:233], 0, s[86:87]
	s_mov_b32 m0, s38
	s_nop 0
	global_load_lds_dwordx4 v[148:149], off
	s_waitcnt vmcnt(8)
	s_waitcnt lgkmcnt(0)
	s_barrier
; #define PG8_BAR __builtin_amdgcn_s_barrier()
; template <class Epi, class Sched, bool ALIGN_EPI = false, bool SP2 = false>
; __device__ __forceinline__ void gemm_phase(PG8_LAS unsigned char* lds, const Gemm g, const Sched& S, const Epi& E) {
;     ...
;             PG8_WAIT_V(8); PG8_WAIT_L(0); PG8_BAR; PG8_MMA(1, 0, At, B0); PG8_MMA(1, 1, At, B1); PG8_BAR; PG8_SCHED;
;             } else {
;             PG8_LDB(B0, 0, 0); PG8_SCHED; PG8_LDA(At, 0, 0); PG8_STAGE(PG8_SA(1, 1), a1 + hstep, voffA);
;             PG8_WAIT_L(8); PG8_BAR; PG8_WAIT_L(0); PG8_MMA(0, 0, At, B0); PG8_BAR; PG8_SCHED;
;             PG8_LDB(B1, 0, 1); PG8_STAGE(PG8_SB(0, 0), b2, voffB);
;             PG8_BAR; PG8_WAIT_L(0); PG8_MMA(0, 1, At, B1); PG8_BAR;
;             PG8_LDA(At, 0, 1); PG8_STAGE(PG8_SA(0, 0), a2, voffA);
;             PG8_BAR; PG8_WAIT_L(0); PG8_MMA(1, 0, At, B0); PG8_BAR; PG8_SCHED;
;             PG8_STAGE(PG8_SB(0, 1), b2 + hstep, voffB);
;             PG8_WAIT_V(6); PG8_BAR; PG8_MMA(1, 1, At, B1); PG8_BAR;
;             PG8_LDB(B0, 1, 0); PG8_SCHED; PG8_LDA(At, 1, 0); PG8_STAGE(PG8_SA(0, 1), a2 + hstep, voffA);
;             PG8_WAIT_L(8); PG8_BAR; PG8_WAIT_L(0); PG8_MMA(0, 0, At, B0); PG8_BAR; PG8_SCHED;
;             PG8_LDB(B1, 1, 1); PG8_STAGE(PG8_SB(1, 0), b3, voffB);
;             PG8_BAR; PG8_WAIT_L(0); PG8_MMA(0, 1, At, B1); PG8_BAR;
;             PG8_LDA(At, 1, 1); PG8_STAGE(PG8_SA(1, 0), a3, voffA);
;             PG8_BAR; PG8_WAIT_L(0); PG8_MMA(1, 0, At, B0); PG8_BAR; PG8_SCHED;
;             PG8_STAGE(PG8_SB(1, 1), b3 + hstep, voffB);
;             PG8_WAIT_V(6); PG8_BAR; PG8_MMA(1, 1, At, B1); PG8_BAR;
;             }
;         }
;         if constexpr (ALIGN_EPI) { if (wr == 0) PG8_BAR; }
;     __device__ __forceinline__ void operator()(const f32x4 (&acc)[2][2][4][2], const Unit& u, int wr, int wc, int fr, int fq) const {
;     ...
;                 const int row = row0 + ai * 128 + m * 16;
; #pragma unroll
;                 for (int bj = 0; bj < 2; ++bj) {
;                     const int c = col0 + bj * 128;
;                     const u32x4 g = *(const u32x4*)(G + (size_t)row * P2W + c);
;                     f32x4 o0 = acc[ai][bj][m][0], o1 = acc[ai][bj][m][1];
;                     o0[0] *= bflo(g.x); o0[1] *= bfhi(g.x); o0[2] *= bflo(g.y); o0[3] *= bfhi(g.y); o1[0] *= bflo(g.z); o1[1] *= bfhi(g.z); o1[2] *= bflo(g.w); o1[3] *= bfhi(g.w);
	s_setprio 1
	s_waitcnt lgkmcnt(0)
	v_mfma_f32_16x16x32_bf16 v[62:65], v[138:141], v[178:181], v[62:65]
	v_mfma_f32_16x16x32_bf16 v[58:61], v[154:157], v[178:181], v[58:61]
	v_mfma_f32_16x16x32_bf16 v[46:49], v[138:141], v[186:189], v[46:49]
	v_mfma_f32_16x16x32_bf16 v[42:45], v[154:157], v[186:189], v[42:45]
	v_mfma_f32_16x16x32_bf16 v[30:33], v[138:141], v[194:197], v[30:33]
	v_mfma_f32_16x16x32_bf16 v[26:29], v[154:157], v[194:197], v[26:29]
	v_mfma_f32_16x16x32_bf16 v[14:17], v[138:141], v[202:205], v[14:17]
	v_mfma_f32_16x16x32_bf16 v[10:13], v[154:157], v[202:205], v[10:13]
	v_mfma_f32_16x16x32_bf16 v[62:65], v[144:147], v[182:185], v[62:65]
	v_mfma_f32_16x16x32_bf16 v[58:61], v[158:161], v[182:185], v[58:61]
	v_mfma_f32_16x16x32_bf16 v[46:49], v[144:147], v[190:193], v[46:49]
	v_mfma_f32_16x16x32_bf16 v[42:45], v[158:161], v[190:193], v[42:45]
	v_mfma_f32_16x16x32_bf16 v[30:33], v[144:147], v[198:201], v[30:33]
	v_mfma_f32_16x16x32_bf16 v[26:29], v[158:161], v[198:201], v[26:29]
	v_mfma_f32_16x16x32_bf16 v[14:17], v[144:147], v[224:227], v[14:17]
	v_mfma_f32_16x16x32_bf16 v[10:13], v[158:161], v[224:227], v[10:13]
	s_setprio 0
	s_setprio 1
	v_mfma_f32_16x16x32_bf16 v[54:57], v[162:165], v[178:181], v[54:57]
	v_mfma_f32_16x16x32_bf16 v[50:53], v[170:173], v[178:181], v[50:53]
	v_mfma_f32_16x16x32_bf16 v[38:41], v[162:165], v[186:189], v[38:41]
	v_mfma_f32_16x16x32_bf16 v[34:37], v[170:173], v[186:189], v[34:37]
	v_mfma_f32_16x16x32_bf16 v[22:25], v[162:165], v[194:197], v[22:25]
	v_mfma_f32_16x16x32_bf16 v[18:21], v[170:173], v[194:197], v[18:21]
	v_mfma_f32_16x16x32_bf16 v[6:9], v[162:165], v[202:205], v[6:9]
	v_mfma_f32_16x16x32_bf16 v[2:5], v[170:173], v[202:205], v[2:5]
	v_mfma_f32_16x16x32_bf16 v[54:57], v[166:169], v[182:185], v[54:57]
	v_mfma_f32_16x16x32_bf16 v[50:53], v[174:177], v[182:185], v[50:53]
	v_mfma_f32_16x16x32_bf16 v[38:41], v[166:169], v[190:193], v[38:41]
	v_mfma_f32_16x16x32_bf16 v[34:37], v[174:177], v[190:193], v[34:37]
	v_mfma_f32_16x16x32_bf16 v[22:25], v[166:169], v[198:201], v[22:25]
	v_mfma_f32_16x16x32_bf16 v[18:21], v[174:177], v[198:201], v[18:21]
	v_mfma_f32_16x16x32_bf16 v[6:9], v[166:169], v[224:227], v[6:9]
	v_mfma_f32_16x16x32_bf16 v[2:5], v[174:177], v[224:227], v[2:5]
	s_setprio 0
	s_add_i32 s45, s45, 2
	s_add_u32 s16, s16, 0x100
	s_addc_u32 s17, s17, 0
	s_add_u32 s43, s43, 0x100
	s_addc_u32 s44, s44, 0
	s_add_u32 s18, s16, 0xfffe0080
	s_addc_u32 s19, s17, -1
	s_add_i32 s46, 0, 0x10000
	s_cmp_eq_u32 s45, 4
	s_cselect_b32 s21, s9, s19
	s_cselect_b32 s20, s41, s18
	v_add_u32_e32 v148, s46, v151
	s_cselect_b32 s19, s7, s44
	s_cselect_b32 s18, s42, s43
	s_add_i32 s48, 0, 0x14000
	s_cmp_gt_u32 s45, 5
	s_barrier
	s_cbranch_scc0 .LBB0_891
	v_lshl_add_u32 v140, s14, 8, v150
	v_lshl_or_b32 v141, s15, 8, v152
	v_mul_lo_u32 v138, v140, s83
	v_lshlrev_b32_e32 v139, 11, v140
	v_lshl_add_u32 v138, v141, 1, v138
	v_lshl_add_u32 v139, v141, 1, v139
	global_load_dwordx4 v[144:147], v138, s[74:75]
	global_load_dwordx4 v[156:159], v138, s[74:75] offset:256
	v_add_u32_e32 v140, 0x1a000, v138
	global_load_dwordx4 v[160:163], v140, s[74:75]
	global_load_dwordx4 v[164:167], v140, s[74:75] offset:256
	v_add_u32_e32 v140, 0x34000, v138
	global_load_dwordx4 v[168:171], v140, s[74:75]
	global_load_dwordx4 v[172:175], v140, s[74:75] offset:256
	v_add_u32_e32 v140, 0x4e000, v138
	global_load_dwordx4 v[176:179], v140, s[74:75]
	global_load_dwordx4 v[180:183], v140, s[74:75] offset:256
	v_add_u32_e32 v140, 0xd0000, v138
	global_load_dwordx4 v[184:187], v140, s[74:75]
	global_load_dwordx4 v[188:191], v140, s[74:75] offset:256
	v_add_u32_e32 v140, 0xea000, v138
	global_load_dwordx4 v[192:195], v140, s[74:75]
	global_load_dwordx4 v[196:199], v140, s[74:75] offset:256
	v_add_u32_e32 v140, 0x104000, v138
	global_load_dwordx4 v[200:203], v140, s[74:75]
	global_load_dwordx4 v[224:227], v140, s[74:75] offset:256
	v_add_u32_e32 v140, 0x11e000, v138
	global_load_dwordx4 v[228:231], v140, s[74:75]
	global_load_dwordx4 v[232:235], v140, s[74:75] offset:256
	s_and_b64 vcc, exec, s[4:5]
	s_cbranch_vccz .LBB0_894
	s_barrier

; #define PG8_STAGE(bufoff, gbase, voff) do { _Pragma("unroll") for (int _i = 0; _i < 2; ++_i) \
;         __builtin_amdgcn_global_load_lds((const unsigned*)((const char*)(gbase) + (voff)[_i]), (PG8_LAS unsigned*)(lds + (bufoff) + ldsw + _i * 8192), 16, 0, 0); } while (0)
; #define PG8_LDA(dst, b, h) do { _Pragma("unroll") for (int m = 0; m < 4; ++m) _Pragma("unroll") for (int k = 0; k < 2; ++k) dst[m][k] = *(const PG8_LAS bf16x8*)(lds + PG8_SA(b, h) + aoff + m * 2048 + k * 1024); } while (0)
; #define PG8_LDB(dst, b, h) do { _Pragma("unroll") for (int n = 0; n < 2; ++n) _Pragma("unroll") for (int k = 0; k < 2; ++k) dst[n][k] = *(const PG8_LAS bf16x8*)(lds + PG8_SB(b, h) + boff + n * 2048 + k * 1024); } while (0)
; #define PG8_MMA(ai, bj, At, Bt) do { __builtin_amdgcn_s_setprio(1); _Pragma("unroll") for (int m = 0; m < 4; ++m) _Pragma("unroll") for (int n = 0; n < 2; ++n) _Pragma("unroll") for (int k = 0; k < 2; ++k) \
;         acc[ai][bj][m][n] = __builtin_amdgcn_mfma_f32_16x16x32_bf16(Bt[n][k], At[m][k], acc[ai][bj][m][n], 0, 0, 0); __builtin_amdgcn_s_setprio(0); } while (0)
; #define PG8_WAIT_V(n) asm volatile("s_waitcnt vmcnt(" #n ")" ::: "memory")
; #define PG8_BAR __builtin_amdgcn_s_barrier()
; template <class Epi, class Sched, bool ALIGN_EPI = false, bool SP2 = false>
; __device__ __forceinline__ void gemm_phase(PG8_LAS unsigned char* lds, const Gemm g, const Sched& S, const Epi& E) {
;     ...
;             const bool last = (t == nt - 2);
;             const char* a1 = cA + (size_t)(t + 1) * kstep;
;             const char* a2 = last ? nA : cA + (size_t)(t + 2) * kstep; const char* b2 = last ? nB : cB + (size_t)(t + 2) * kstep;
;             const char* a3 = a2 + kstep; const char* b3 = b2 + kstep;
;             if (last && has_next) S.a_ready(nxt);
;             if constexpr (SP2) {
;             PG8_LDB(B0, 0, 0); PG8_LDB(B1, 0, 1); PG8_SCHED; PG8_LDA(At, 0, 0); PG8_STAGE(PG8_SA(1, 1), a1 + hstep, voffA);
;             PG8_WAIT_V(8); PG8_WAIT_L(0); PG8_BAR; PG8_MMA(0, 0, At, B0); PG8_MMA(0, 1, At, B1); PG8_BAR; PG8_SCHED;
;     ...
; #pragma unroll
;         for (int a = 0; a < 2; ++a)
; #pragma unroll
;             for (int b = 0; b < 2; ++b)
; #pragma unroll
;                 for (int m = 0; m < 4; ++m)
; #pragma unroll
;                     for (int n = 0; n < 2; ++n) acc[a][b][m][n] = (f32x4){0.f, 0.f, 0.f, 0.f};
;         cur = nxt; cA = nA; cB = nB; ++ui;
.LBB0_918:
	s_add_u32 s41, s12, 0x100
	v_mov_b32_e32 v2, 0
	s_addc_u32 s42, s13, 0
	s_mov_b32 s43, -2
	v_mov_b32_e32 v3, v2
	v_mov_b32_e32 v4, v2
	v_mov_b32_e32 v5, v2
	v_mov_b32_e32 v6, v2
	v_mov_b32_e32 v7, v2
	v_mov_b32_e32 v8, v2
	v_mov_b32_e32 v9, v2
	v_mov_b32_e32 v18, v2
	v_mov_b32_e32 v19, v2
	v_mov_b32_e32 v20, v2
	v_mov_b32_e32 v21, v2
	v_mov_b32_e32 v22, v2
	v_mov_b32_e32 v23, v2
	v_mov_b32_e32 v24, v2
	v_mov_b32_e32 v25, v2
	v_mov_b32_e32 v34, v2
	v_mov_b32_e32 v35, v2
	v_mov_b32_e32 v36, v2
	v_mov_b32_e32 v37, v2
	v_mov_b32_e32 v38, v2
	v_mov_b32_e32 v39, v2
	v_mov_b32_e32 v40, v2
	v_mov_b32_e32 v41, v2
	v_mov_b32_e32 v50, v2
	v_mov_b32_e32 v51, v2
	v_mov_b32_e32 v52, v2
	v_mov_b32_e32 v53, v2
	v_mov_b32_e32 v54, v2
	v_mov_b32_e32 v55, v2
	v_mov_b32_e32 v56, v2
	v_mov_b32_e32 v57, v2
	v_mov_b32_e32 v10, v2
	v_mov_b32_e32 v11, v2
	v_mov_b32_e32 v12, v2
	v_mov_b32_e32 v13, v2
	v_mov_b32_e32 v14, v2
	v_mov_b32_e32 v15, v2
	v_mov_b32_e32 v16, v2
	v_mov_b32_e32 v17, v2
	v_mov_b32_e32 v26, v2
	v_mov_b32_e32 v27, v2
	v_mov_b32_e32 v28, v2
	v_mov_b32_e32 v29, v2
	v_mov_b32_e32 v30, v2
	v_mov_b32_e32 v31, v2
	v_mov_b32_e32 v32, v2
	v_mov_b32_e32 v33, v2
	v_mov_b32_e32 v42, v2
	v_mov_b32_e32 v43, v2
	v_mov_b32_e32 v44, v2
	v_mov_b32_e32 v45, v2
	v_mov_b32_e32 v46, v2
	v_mov_b32_e32 v47, v2
	v_mov_b32_e32 v48, v2
	v_mov_b32_e32 v49, v2
	v_mov_b32_e32 v58, v2
	v_mov_b32_e32 v59, v2
	v_mov_b32_e32 v60, v2
	v_mov_b32_e32 v61, v2
	v_mov_b32_e32 v62, v2
	v_mov_b32_e32 v63, v2
	v_mov_b32_e32 v64, v2
	v_mov_b32_e32 v65, v2
	v_mov_b32_e32 v66, v2
	v_mov_b32_e32 v67, v2
	v_mov_b32_e32 v68, v2
	v_mov_b32_e32 v69, v2
	v_mov_b32_e32 v70, v2
	v_mov_b32_e32 v71, v2
	v_mov_b32_e32 v72, v2
	v_mov_b32_e32 v73, v2
	v_mov_b32_e32 v82, v2
	v_mov_b32_e32 v83, v2
	v_mov_b32_e32 v84, v2
	v_mov_b32_e32 v85, v2
	v_mov_b32_e32 v86, v2
	v_mov_b32_e32 v87, v2
	v_mov_b32_e32 v88, v2
	v_mov_b32_e32 v89, v2
	v_mov_b32_e32 v98, v2
	v_mov_b32_e32 v99, v2
	v_mov_b32_e32 v100, v2
	v_mov_b32_e32 v101, v2
	v_mov_b32_e32 v102, v2
	v_mov_b32_e32 v103, v2
	v_mov_b32_e32 v104, v2
	v_mov_b32_e32 v105, v2
	v_mov_b32_e32 v114, v2
	v_mov_b32_e32 v115, v2
	v_mov_b32_e32 v116, v2
	v_mov_b32_e32 v117, v2
	v_mov_b32_e32 v118, v2
	v_mov_b32_e32 v119, v2
	v_mov_b32_e32 v120, v2
	v_mov_b32_e32 v121, v2
	v_mov_b32_e32 v74, v2
	v_mov_b32_e32 v75, v2
	v_mov_b32_e32 v76, v2
	v_mov_b32_e32 v77, v2
	v_mov_b32_e32 v78, v2
	v_mov_b32_e32 v79, v2
	v_mov_b32_e32 v80, v2
	v_mov_b32_e32 v81, v2
	v_mov_b32_e32 v90, v2
	v_mov_b32_e32 v91, v2
	v_mov_b32_e32 v92, v2
	v_mov_b32_e32 v93, v2
	v_mov_b32_e32 v94, v2
	v_mov_b32_e32 v95, v2
	v_mov_b32_e32 v96, v2
	v_mov_b32_e32 v97, v2
	v_mov_b32_e32 v106, v2
	v_mov_b32_e32 v107, v2
	v_mov_b32_e32 v108, v2
	v_mov_b32_e32 v109, v2
	v_mov_b32_e32 v110, v2
	v_mov_b32_e32 v111, v2
	v_mov_b32_e32 v112, v2
	v_mov_b32_e32 v113, v2
	v_mov_b32_e32 v122, v2
	v_mov_b32_e32 v123, v2
	v_mov_b32_e32 v124, v2
	v_mov_b32_e32 v125, v2
	v_mov_b32_e32 v126, v2
	v_mov_b32_e32 v127, v2
	v_mov_b32_e32 v128, v2
	v_mov_b32_e32 v129, v2
	s_add_u32 s12, s10, 0x100
	s_addc_u32 s13, s11, 0
	s_add_i32 s44, 0, 0x10000
	s_cmp_eq_u32 s43, 16
	s_cselect_b32 s17, s5, s13
	s_cselect_b32 s16, s4, s12
	v_add_u32_e32 v148, s44, v151
	s_cselect_b32 s15, s9, s42
	s_cselect_b32 s14, s8, s41
	s_add_i32 s45, 0, 0x14000
.LBB0_919:
	ds_read_b128 v[138:141], v148
	ds_read_b128 v[144:147], v148 offset:1024
	ds_read_b128 v[154:157], v148 offset:2048
	ds_read_b128 v[158:161], v148 offset:3072
	v_add_u32_e32 v148, s45, v151
	ds_read_b128 v[162:165], v148
	ds_read_b128 v[166:169], v148 offset:1024
	ds_read_b128 v[170:173], v148 offset:2048
	ds_read_b128 v[174:177], v148 offset:3072
	v_lshl_add_u64 v[148:149], s[10:11], 0, v[136:137]
	s_add_i32 m0, s23, 0xc000
	ds_read_b128 v[178:181], v153
	ds_read_b128 v[182:185], v153 offset:1024
	ds_read_b128 v[186:189], v153 offset:2048
	ds_read_b128 v[190:193], v153 offset:3072
	ds_read_b128 v[194:197], v153 offset:4096
	ds_read_b128 v[198:201], v153 offset:5120
	ds_read_b128 v[202:205], v153 offset:6144
	ds_read_b128 v[224:227], v153 offset:7168
	global_load_lds_dwordx4 v[148:149], off
	v_lshl_add_u64 v[148:149], s[10:11], 0, v[142:143]
	s_add_i32 m0, s23, 0xe000
	s_nop 0
	global_load_lds_dwordx4 v[148:149], off
	s_waitcnt vmcnt(8)
	s_waitcnt lgkmcnt(0)
	s_barrier
	s_setprio 1
	s_waitcnt lgkmcnt(0)
	v_mfma_f32_16x16x32_bf16 v[126:129], v[138:141], v[178:181], v[126:129]
	v_mfma_f32_16x16x32_bf16 v[122:125], v[154:157], v[178:181], v[122:125]
	v_mfma_f32_16x16x32_bf16 v[110:113], v[138:141], v[186:189], v[110:113]
	v_mfma_f32_16x16x32_bf16 v[106:109], v[154:157], v[186:189], v[106:109]
	v_mfma_f32_16x16x32_bf16 v[94:97], v[138:141], v[194:197], v[94:97]
	v_mfma_f32_16x16x32_bf16 v[90:93], v[154:157], v[194:197], v[90:93]
	v_mfma_f32_16x16x32_bf16 v[78:81], v[138:141], v[202:205], v[78:81]
	v_mfma_f32_16x16x32_bf16 v[74:77], v[154:157], v[202:205], v[74:77]
	v_mfma_f32_16x16x32_bf16 v[126:129], v[144:147], v[182:185], v[126:129]
	v_mfma_f32_16x16x32_bf16 v[122:125], v[158:161], v[182:185], v[122:125]
	v_mfma_f32_16x16x32_bf16 v[110:113], v[144:147], v[190:193], v[110:113]
	v_mfma_f32_16x16x32_bf16 v[106:109], v[158:161], v[190:193], v[106:109]
	v_mfma_f32_16x16x32_bf16 v[94:97], v[144:147], v[198:201], v[94:97]
	v_mfma_f32_16x16x32_bf16 v[90:93], v[158:161], v[198:201], v[90:93]
	v_mfma_f32_16x16x32_bf16 v[78:81], v[144:147], v[224:227], v[78:81]
	v_mfma_f32_16x16x32_bf16 v[74:77], v[158:161], v[224:227], v[74:77]
	s_setprio 0
	s_setprio 1
	v_mfma_f32_16x16x32_bf16 v[118:121], v[162:165], v[178:181], v[118:121]
	v_mfma_f32_16x16x32_bf16 v[114:117], v[170:173], v[178:181], v[114:117]
	v_mfma_f32_16x16x32_bf16 v[102:105], v[162:165], v[186:189], v[102:105]
	v_mfma_f32_16x16x32_bf16 v[98:101], v[170:173], v[186:189], v[98:101]
	v_mfma_f32_16x16x32_bf16 v[86:89], v[162:165], v[194:197], v[86:89]
	v_mfma_f32_16x16x32_bf16 v[82:85], v[170:173], v[194:197], v[82:85]
	v_mfma_f32_16x16x32_bf16 v[70:73], v[162:165], v[202:205], v[70:73]
	v_mfma_f32_16x16x32_bf16 v[66:69], v[170:173], v[202:205], v[66:69]
	v_mfma_f32_16x16x32_bf16 v[118:121], v[166:169], v[182:185], v[118:121]
	v_mfma_f32_16x16x32_bf16 v[114:117], v[174:177], v[182:185], v[114:117]
	v_mfma_f32_16x16x32_bf16 v[102:105], v[166:169], v[190:193], v[102:105]
	v_mfma_f32_16x16x32_bf16 v[98:101], v[174:177], v[190:193], v[98:101]
	v_mfma_f32_16x16x32_bf16 v[86:89], v[166:169], v[198:201], v[86:89]
	v_mfma_f32_16x16x32_bf16 v[82:85], v[174:177], v[198:201], v[82:85]
	v_mfma_f32_16x16x32_bf16 v[70:73], v[166:169], v[224:227], v[70:73]
	v_mfma_f32_16x16x32_bf16 v[66:69], v[174:177], v[224:227], v[66:69]
	s_setprio 0
	s_barrier
; #define PG8_STAGE(bufoff, gbase, voff) do { _Pragma("unroll") for (int _i = 0; _i < 2; ++_i) \
;         __builtin_amdgcn_global_load_lds((const unsigned*)((const char*)(gbase) + (voff)[_i]), (PG8_LAS unsigned*)(lds + (bufoff) + ldsw + _i * 8192), 16, 0, 0); } while (0)
; #define PG8_LDA(dst, b, h) do { _Pragma("unroll") for (int m = 0; m < 4; ++m) _Pragma("unroll") for (int k = 0; k < 2; ++k) dst[m][k] = *(const PG8_LAS bf16x8*)(lds + PG8_SA(b, h) + aoff + m * 2048 + k * 1024); } while (0)
; #define PG8_LDB(dst, b, h) do { _Pragma("unroll") for (int n = 0; n < 2; ++n) _Pragma("unroll") for (int k = 0; k < 2; ++k) dst[n][k] = *(const PG8_LAS bf16x8*)(lds + PG8_SB(b, h) + boff + n * 2048 + k * 1024); } while (0)
; #define PG8_MMA(ai, bj, At, Bt) do { __builtin_amdgcn_s_setprio(1); _Pragma("unroll") for (int m = 0; m < 4; ++m) _Pragma("unroll") for (int n = 0; n < 2; ++n) _Pragma("unroll") for (int k = 0; k < 2; ++k) \
;         acc[ai][bj][m][n] = __builtin_amdgcn_mfma_f32_16x16x32_bf16(Bt[n][k], At[m][k], acc[ai][bj][m][n], 0, 0, 0); __builtin_amdgcn_s_setprio(0); } while (0)
; #define PG8_WAIT_V(n) asm volatile("s_waitcnt vmcnt(" #n ")" ::: "memory")
; #define PG8_WAIT_L(n) asm volatile("s_waitcnt lgkmcnt(" #n ")" ::: "memory")
; #define PG8_BAR __builtin_amdgcn_s_barrier()
; #define PG8_SCHED __builtin_amdgcn_sched_barrier(0)
; template <class Epi, class Sched, bool ALIGN_EPI = false, bool SP2 = false>
; __device__ __forceinline__ void gemm_phase(PG8_LAS unsigned char* lds, const Gemm g, const Sched& S, const Epi& E) {
;     ...
;             PG8_LDA(At, 0, 1); PG8_STAGE(PG8_SB(0, 0), b2, voffB); PG8_STAGE(PG8_SB(0, 1), b2 + hstep, voffB); PG8_STAGE(PG8_SA(0, 0), a2, voffA);
;             PG8_WAIT_V(8); PG8_WAIT_L(0); PG8_BAR; PG8_MMA(1, 0, At, B0); PG8_MMA(1, 1, At, B1); PG8_BAR; PG8_SCHED;
;             PG8_LDB(B0, 1, 0); PG8_LDB(B1, 1, 1); PG8_SCHED; PG8_LDA(At, 1, 0); PG8_STAGE(PG8_SA(0, 1), a2 + hstep, voffA);
	s_add_i32 s10, s44, s20
	v_lshl_add_u64 v[148:149], s[14:15], 0, v[0:1]
	s_mov_b32 m0, s10
	ds_read_b128 v[178:181], v153 offset:16384
	ds_read_b128 v[182:185], v153 offset:17408
	ds_read_b128 v[186:189], v153 offset:18432
	ds_read_b128 v[190:193], v153 offset:19456
	ds_read_b128 v[194:197], v153 offset:20480
	ds_read_b128 v[198:201], v153 offset:21504
	ds_read_b128 v[202:205], v153 offset:22528
	ds_read_b128 v[224:227], v153 offset:23552
	global_load_lds_dwordx4 v[148:149], off
	s_add_i32 m0, s10, 0x2000
	s_add_u32 s10, s14, 0x50000
	v_lshl_add_u64 v[228:229], s[14:15], 0, v[134:135]
	s_addc_u32 s11, s15, 0
	s_add_i32 s44, s45, s20
	global_load_lds_dwordx4 v[228:229], off
	v_lshl_add_u64 v[230:231], s[10:11], 0, v[0:1]
	s_mov_b32 m0, s44
	v_lshl_add_u64 v[232:233], s[16:17], 0, v[132:133]
	global_load_lds_dwordx4 v[230:231], off
	v_lshl_add_u64 v[230:231], s[10:11], 0, v[134:135]
	s_add_i32 m0, s44, 0x2000
	s_nop 0
	global_load_lds_dwordx4 v[230:231], off
	v_lshl_add_u64 v[230:231], s[16:17], 0, v[130:131]
	s_mov_b32 m0, s23
	s_nop 0
	global_load_lds_dwordx4 v[230:231], off
	s_mov_b32 m0, s24
	s_nop 0
	global_load_lds_dwordx4 v[232:233], off
	s_waitcnt vmcnt(8)
	s_waitcnt lgkmcnt(0)
	s_barrier
	s_setprio 1
	s_waitcnt lgkmcnt(0)
	v_mfma_f32_16x16x32_bf16 v[62:65], v[138:141], v[178:181], v[62:65]
	v_mfma_f32_16x16x32_bf16 v[58:61], v[154:157], v[178:181], v[58:61]
	v_mfma_f32_16x16x32_bf16 v[46:49], v[138:141], v[186:189], v[46:49]
	v_mfma_f32_16x16x32_bf16 v[42:45], v[154:157], v[186:189], v[42:45]
	v_mfma_f32_16x16x32_bf16 v[30:33], v[138:141], v[194:197], v[30:33]
	v_mfma_f32_16x16x32_bf16 v[26:29], v[154:157], v[194:197], v[26:29]
	v_mfma_f32_16x16x32_bf16 v[14:17], v[138:141], v[202:205], v[14:17]
	v_mfma_f32_16x16x32_bf16 v[10:13], v[154:157], v[202:205], v[10:13]
	v_mfma_f32_16x16x32_bf16 v[62:65], v[144:147], v[182:185], v[62:65]
	v_mfma_f32_16x16x32_bf16 v[58:61], v[158:161], v[182:185], v[58:61]
	v_mfma_f32_16x16x32_bf16 v[46:49], v[144:147], v[190:193], v[46:49]
	v_mfma_f32_16x16x32_bf16 v[42:45], v[158:161], v[190:193], v[42:45]
	v_mfma_f32_16x16x32_bf16 v[30:33], v[144:147], v[198:201], v[30:33]
	v_mfma_f32_16x16x32_bf16 v[26:29], v[158:161], v[198:201], v[26:29]
	v_mfma_f32_16x16x32_bf16 v[14:17], v[144:147], v[224:227], v[14:17]
	v_mfma_f32_16x16x32_bf16 v[10:13], v[158:161], v[224:227], v[10:13]
	s_setprio 0
	s_setprio 1
	v_mfma_f32_16x16x32_bf16 v[54:57], v[162:165], v[178:181], v[54:57]
	v_mfma_f32_16x16x32_bf16 v[50:53], v[170:173], v[178:181], v[50:53]
	v_mfma_f32_16x16x32_bf16 v[38:41], v[162:165], v[186:189], v[38:41]
	v_mfma_f32_16x16x32_bf16 v[34:37], v[170:173], v[186:189], v[34:37]
	v_mfma_f32_16x16x32_bf16 v[22:25], v[162:165], v[194:197], v[22:25]
	v_mfma_f32_16x16x32_bf16 v[18:21], v[170:173], v[194:197], v[18:21]
	v_mfma_f32_16x16x32_bf16 v[6:9], v[162:165], v[202:205], v[6:9]
	v_mfma_f32_16x16x32_bf16 v[2:5], v[170:173], v[202:205], v[2:5]
	v_mfma_f32_16x16x32_bf16 v[54:57], v[166:169], v[182:185], v[54:57]
	v_mfma_f32_16x16x32_bf16 v[50:53], v[174:177], v[182:185], v[50:53]
	v_mfma_f32_16x16x32_bf16 v[38:41], v[166:169], v[190:193], v[38:41]
	v_mfma_f32_16x16x32_bf16 v[34:37], v[174:177], v[190:193], v[34:37]
	v_mfma_f32_16x16x32_bf16 v[22:25], v[166:169], v[198:201], v[22:25]
	v_mfma_f32_16x16x32_bf16 v[18:21], v[174:177], v[198:201], v[18:21]
	v_mfma_f32_16x16x32_bf16 v[6:9], v[166:169], v[224:227], v[6:9]
	v_mfma_f32_16x16x32_bf16 v[2:5], v[174:177], v[224:227], v[2:5]
	s_setprio 0
	s_barrier
	s_add_i32 s44, 0, 0x18000
	s_add_i32 s45, 0, 0x1c000
	v_add_u32_e32 v158, s44, v151
	v_add_u32_e32 v174, s45, v151
	ds_read_b128 v[138:141], v158
	ds_read_b128 v[144:147], v158 offset:1024
	ds_read_b128 v[154:157], v158 offset:2048
	ds_read_b128 v[158:161], v158 offset:3072
	ds_read_b128 v[162:165], v174
	ds_read_b128 v[166:169], v174 offset:1024
	ds_read_b128 v[170:173], v174 offset:2048
	ds_read_b128 v[174:177], v174 offset:3072
	s_add_u32 s10, s16, 0x50000
	s_addc_u32 s11, s17, 0
	s_mov_b32 m0, s25
	v_lshl_add_u64 v[234:235], s[10:11], 0, v[130:131]
	ds_read_b128 v[178:181], v153 offset:32768
	ds_read_b128 v[182:185], v153 offset:33792
	ds_read_b128 v[186:189], v153 offset:34816
	ds_read_b128 v[190:193], v153 offset:35840
	ds_read_b128 v[194:197], v153 offset:36864
	ds_read_b128 v[198:201], v153 offset:37888
	ds_read_b128 v[202:205], v153 offset:38912
	ds_read_b128 v[224:227], v153 offset:39936
	global_load_lds_dwordx4 v[234:235], off
	v_lshl_add_u64 v[234:235], s[10:11], 0, v[132:133]
	s_mov_b32 m0, s26
	s_nop 0
	global_load_lds_dwordx4 v[234:235], off
	s_waitcnt vmcnt(8)
	s_waitcnt lgkmcnt(0)
	s_barrier
; #define PG8_STAGE(bufoff, gbase, voff) do { _Pragma("unroll") for (int _i = 0; _i < 2; ++_i) \
;         __builtin_amdgcn_global_load_lds((const unsigned*)((const char*)(gbase) + (voff)[_i]), (PG8_LAS unsigned*)(lds + (bufoff) + ldsw + _i * 8192), 16, 0, 0); } while (0)
; #define PG8_LDA(dst, b, h) do { _Pragma("unroll") for (int m = 0; m < 4; ++m) _Pragma("unroll") for (int k = 0; k < 2; ++k) dst[m][k] = *(const PG8_LAS bf16x8*)(lds + PG8_SA(b, h) + aoff + m * 2048 + k * 1024); } while (0)
; #define PG8_MMA(ai, bj, At, Bt) do { __builtin_amdgcn_s_setprio(1); _Pragma("unroll") for (int m = 0; m < 4; ++m) _Pragma("unroll") for (int n = 0; n < 2; ++n) _Pragma("unroll") for (int k = 0; k < 2; ++k) \
;         acc[ai][bj][m][n] = __builtin_amdgcn_mfma_f32_16x16x32_bf16(Bt[n][k], At[m][k], acc[ai][bj][m][n], 0, 0, 0); __builtin_amdgcn_s_setprio(0); } while (0)
; #define PG8_WAIT_V(n) asm volatile("s_waitcnt vmcnt(" #n ")" ::: "memory")
; #define PG8_WAIT_L(n) asm volatile("s_waitcnt lgkmcnt(" #n ")" ::: "memory")
; #define PG8_BAR __builtin_amdgcn_s_barrier()
; #define PG8_SCHED __builtin_amdgcn_sched_barrier(0)
; template <class Epi, class Sched, bool ALIGN_EPI = false, bool SP2 = false>
; __device__ __forceinline__ void gemm_phase(PG8_LAS unsigned char* lds, const Gemm g, const Sched& S, const Epi& E) {
;     ...
;             PG8_WAIT_V(8); PG8_WAIT_L(0); PG8_BAR; PG8_MMA(0, 0, At, B0); PG8_MMA(0, 1, At, B1); PG8_BAR; PG8_SCHED;
;             PG8_LDA(At, 1, 1); PG8_STAGE(PG8_SB(1, 0), b3, voffB); PG8_STAGE(PG8_SB(1, 1), b3 + hstep, voffB); PG8_STAGE(PG8_SA(1, 0), a3, voffA);
	s_setprio 1
	s_waitcnt lgkmcnt(0)
	v_mfma_f32_16x16x32_bf16 v[126:129], v[138:141], v[178:181], v[126:129]
	v_mfma_f32_16x16x32_bf16 v[122:125], v[154:157], v[178:181], v[122:125]
	v_mfma_f32_16x16x32_bf16 v[110:113], v[138:141], v[186:189], v[110:113]
	v_mfma_f32_16x16x32_bf16 v[106:109], v[154:157], v[186:189], v[106:109]
	v_mfma_f32_16x16x32_bf16 v[94:97], v[138:141], v[194:197], v[94:97]
	v_mfma_f32_16x16x32_bf16 v[90:93], v[154:157], v[194:197], v[90:93]
	v_mfma_f32_16x16x32_bf16 v[78:81], v[138:141], v[202:205], v[78:81]
	v_mfma_f32_16x16x32_bf16 v[74:77], v[154:157], v[202:205], v[74:77]
	v_mfma_f32_16x16x32_bf16 v[126:129], v[144:147], v[182:185], v[126:129]
	v_mfma_f32_16x16x32_bf16 v[122:125], v[158:161], v[182:185], v[122:125]
	v_mfma_f32_16x16x32_bf16 v[110:113], v[144:147], v[190:193], v[110:113]
	v_mfma_f32_16x16x32_bf16 v[106:109], v[158:161], v[190:193], v[106:109]
	v_mfma_f32_16x16x32_bf16 v[94:97], v[144:147], v[198:201], v[94:97]
	v_mfma_f32_16x16x32_bf16 v[90:93], v[158:161], v[198:201], v[90:93]
	v_mfma_f32_16x16x32_bf16 v[78:81], v[144:147], v[224:227], v[78:81]
	v_mfma_f32_16x16x32_bf16 v[74:77], v[158:161], v[224:227], v[74:77]
	s_setprio 0
	s_setprio 1
	v_mfma_f32_16x16x32_bf16 v[118:121], v[162:165], v[178:181], v[118:121]
	v_mfma_f32_16x16x32_bf16 v[114:117], v[170:173], v[178:181], v[114:117]
	v_mfma_f32_16x16x32_bf16 v[102:105], v[162:165], v[186:189], v[102:105]
	v_mfma_f32_16x16x32_bf16 v[98:101], v[170:173], v[186:189], v[98:101]
	v_mfma_f32_16x16x32_bf16 v[86:89], v[162:165], v[194:197], v[86:89]
	v_mfma_f32_16x16x32_bf16 v[82:85], v[170:173], v[194:197], v[82:85]
	v_mfma_f32_16x16x32_bf16 v[70:73], v[162:165], v[202:205], v[70:73]
	v_mfma_f32_16x16x32_bf16 v[66:69], v[170:173], v[202:205], v[66:69]
	v_mfma_f32_16x16x32_bf16 v[118:121], v[166:169], v[182:185], v[118:121]
	v_mfma_f32_16x16x32_bf16 v[114:117], v[174:177], v[182:185], v[114:117]
	v_mfma_f32_16x16x32_bf16 v[102:105], v[166:169], v[190:193], v[102:105]
	v_mfma_f32_16x16x32_bf16 v[98:101], v[174:177], v[190:193], v[98:101]
	v_mfma_f32_16x16x32_bf16 v[86:89], v[166:169], v[198:201], v[86:89]
	v_mfma_f32_16x16x32_bf16 v[82:85], v[174:177], v[198:201], v[82:85]
	v_mfma_f32_16x16x32_bf16 v[70:73], v[166:169], v[224:227], v[70:73]
	v_mfma_f32_16x16x32_bf16 v[66:69], v[174:177], v[224:227], v[66:69]
	s_setprio 0
	s_barrier
	s_add_i32 s10, s44, s20
	v_lshl_add_u64 v[148:149], v[148:149], 0, s[86:87]
	s_mov_b32 m0, s10
	ds_read_b128 v[178:181], v153 offset:49152
	ds_read_b128 v[182:185], v153 offset:50176
	ds_read_b128 v[186:189], v153 offset:51200
	ds_read_b128 v[190:193], v153 offset:52224
	ds_read_b128 v[194:197], v153 offset:53248
	ds_read_b128 v[198:201], v153 offset:54272
	ds_read_b128 v[202:205], v153 offset:55296
	ds_read_b128 v[224:227], v153 offset:56320
	global_load_lds_dwordx4 v[148:149], off
	s_add_i32 m0, s10, 0x2000
	s_add_u32 s10, s14, 0x50080
	v_lshl_add_u64 v[148:149], v[228:229], 0, s[86:87]
	s_addc_u32 s11, s15, 0
	s_add_i32 s14, s45, s20
	global_load_lds_dwordx4 v[148:149], off
	v_lshl_add_u64 v[148:149], s[10:11], 0, v[0:1]
	s_mov_b32 m0, s14
	s_nop 0
	global_load_lds_dwordx4 v[148:149], off
	v_lshl_add_u64 v[148:149], s[10:11], 0, v[134:135]
	s_add_i32 m0, s14, 0x2000
	s_nop 0
	global_load_lds_dwordx4 v[148:149], off
	v_lshl_add_u64 v[148:149], v[230:231], 0, s[86:87]
	s_mov_b32 m0, s27
	s_nop 0
	global_load_lds_dwordx4 v[148:149], off
	v_lshl_add_u64 v[148:149], v[232:233], 0, s[86:87]
	s_mov_b32 m0, s28
	s_nop 0
	global_load_lds_dwordx4 v[148:149], off
	s_waitcnt vmcnt(8)
	s_waitcnt lgkmcnt(0)
	s_barrier
; #define PG8_LDA(dst, b, h) do { _Pragma("unroll") for (int m = 0; m < 4; ++m) _Pragma("unroll") for (int k = 0; k < 2; ++k) dst[m][k] = *(const PG8_LAS bf16x8*)(lds + PG8_SA(b, h) + aoff + m * 2048 + k * 1024); } while (0)
; template <class Epi, class Sched, bool ALIGN_EPI = false, bool SP2 = false>
; __device__ __forceinline__ void gemm_phase(PG8_LAS unsigned char* lds, const Gemm g, const Sched& S, const Epi& E) {
;     ...
;             PG8_WAIT_V(8); PG8_WAIT_L(0); PG8_BAR; PG8_MMA(1, 0, At, B0); PG8_MMA(1, 1, At, B1); PG8_BAR; PG8_SCHED;
;             } else {
;             PG8_LDB(B0, 0, 0); PG8_SCHED; PG8_LDA(At, 0, 0); PG8_STAGE(PG8_SA(1, 1), a1 + hstep, voffA);
;             PG8_WAIT_L(8); PG8_BAR; PG8_WAIT_L(0); PG8_MMA(0, 0, At, B0); PG8_BAR; PG8_SCHED;
;             PG8_LDB(B1, 0, 1); PG8_STAGE(PG8_SB(0, 0), b2, voffB);
;             PG8_BAR; PG8_WAIT_L(0); PG8_MMA(0, 1, At, B1); PG8_BAR;
;             PG8_LDA(At, 0, 1); PG8_STAGE(PG8_SA(0, 0), a2, voffA);
;             PG8_BAR; PG8_WAIT_L(0); PG8_MMA(1, 0, At, B0); PG8_BAR; PG8_SCHED;
;             PG8_STAGE(PG8_SB(0, 1), b2 + hstep, voffB);
;             PG8_WAIT_V(6); PG8_BAR; PG8_MMA(1, 1, At, B1); PG8_BAR;
;             PG8_LDB(B0, 1, 0); PG8_SCHED; PG8_LDA(At, 1, 0); PG8_STAGE(PG8_SA(0, 1), a2 + hstep, voffA);
;             PG8_WAIT_L(8); PG8_BAR; PG8_WAIT_L(0); PG8_MMA(0, 0, At, B0); PG8_BAR; PG8_SCHED;
;             PG8_LDB(B1, 1, 1); PG8_STAGE(PG8_SB(1, 0), b3, voffB);
;             PG8_BAR; PG8_WAIT_L(0); PG8_MMA(0, 1, At, B1); PG8_BAR;
;             PG8_LDA(At, 1, 1); PG8_STAGE(PG8_SA(1, 0), a3, voffA);
;             PG8_BAR; PG8_WAIT_L(0); PG8_MMA(1, 0, At, B0); PG8_BAR; PG8_SCHED;
;             PG8_STAGE(PG8_SB(1, 1), b3 + hstep, voffB);
;             PG8_WAIT_V(6); PG8_BAR; PG8_MMA(1, 1, At, B1); PG8_BAR;
;             }
;         }
;         if constexpr (ALIGN_EPI) { if (wr == 0) PG8_BAR; }
;     __device__ __forceinline__ void operator()(const f32x4 (&acc)[2][2][4][2], const Unit& u, int wr, int wc, int fr, int fq) const {
;     ...
;                 const int row = row0 + ai * 128 + m * 16;
; #pragma unroll
;                 for (int bj = 0; bj < 2; ++bj) {
;                     const int c = col0 + bj * 128;
;                     const u32x4 g = *(const u32x4*)(G + (size_t)row * P2W + c);
;                     const u32x4 t = *(const u32x4*)(T + (size_t)row * D + c);
	s_setprio 1
	s_waitcnt lgkmcnt(0)
	v_mfma_f32_16x16x32_bf16 v[62:65], v[138:141], v[178:181], v[62:65]
	v_mfma_f32_16x16x32_bf16 v[58:61], v[154:157], v[178:181], v[58:61]
	v_mfma_f32_16x16x32_bf16 v[46:49], v[138:141], v[186:189], v[46:49]
	v_mfma_f32_16x16x32_bf16 v[42:45], v[154:157], v[186:189], v[42:45]
	v_mfma_f32_16x16x32_bf16 v[30:33], v[138:141], v[194:197], v[30:33]
	v_mfma_f32_16x16x32_bf16 v[26:29], v[154:157], v[194:197], v[26:29]
	v_mfma_f32_16x16x32_bf16 v[14:17], v[138:141], v[202:205], v[14:17]
	v_mfma_f32_16x16x32_bf16 v[10:13], v[154:157], v[202:205], v[10:13]
	v_mfma_f32_16x16x32_bf16 v[62:65], v[144:147], v[182:185], v[62:65]
	v_mfma_f32_16x16x32_bf16 v[58:61], v[158:161], v[182:185], v[58:61]
	v_mfma_f32_16x16x32_bf16 v[46:49], v[144:147], v[190:193], v[46:49]
	v_mfma_f32_16x16x32_bf16 v[42:45], v[158:161], v[190:193], v[42:45]
	v_mfma_f32_16x16x32_bf16 v[30:33], v[144:147], v[198:201], v[30:33]
	v_mfma_f32_16x16x32_bf16 v[26:29], v[158:161], v[198:201], v[26:29]
	v_mfma_f32_16x16x32_bf16 v[14:17], v[144:147], v[224:227], v[14:17]
	v_mfma_f32_16x16x32_bf16 v[10:13], v[158:161], v[224:227], v[10:13]
	s_setprio 0
	s_setprio 1
	v_mfma_f32_16x16x32_bf16 v[54:57], v[162:165], v[178:181], v[54:57]
	v_mfma_f32_16x16x32_bf16 v[50:53], v[170:173], v[178:181], v[50:53]
	v_mfma_f32_16x16x32_bf16 v[38:41], v[162:165], v[186:189], v[38:41]
	v_mfma_f32_16x16x32_bf16 v[34:37], v[170:173], v[186:189], v[34:37]
	v_mfma_f32_16x16x32_bf16 v[22:25], v[162:165], v[194:197], v[22:25]
	v_mfma_f32_16x16x32_bf16 v[18:21], v[170:173], v[194:197], v[18:21]
	v_mfma_f32_16x16x32_bf16 v[6:9], v[162:165], v[202:205], v[6:9]
	v_mfma_f32_16x16x32_bf16 v[2:5], v[170:173], v[202:205], v[2:5]
	v_mfma_f32_16x16x32_bf16 v[54:57], v[166:169], v[182:185], v[54:57]
	v_mfma_f32_16x16x32_bf16 v[50:53], v[174:177], v[182:185], v[50:53]
	v_mfma_f32_16x16x32_bf16 v[38:41], v[166:169], v[190:193], v[38:41]
	v_mfma_f32_16x16x32_bf16 v[34:37], v[174:177], v[190:193], v[34:37]
	v_mfma_f32_16x16x32_bf16 v[22:25], v[166:169], v[198:201], v[22:25]
	v_mfma_f32_16x16x32_bf16 v[18:21], v[174:177], v[198:201], v[18:21]
	v_mfma_f32_16x16x32_bf16 v[6:9], v[166:169], v[224:227], v[6:9]
	v_mfma_f32_16x16x32_bf16 v[2:5], v[174:177], v[224:227], v[2:5]
	s_setprio 0
	s_add_i32 s43, s43, 2
	s_add_u32 s41, s41, 0x100
	s_addc_u32 s42, s42, 0
	s_mov_b64 s[10:11], s[12:13]
	s_add_u32 s12, s10, 0x100
	s_addc_u32 s13, s11, 0
	s_add_i32 s44, 0, 0x10000
	s_cmp_eq_u32 s43, 16
	s_cselect_b32 s17, s5, s13
	s_cselect_b32 s16, s4, s12
	v_add_u32_e32 v148, s44, v151
	s_cselect_b32 s15, s9, s42
	s_cselect_b32 s14, s8, s41
	s_add_i32 s45, 0, 0x14000
	s_cmp_gt_u32 s43, 17
	s_barrier
	s_cbranch_scc0 .LBB0_919
	v_lshl_add_u32 v140, s38, 8, v150
	v_lshl_or_b32 v141, s39, 8, v152
	v_mul_lo_u32 v138, v140, s83
	v_lshlrev_b32_e32 v139, 11, v140
	v_lshl_add_u32 v138, v141, 1, v138
	v_lshl_add_u32 v139, v141, 1, v139
	global_load_dwordx4 v[144:147], v138, s[72:73]
	global_load_dwordx4 v[156:159], v139, s[36:37]
	global_load_dwordx4 v[160:163], v138, s[72:73] offset:256
	global_load_dwordx4 v[164:167], v139, s[36:37] offset:256
	v_add_u32_e32 v140, 0x1a000, v138
	v_add_u32_e32 v141, 0x8000, v139
	global_load_dwordx4 v[168:171], v140, s[72:73]
	global_load_dwordx4 v[172:175], v141, s[36:37]
	global_load_dwordx4 v[176:179], v140, s[72:73] offset:256
	global_load_dwordx4 v[180:183], v141, s[36:37] offset:256
	v_add_u32_e32 v140, 0x34000, v138
	v_add_u32_e32 v141, 0x10000, v139
	global_load_dwordx4 v[184:187], v140, s[72:73]
	global_load_dwordx4 v[188:191], v141, s[36:37]
	global_load_dwordx4 v[192:195], v140, s[72:73] offset:256
	global_load_dwordx4 v[196:199], v141, s[36:37] offset:256
	v_add_u32_e32 v140, 0x4e000, v138
	v_add_u32_e32 v141, 0x18000, v139
	global_load_dwordx4 v[200:203], v140, s[72:73]
	global_load_dwordx4 v[224:227], v141, s[36:37]
	global_load_dwordx4 v[228:231], v140, s[72:73] offset:256
	global_load_dwordx4 v[232:235], v141, s[36:37] offset:256
	s_and_b64 vcc, exec, s[6:7]
	s_cbranch_vccz .LBB0_922
	s_barrier

; #define PG8_STAGE(bufoff, gbase, voff) do { _Pragma("unroll") for (int _i = 0; _i < 2; ++_i) \
;         __builtin_amdgcn_global_load_lds((const unsigned*)((const char*)(gbase) + (voff)[_i]), (PG8_LAS unsigned*)(lds + (bufoff) + ldsw + _i * 8192), 16, 0, 0); } while (0)
; #define PG8_LDA(dst, b, h) do { _Pragma("unroll") for (int m = 0; m < 4; ++m) _Pragma("unroll") for (int k = 0; k < 2; ++k) dst[m][k] = *(const PG8_LAS bf16x8*)(lds + PG8_SA(b, h) + aoff + m * 2048 + k * 1024); } while (0)
; #define PG8_LDB(dst, b, h) do { _Pragma("unroll") for (int n = 0; n < 2; ++n) _Pragma("unroll") for (int k = 0; k < 2; ++k) dst[n][k] = *(const PG8_LAS bf16x8*)(lds + PG8_SB(b, h) + boff + n * 2048 + k * 1024); } while (0)
; #define PG8_SCHED __builtin_amdgcn_sched_barrier(0)
; template <class Epi, class Sched, bool ALIGN_EPI = false, bool SP2 = false>
; __device__ __forceinline__ void gemm_phase(PG8_LAS unsigned char* lds, const Gemm g, const Sched& S, const Epi& E) {
;     ...
;         const bool has_next = S.next(ui + 1, nxt);
;         const char* nA = has_next ? (const char*)g.A + (size_t)nxt.pm * tstep : cA; const char* nB = has_next ? (const char*)g.Bt + (size_t)nxt.pn * tstep : cB;
;         for (int t = 0; t < nt; t += 2) {
;             const bool last = (t == nt - 2);
;             const char* a1 = cA + (size_t)(t + 1) * kstep;
;             const char* a2 = last ? nA : cA + (size_t)(t + 2) * kstep; const char* b2 = last ? nB : cB + (size_t)(t + 2) * kstep;
;             const char* a3 = a2 + kstep; const char* b3 = b2 + kstep;
;             if (last && has_next) S.a_ready(nxt);
;             if constexpr (SP2) {
;             PG8_LDB(B0, 0, 0); PG8_LDB(B1, 0, 1); PG8_SCHED; PG8_LDA(At, 0, 0); PG8_STAGE(PG8_SA(1, 1), a1 + hstep, voffA);
;     ...
; #pragma unroll
;         for (int a = 0; a < 2; ++a)
; #pragma unroll
;             for (int b = 0; b < 2; ++b)
; #pragma unroll
;                 for (int m = 0; m < 4; ++m)
; #pragma unroll
;                     for (int n = 0; n < 2; ++n) acc[a][b][m][n] = (f32x4){0.f, 0.f, 0.f, 0.f};
;         cur = nxt; cA = nA; cB = nB; ++ui;
.LBB0_1049:
	s_ashr_i32 s13, s12, 31
	s_lshl_b64 s[14:15], s[12:13], 19
	s_add_u32 s14, s84, s14
	s_addc_u32 s15, s85, s15
	s_and_b64 s[16:17], s[4:5], exec
	s_cselect_b32 s13, s15, s23
	s_cselect_b32 s19, s14, s22
	s_ashr_i32 s11, s10, 31
	s_lshl_b64 s[16:17], s[10:11], 19
	s_add_u32 s16, s29, s16
	s_addc_u32 s17, s30, s17
	s_and_b64 s[26:27], s[4:5], exec
	s_cselect_b32 s11, s17, s25
	s_cselect_b32 s21, s16, s24
	s_add_u32 s22, s22, 0x40080
	s_addc_u32 s23, s23, 0
	s_add_u32 s48, s24, 0x100
	v_mov_b32_e32 v2, 0
	s_addc_u32 s49, s25, 0
	s_mov_b32 s50, -2
	s_waitcnt lgkmcnt(0)
	v_mov_b32_e32 v3, v2
	v_mov_b32_e32 v4, v2
	v_mov_b32_e32 v5, v2
	v_mov_b32_e32 v6, v2
	v_mov_b32_e32 v7, v2
	v_mov_b32_e32 v8, v2
	v_mov_b32_e32 v9, v2
	v_mov_b32_e32 v18, v2
	v_mov_b32_e32 v19, v2
	v_mov_b32_e32 v20, v2
	v_mov_b32_e32 v21, v2
	v_mov_b32_e32 v22, v2
	v_mov_b32_e32 v23, v2
	v_mov_b32_e32 v24, v2
	v_mov_b32_e32 v25, v2
	v_mov_b32_e32 v34, v2
	v_mov_b32_e32 v35, v2
	v_mov_b32_e32 v36, v2
	v_mov_b32_e32 v37, v2
	v_mov_b32_e32 v38, v2
	v_mov_b32_e32 v39, v2
	v_mov_b32_e32 v40, v2
	v_mov_b32_e32 v41, v2
	v_mov_b32_e32 v50, v2
	v_mov_b32_e32 v51, v2
	v_mov_b32_e32 v52, v2
	v_mov_b32_e32 v53, v2
	v_mov_b32_e32 v54, v2
	v_mov_b32_e32 v55, v2
	v_mov_b32_e32 v56, v2
	v_mov_b32_e32 v57, v2
	v_mov_b32_e32 v10, v2
	v_mov_b32_e32 v11, v2
	v_mov_b32_e32 v12, v2
	v_mov_b32_e32 v13, v2
	v_mov_b32_e32 v14, v2
	v_mov_b32_e32 v15, v2
	v_mov_b32_e32 v16, v2
	v_mov_b32_e32 v17, v2
	v_mov_b32_e32 v26, v2
	v_mov_b32_e32 v27, v2
	v_mov_b32_e32 v28, v2
	v_mov_b32_e32 v29, v2
	v_mov_b32_e32 v30, v2
	v_mov_b32_e32 v31, v2
	v_mov_b32_e32 v32, v2
	v_mov_b32_e32 v33, v2
	v_mov_b32_e32 v42, v2
	v_mov_b32_e32 v43, v2
	v_mov_b32_e32 v44, v2
	v_mov_b32_e32 v45, v2
	v_mov_b32_e32 v46, v2
	v_mov_b32_e32 v47, v2
	v_mov_b32_e32 v48, v2
	v_mov_b32_e32 v49, v2
	v_mov_b32_e32 v58, v2
	v_mov_b32_e32 v59, v2
	v_mov_b32_e32 v60, v2
	v_mov_b32_e32 v61, v2
	v_mov_b32_e32 v62, v2
	v_mov_b32_e32 v63, v2
	v_mov_b32_e32 v64, v2
	v_mov_b32_e32 v65, v2
	v_mov_b32_e32 v66, v2
	v_mov_b32_e32 v67, v2
	v_mov_b32_e32 v68, v2
	v_mov_b32_e32 v69, v2
	v_mov_b32_e32 v70, v2
	v_mov_b32_e32 v71, v2
	v_mov_b32_e32 v72, v2
	v_mov_b32_e32 v73, v2
	v_mov_b32_e32 v82, v2
	v_mov_b32_e32 v83, v2
	v_mov_b32_e32 v84, v2
	v_mov_b32_e32 v85, v2
	v_mov_b32_e32 v86, v2
	v_mov_b32_e32 v87, v2
	v_mov_b32_e32 v88, v2
	v_mov_b32_e32 v89, v2
	v_mov_b32_e32 v98, v2
	v_mov_b32_e32 v99, v2
	v_mov_b32_e32 v100, v2
	v_mov_b32_e32 v101, v2
	v_mov_b32_e32 v102, v2
	v_mov_b32_e32 v103, v2
	v_mov_b32_e32 v104, v2
	v_mov_b32_e32 v105, v2
	v_mov_b32_e32 v114, v2
	v_mov_b32_e32 v115, v2
	v_mov_b32_e32 v116, v2
	v_mov_b32_e32 v117, v2
	v_mov_b32_e32 v118, v2
	v_mov_b32_e32 v119, v2
	v_mov_b32_e32 v120, v2
	v_mov_b32_e32 v121, v2
	v_mov_b32_e32 v74, v2
	v_mov_b32_e32 v75, v2
	v_mov_b32_e32 v76, v2
	v_mov_b32_e32 v77, v2
	v_mov_b32_e32 v78, v2
	v_mov_b32_e32 v79, v2
	v_mov_b32_e32 v80, v2
	v_mov_b32_e32 v81, v2
	v_mov_b32_e32 v90, v2
	v_mov_b32_e32 v91, v2
	v_mov_b32_e32 v92, v2
	v_mov_b32_e32 v93, v2
	v_mov_b32_e32 v94, v2
	v_mov_b32_e32 v95, v2
	v_mov_b32_e32 v96, v2
	v_mov_b32_e32 v97, v2
	v_mov_b32_e32 v106, v2
	v_mov_b32_e32 v107, v2
	v_mov_b32_e32 v108, v2
	v_mov_b32_e32 v109, v2
	v_mov_b32_e32 v110, v2
	v_mov_b32_e32 v111, v2
	v_mov_b32_e32 v112, v2
	v_mov_b32_e32 v113, v2
	v_mov_b32_e32 v122, v2
	v_mov_b32_e32 v123, v2
	v_mov_b32_e32 v124, v2
	v_mov_b32_e32 v125, v2
	v_mov_b32_e32 v126, v2
	v_mov_b32_e32 v127, v2
	v_mov_b32_e32 v128, v2
	v_mov_b32_e32 v129, v2
	s_add_u32 s24, s22, 0xfffc0080
	s_addc_u32 s25, s23, -1
	s_add_i32 s51, 0, 0x10000
	s_cmp_eq_u32 s50, 12
	s_cselect_b32 s27, s13, s25
	s_cselect_b32 s26, s19, s24
	s_cselect_b32 s25, s11, s49
	s_cselect_b32 s24, s21, s48
	s_add_i32 s55, 0, 0x14000
	v_add_u32_e32 v156, s51, v149
	v_add_u32_e32 v172, s55, v149
.LBB0_1050:
	ds_read_b128 v[138:141], v156
	ds_read_b128 v[144:147], v156 offset:1024
	ds_read_b128 v[152:155], v156 offset:2048
	ds_read_b128 v[156:159], v156 offset:3072
	ds_read_b128 v[160:163], v172
	ds_read_b128 v[164:167], v172 offset:1024
	ds_read_b128 v[168:171], v172 offset:2048
	ds_read_b128 v[172:175], v172 offset:3072
	v_lshl_add_u64 v[204:205], s[22:23], 0, v[136:137]
	s_add_i32 m0, s38, 0xc000
	ds_read_b128 v[176:179], v151
	ds_read_b128 v[180:183], v151 offset:1024
	ds_read_b128 v[184:187], v151 offset:2048
	ds_read_b128 v[188:191], v151 offset:3072
	ds_read_b128 v[192:195], v151 offset:4096
	ds_read_b128 v[196:199], v151 offset:5120
	ds_read_b128 v[200:203], v151 offset:6144
	ds_read_b128 v[224:227], v151 offset:7168
	global_load_lds_dwordx4 v[204:205], off
	v_lshl_add_u64 v[204:205], s[22:23], 0, v[142:143]
	s_add_i32 m0, s38, 0xe000
	s_nop 0
	global_load_lds_dwordx4 v[204:205], off
	s_waitcnt vmcnt(8)
	s_waitcnt lgkmcnt(0)
	s_barrier
; #define PG8_STAGE(bufoff, gbase, voff) do { _Pragma("unroll") for (int _i = 0; _i < 2; ++_i) \
;         __builtin_amdgcn_global_load_lds((const unsigned*)((const char*)(gbase) + (voff)[_i]), (PG8_LAS unsigned*)(lds + (bufoff) + ldsw + _i * 8192), 16, 0, 0); } while (0)
; #define PG8_LDA(dst, b, h) do { _Pragma("unroll") for (int m = 0; m < 4; ++m) _Pragma("unroll") for (int k = 0; k < 2; ++k) dst[m][k] = *(const PG8_LAS bf16x8*)(lds + PG8_SA(b, h) + aoff + m * 2048 + k * 1024); } while (0)
; #define PG8_MMA(ai, bj, At, Bt) do { __builtin_amdgcn_s_setprio(1); _Pragma("unroll") for (int m = 0; m < 4; ++m) _Pragma("unroll") for (int n = 0; n < 2; ++n) _Pragma("unroll") for (int k = 0; k < 2; ++k) \
;         acc[ai][bj][m][n] = __builtin_amdgcn_mfma_f32_16x16x32_bf16(Bt[n][k], At[m][k], acc[ai][bj][m][n], 0, 0, 0); __builtin_amdgcn_s_setprio(0); } while (0)
; #define PG8_WAIT_V(n) asm volatile("s_waitcnt vmcnt(" #n ")" ::: "memory")
; #define PG8_WAIT_L(n) asm volatile("s_waitcnt lgkmcnt(" #n ")" ::: "memory")
; #define PG8_BAR __builtin_amdgcn_s_barrier()
; #define PG8_SCHED __builtin_amdgcn_sched_barrier(0)
; template <class Epi, class Sched, bool ALIGN_EPI = false, bool SP2 = false>
; __device__ __forceinline__ void gemm_phase(PG8_LAS unsigned char* lds, const Gemm g, const Sched& S, const Epi& E) {
;     ...
;             PG8_WAIT_V(8); PG8_WAIT_L(0); PG8_BAR; PG8_MMA(0, 0, At, B0); PG8_MMA(0, 1, At, B1); PG8_BAR; PG8_SCHED;
;             PG8_LDA(At, 0, 1); PG8_STAGE(PG8_SB(0, 0), b2, voffB); PG8_STAGE(PG8_SB(0, 1), b2 + hstep, voffB); PG8_STAGE(PG8_SA(0, 0), a2, voffA);
;             PG8_WAIT_V(8); PG8_WAIT_L(0); PG8_BAR; PG8_MMA(1, 0, At, B0); PG8_MMA(1, 1, At, B1); PG8_BAR; PG8_SCHED;
	s_setprio 1
	s_waitcnt lgkmcnt(0)
	v_mfma_f32_16x16x32_bf16 v[126:129], v[138:141], v[176:179], v[126:129]
	v_mfma_f32_16x16x32_bf16 v[122:125], v[152:155], v[176:179], v[122:125]
	v_mfma_f32_16x16x32_bf16 v[110:113], v[138:141], v[184:187], v[110:113]
	v_mfma_f32_16x16x32_bf16 v[106:109], v[152:155], v[184:187], v[106:109]
	v_mfma_f32_16x16x32_bf16 v[94:97], v[138:141], v[192:195], v[94:97]
	v_mfma_f32_16x16x32_bf16 v[90:93], v[152:155], v[192:195], v[90:93]
	v_mfma_f32_16x16x32_bf16 v[78:81], v[138:141], v[200:203], v[78:81]
	v_mfma_f32_16x16x32_bf16 v[74:77], v[152:155], v[200:203], v[74:77]
	v_mfma_f32_16x16x32_bf16 v[126:129], v[144:147], v[180:183], v[126:129]
	v_mfma_f32_16x16x32_bf16 v[122:125], v[156:159], v[180:183], v[122:125]
	v_mfma_f32_16x16x32_bf16 v[110:113], v[144:147], v[188:191], v[110:113]
	v_mfma_f32_16x16x32_bf16 v[106:109], v[156:159], v[188:191], v[106:109]
	v_mfma_f32_16x16x32_bf16 v[94:97], v[144:147], v[196:199], v[94:97]
	v_mfma_f32_16x16x32_bf16 v[90:93], v[156:159], v[196:199], v[90:93]
	v_mfma_f32_16x16x32_bf16 v[78:81], v[144:147], v[224:227], v[78:81]
	v_mfma_f32_16x16x32_bf16 v[74:77], v[156:159], v[224:227], v[74:77]
	s_setprio 0
	s_setprio 1
	v_mfma_f32_16x16x32_bf16 v[118:121], v[160:163], v[176:179], v[118:121]
	v_mfma_f32_16x16x32_bf16 v[114:117], v[168:171], v[176:179], v[114:117]
	v_mfma_f32_16x16x32_bf16 v[102:105], v[160:163], v[184:187], v[102:105]
	v_mfma_f32_16x16x32_bf16 v[98:101], v[168:171], v[184:187], v[98:101]
	v_mfma_f32_16x16x32_bf16 v[86:89], v[160:163], v[192:195], v[86:89]
	v_mfma_f32_16x16x32_bf16 v[82:85], v[168:171], v[192:195], v[82:85]
	v_mfma_f32_16x16x32_bf16 v[70:73], v[160:163], v[200:203], v[70:73]
	v_mfma_f32_16x16x32_bf16 v[66:69], v[168:171], v[200:203], v[66:69]
	v_mfma_f32_16x16x32_bf16 v[118:121], v[164:167], v[180:183], v[118:121]
	v_mfma_f32_16x16x32_bf16 v[114:117], v[172:175], v[180:183], v[114:117]
	v_mfma_f32_16x16x32_bf16 v[102:105], v[164:167], v[188:191], v[102:105]
	v_mfma_f32_16x16x32_bf16 v[98:101], v[172:175], v[188:191], v[98:101]
	v_mfma_f32_16x16x32_bf16 v[86:89], v[164:167], v[196:199], v[86:89]
	v_mfma_f32_16x16x32_bf16 v[82:85], v[172:175], v[196:199], v[82:85]
	v_mfma_f32_16x16x32_bf16 v[70:73], v[164:167], v[224:227], v[70:73]
	v_mfma_f32_16x16x32_bf16 v[66:69], v[172:175], v[224:227], v[66:69]
	s_setprio 0
	s_barrier
	s_add_i32 s51, s51, s31
	v_lshl_add_u64 v[204:205], s[24:25], 0, v[0:1]
	s_mov_b32 m0, s51
	ds_read_b128 v[176:179], v151 offset:16384
	ds_read_b128 v[180:183], v151 offset:17408
	ds_read_b128 v[184:187], v151 offset:18432
	ds_read_b128 v[188:191], v151 offset:19456
	ds_read_b128 v[192:195], v151 offset:20480
	ds_read_b128 v[196:199], v151 offset:21504
	ds_read_b128 v[200:203], v151 offset:22528
	ds_read_b128 v[224:227], v151 offset:23552
	global_load_lds_dwordx4 v[204:205], off
	s_add_i32 m0, s51, 0x2000
	s_add_u32 s52, s24, 0x40000
	v_lshl_add_u64 v[228:229], s[24:25], 0, v[134:135]
	s_addc_u32 s53, s25, 0
	s_add_i32 s51, s55, s31
	global_load_lds_dwordx4 v[228:229], off
	v_lshl_add_u64 v[230:231], s[52:53], 0, v[0:1]
	s_mov_b32 m0, s51
	v_lshl_add_u64 v[232:233], s[26:27], 0, v[132:133]
	global_load_lds_dwordx4 v[230:231], off
	v_lshl_add_u64 v[230:231], s[52:53], 0, v[134:135]
	s_add_i32 m0, s51, 0x2000
	s_nop 0
	global_load_lds_dwordx4 v[230:231], off
	v_lshl_add_u64 v[230:231], s[26:27], 0, v[130:131]
	s_mov_b32 m0, s38
	s_nop 0
	global_load_lds_dwordx4 v[230:231], off
	s_mov_b32 m0, s39
	s_nop 0
	global_load_lds_dwordx4 v[232:233], off
	s_waitcnt vmcnt(8)
	s_waitcnt lgkmcnt(0)
	s_barrier
	s_setprio 1
	s_waitcnt lgkmcnt(0)
	v_mfma_f32_16x16x32_bf16 v[62:65], v[138:141], v[176:179], v[62:65]
	v_mfma_f32_16x16x32_bf16 v[58:61], v[152:155], v[176:179], v[58:61]
	v_mfma_f32_16x16x32_bf16 v[46:49], v[138:141], v[184:187], v[46:49]
	v_mfma_f32_16x16x32_bf16 v[42:45], v[152:155], v[184:187], v[42:45]
	v_mfma_f32_16x16x32_bf16 v[30:33], v[138:141], v[192:195], v[30:33]
	v_mfma_f32_16x16x32_bf16 v[26:29], v[152:155], v[192:195], v[26:29]
	v_mfma_f32_16x16x32_bf16 v[14:17], v[138:141], v[200:203], v[14:17]
	v_mfma_f32_16x16x32_bf16 v[10:13], v[152:155], v[200:203], v[10:13]
	v_mfma_f32_16x16x32_bf16 v[62:65], v[144:147], v[180:183], v[62:65]
	v_mfma_f32_16x16x32_bf16 v[58:61], v[156:159], v[180:183], v[58:61]
	v_mfma_f32_16x16x32_bf16 v[46:49], v[144:147], v[188:191], v[46:49]
	v_mfma_f32_16x16x32_bf16 v[42:45], v[156:159], v[188:191], v[42:45]
	v_mfma_f32_16x16x32_bf16 v[30:33], v[144:147], v[196:199], v[30:33]
	v_mfma_f32_16x16x32_bf16 v[26:29], v[156:159], v[196:199], v[26:29]
	v_mfma_f32_16x16x32_bf16 v[14:17], v[144:147], v[224:227], v[14:17]
	v_mfma_f32_16x16x32_bf16 v[10:13], v[156:159], v[224:227], v[10:13]
	s_setprio 0
	s_setprio 1
	v_mfma_f32_16x16x32_bf16 v[54:57], v[160:163], v[176:179], v[54:57]
	v_mfma_f32_16x16x32_bf16 v[50:53], v[168:171], v[176:179], v[50:53]
	v_mfma_f32_16x16x32_bf16 v[38:41], v[160:163], v[184:187], v[38:41]
	v_mfma_f32_16x16x32_bf16 v[34:37], v[168:171], v[184:187], v[34:37]
	v_mfma_f32_16x16x32_bf16 v[22:25], v[160:163], v[192:195], v[22:25]
	v_mfma_f32_16x16x32_bf16 v[18:21], v[168:171], v[192:195], v[18:21]
	v_mfma_f32_16x16x32_bf16 v[6:9], v[160:163], v[200:203], v[6:9]
	v_mfma_f32_16x16x32_bf16 v[2:5], v[168:171], v[200:203], v[2:5]
	v_mfma_f32_16x16x32_bf16 v[54:57], v[164:167], v[180:183], v[54:57]
	v_mfma_f32_16x16x32_bf16 v[50:53], v[172:175], v[180:183], v[50:53]
	v_mfma_f32_16x16x32_bf16 v[38:41], v[164:167], v[188:191], v[38:41]
	v_mfma_f32_16x16x32_bf16 v[34:37], v[172:175], v[188:191], v[34:37]
	v_mfma_f32_16x16x32_bf16 v[22:25], v[164:167], v[196:199], v[22:25]
	v_mfma_f32_16x16x32_bf16 v[18:21], v[172:175], v[196:199], v[18:21]
	v_mfma_f32_16x16x32_bf16 v[6:9], v[164:167], v[224:227], v[6:9]
	v_mfma_f32_16x16x32_bf16 v[2:5], v[172:175], v[224:227], v[2:5]
	s_setprio 0
	s_barrier
; #define PG8_STAGE(bufoff, gbase, voff) do { _Pragma("unroll") for (int _i = 0; _i < 2; ++_i) \
;         __builtin_amdgcn_global_load_lds((const unsigned*)((const char*)(gbase) + (voff)[_i]), (PG8_LAS unsigned*)(lds + (bufoff) + ldsw + _i * 8192), 16, 0, 0); } while (0)
; #define PG8_LDA(dst, b, h) do { _Pragma("unroll") for (int m = 0; m < 4; ++m) _Pragma("unroll") for (int k = 0; k < 2; ++k) dst[m][k] = *(const PG8_LAS bf16x8*)(lds + PG8_SA(b, h) + aoff + m * 2048 + k * 1024); } while (0)
; #define PG8_LDB(dst, b, h) do { _Pragma("unroll") for (int n = 0; n < 2; ++n) _Pragma("unroll") for (int k = 0; k < 2; ++k) dst[n][k] = *(const PG8_LAS bf16x8*)(lds + PG8_SB(b, h) + boff + n * 2048 + k * 1024); } while (0)
; #define PG8_MMA(ai, bj, At, Bt) do { __builtin_amdgcn_s_setprio(1); _Pragma("unroll") for (int m = 0; m < 4; ++m) _Pragma("unroll") for (int n = 0; n < 2; ++n) _Pragma("unroll") for (int k = 0; k < 2; ++k) \
;         acc[ai][bj][m][n] = __builtin_amdgcn_mfma_f32_16x16x32_bf16(Bt[n][k], At[m][k], acc[ai][bj][m][n], 0, 0, 0); __builtin_amdgcn_s_setprio(0); } while (0)
; #define PG8_WAIT_V(n) asm volatile("s_waitcnt vmcnt(" #n ")" ::: "memory")
; #define PG8_WAIT_L(n) asm volatile("s_waitcnt lgkmcnt(" #n ")" ::: "memory")
; #define PG8_BAR __builtin_amdgcn_s_barrier()
; #define PG8_SCHED __builtin_amdgcn_sched_barrier(0)
; template <class Epi, class Sched, bool ALIGN_EPI = false, bool SP2 = false>
; __device__ __forceinline__ void gemm_phase(PG8_LAS unsigned char* lds, const Gemm g, const Sched& S, const Epi& E) {
;     ...
;             PG8_LDB(B0, 1, 0); PG8_LDB(B1, 1, 1); PG8_SCHED; PG8_LDA(At, 1, 0); PG8_STAGE(PG8_SA(0, 1), a2 + hstep, voffA);
;             PG8_WAIT_V(8); PG8_WAIT_L(0); PG8_BAR; PG8_MMA(0, 0, At, B0); PG8_MMA(0, 1, At, B1); PG8_BAR; PG8_SCHED;
;             PG8_LDA(At, 1, 1); PG8_STAGE(PG8_SB(1, 0), b3, voffB); PG8_STAGE(PG8_SB(1, 1), b3 + hstep, voffB); PG8_STAGE(PG8_SA(1, 0), a3, voffA);
	s_add_i32 s51, 0, 0x18000
	s_add_i32 s52, 0, 0x1c000
	v_add_u32_e32 v156, s51, v149
	v_add_u32_e32 v172, s52, v149
	ds_read_b128 v[138:141], v156
	ds_read_b128 v[144:147], v156 offset:1024
	ds_read_b128 v[152:155], v156 offset:2048
	ds_read_b128 v[156:159], v156 offset:3072
	ds_read_b128 v[160:163], v172
	ds_read_b128 v[164:167], v172 offset:1024
	ds_read_b128 v[168:171], v172 offset:2048
	ds_read_b128 v[172:175], v172 offset:3072
	s_add_u32 s26, s26, 0x40000
	s_addc_u32 s27, s27, 0
	s_mov_b32 m0, s41
	v_lshl_add_u64 v[234:235], s[26:27], 0, v[130:131]
	ds_read_b128 v[176:179], v151 offset:32768
	ds_read_b128 v[180:183], v151 offset:33792
	ds_read_b128 v[184:187], v151 offset:34816
	ds_read_b128 v[188:191], v151 offset:35840
	ds_read_b128 v[192:195], v151 offset:36864
	ds_read_b128 v[196:199], v151 offset:37888
	ds_read_b128 v[200:203], v151 offset:38912
	ds_read_b128 v[224:227], v151 offset:39936
	global_load_lds_dwordx4 v[234:235], off
	v_lshl_add_u64 v[234:235], s[26:27], 0, v[132:133]
	s_mov_b32 m0, s42
	s_nop 0
	global_load_lds_dwordx4 v[234:235], off
	s_waitcnt vmcnt(8)
	s_waitcnt lgkmcnt(0)
	s_barrier
	s_setprio 1
	s_waitcnt lgkmcnt(0)
	v_mfma_f32_16x16x32_bf16 v[126:129], v[138:141], v[176:179], v[126:129]
	v_mfma_f32_16x16x32_bf16 v[122:125], v[152:155], v[176:179], v[122:125]
	v_mfma_f32_16x16x32_bf16 v[110:113], v[138:141], v[184:187], v[110:113]
	v_mfma_f32_16x16x32_bf16 v[106:109], v[152:155], v[184:187], v[106:109]
	v_mfma_f32_16x16x32_bf16 v[94:97], v[138:141], v[192:195], v[94:97]
	v_mfma_f32_16x16x32_bf16 v[90:93], v[152:155], v[192:195], v[90:93]
	v_mfma_f32_16x16x32_bf16 v[78:81], v[138:141], v[200:203], v[78:81]
	v_mfma_f32_16x16x32_bf16 v[74:77], v[152:155], v[200:203], v[74:77]
	v_mfma_f32_16x16x32_bf16 v[126:129], v[144:147], v[180:183], v[126:129]
	v_mfma_f32_16x16x32_bf16 v[122:125], v[156:159], v[180:183], v[122:125]
	v_mfma_f32_16x16x32_bf16 v[110:113], v[144:147], v[188:191], v[110:113]
	v_mfma_f32_16x16x32_bf16 v[106:109], v[156:159], v[188:191], v[106:109]
	v_mfma_f32_16x16x32_bf16 v[94:97], v[144:147], v[196:199], v[94:97]
	v_mfma_f32_16x16x32_bf16 v[90:93], v[156:159], v[196:199], v[90:93]
	v_mfma_f32_16x16x32_bf16 v[78:81], v[144:147], v[224:227], v[78:81]
	v_mfma_f32_16x16x32_bf16 v[74:77], v[156:159], v[224:227], v[74:77]
	s_setprio 0
	s_setprio 1
	v_mfma_f32_16x16x32_bf16 v[118:121], v[160:163], v[176:179], v[118:121]
	v_mfma_f32_16x16x32_bf16 v[114:117], v[168:171], v[176:179], v[114:117]
	v_mfma_f32_16x16x32_bf16 v[102:105], v[160:163], v[184:187], v[102:105]
	v_mfma_f32_16x16x32_bf16 v[98:101], v[168:171], v[184:187], v[98:101]
	v_mfma_f32_16x16x32_bf16 v[86:89], v[160:163], v[192:195], v[86:89]
	v_mfma_f32_16x16x32_bf16 v[82:85], v[168:171], v[192:195], v[82:85]
	v_mfma_f32_16x16x32_bf16 v[70:73], v[160:163], v[200:203], v[70:73]
	v_mfma_f32_16x16x32_bf16 v[66:69], v[168:171], v[200:203], v[66:69]
	v_mfma_f32_16x16x32_bf16 v[118:121], v[164:167], v[180:183], v[118:121]
	v_mfma_f32_16x16x32_bf16 v[114:117], v[172:175], v[180:183], v[114:117]
	v_mfma_f32_16x16x32_bf16 v[102:105], v[164:167], v[188:191], v[102:105]
	v_mfma_f32_16x16x32_bf16 v[98:101], v[172:175], v[188:191], v[98:101]
	v_mfma_f32_16x16x32_bf16 v[86:89], v[164:167], v[196:199], v[86:89]
	v_mfma_f32_16x16x32_bf16 v[82:85], v[172:175], v[196:199], v[82:85]
	v_mfma_f32_16x16x32_bf16 v[70:73], v[164:167], v[224:227], v[70:73]
	v_mfma_f32_16x16x32_bf16 v[66:69], v[172:175], v[224:227], v[66:69]
	s_setprio 0
	s_barrier
	s_add_i32 s26, s51, s31
	v_lshl_add_u64 v[204:205], v[204:205], 0, s[86:87]
	s_mov_b32 m0, s26
	ds_read_b128 v[176:179], v151 offset:49152
	ds_read_b128 v[180:183], v151 offset:50176
	ds_read_b128 v[184:187], v151 offset:51200
	ds_read_b128 v[188:191], v151 offset:52224
	ds_read_b128 v[192:195], v151 offset:53248
	ds_read_b128 v[196:199], v151 offset:54272
	ds_read_b128 v[200:203], v151 offset:55296
	ds_read_b128 v[224:227], v151 offset:56320
	global_load_lds_dwordx4 v[204:205], off
	s_add_i32 m0, s26, 0x2000
	s_add_u32 s24, s24, 0x40080
	v_lshl_add_u64 v[204:205], v[228:229], 0, s[86:87]
	s_addc_u32 s25, s25, 0
	s_add_i32 s26, s52, s31
	global_load_lds_dwordx4 v[204:205], off
	v_lshl_add_u64 v[204:205], s[24:25], 0, v[0:1]
	s_mov_b32 m0, s26
	s_nop 0
	global_load_lds_dwordx4 v[204:205], off
	v_lshl_add_u64 v[204:205], s[24:25], 0, v[134:135]
	s_add_i32 m0, s26, 0x2000
	s_nop 0
	global_load_lds_dwordx4 v[204:205], off
	v_lshl_add_u64 v[204:205], v[230:231], 0, s[86:87]
	s_mov_b32 m0, s44
	s_nop 0
	global_load_lds_dwordx4 v[204:205], off
	v_lshl_add_u64 v[204:205], v[232:233], 0, s[86:87]
	s_mov_b32 m0, s45
	s_nop 0
	global_load_lds_dwordx4 v[204:205], off
	s_waitcnt vmcnt(8)
	s_waitcnt lgkmcnt(0)
	s_barrier
; #define PG8_STAGE(bufoff, gbase, voff) do { _Pragma("unroll") for (int _i = 0; _i < 2; ++_i) \
;         __builtin_amdgcn_global_load_lds((const unsigned*)((const char*)(gbase) + (voff)[_i]), (PG8_LAS unsigned*)(lds + (bufoff) + ldsw + _i * 8192), 16, 0, 0); } while (0)
; template <class Epi, class Sched, bool ALIGN_EPI = false, bool SP2 = false>
; __device__ __forceinline__ void gemm_phase(PG8_LAS unsigned char* lds, const Gemm g, const Sched& S, const Epi& E) {
;     ...
;             PG8_WAIT_V(8); PG8_WAIT_L(0); PG8_BAR; PG8_MMA(1, 0, At, B0); PG8_MMA(1, 1, At, B1); PG8_BAR; PG8_SCHED;
;             } else {
;             PG8_LDB(B0, 0, 0); PG8_SCHED; PG8_LDA(At, 0, 0); PG8_STAGE(PG8_SA(1, 1), a1 + hstep, voffA);
;             PG8_WAIT_L(8); PG8_BAR; PG8_WAIT_L(0); PG8_MMA(0, 0, At, B0); PG8_BAR; PG8_SCHED;
;             PG8_LDB(B1, 0, 1); PG8_STAGE(PG8_SB(0, 0), b2, voffB);
;             PG8_BAR; PG8_WAIT_L(0); PG8_MMA(0, 1, At, B1); PG8_BAR;
;             PG8_LDA(At, 0, 1); PG8_STAGE(PG8_SA(0, 0), a2, voffA);
;             PG8_BAR; PG8_WAIT_L(0); PG8_MMA(1, 0, At, B0); PG8_BAR; PG8_SCHED;
;             PG8_STAGE(PG8_SB(0, 1), b2 + hstep, voffB);
;             PG8_WAIT_V(6); PG8_BAR; PG8_MMA(1, 1, At, B1); PG8_BAR;
;             PG8_LDB(B0, 1, 0); PG8_SCHED; PG8_LDA(At, 1, 0); PG8_STAGE(PG8_SA(0, 1), a2 + hstep, voffA);
;             PG8_WAIT_L(8); PG8_BAR; PG8_WAIT_L(0); PG8_MMA(0, 0, At, B0); PG8_BAR; PG8_SCHED;
;             PG8_LDB(B1, 1, 1); PG8_STAGE(PG8_SB(1, 0), b3, voffB);
;             PG8_BAR; PG8_WAIT_L(0); PG8_MMA(0, 1, At, B1); PG8_BAR;
;             PG8_LDA(At, 1, 1); PG8_STAGE(PG8_SA(1, 0), a3, voffA);
;             PG8_BAR; PG8_WAIT_L(0); PG8_MMA(1, 0, At, B0); PG8_BAR; PG8_SCHED;
;             PG8_STAGE(PG8_SB(1, 1), b3 + hstep, voffB);
;             PG8_WAIT_V(6); PG8_BAR; PG8_MMA(1, 1, At, B1); PG8_BAR;
;             }
;         }
;         if constexpr (ALIGN_EPI) { if (wr == 0) PG8_BAR; }
;     __device__ __forceinline__ void operator()(const f32x4 (&acc)[2][2][4][2], const Unit& u, int wr, int wc, int fr, int fq) const {
;     ...
;                 const int row = row0 + ai * 128 + m * 16; float p = 0.f;
; #pragma unroll
;                 for (int bj = 0; bj < 2; ++bj) {
;                     const size_t off = (size_t)row * D + col0 + bj * 128;
;                     const u32x4 xx = *(const u32x4*)(xb + off);
	s_setprio 1
	s_waitcnt lgkmcnt(0)
	v_mfma_f32_16x16x32_bf16 v[62:65], v[138:141], v[176:179], v[62:65]
	v_mfma_f32_16x16x32_bf16 v[58:61], v[152:155], v[176:179], v[58:61]
	v_mfma_f32_16x16x32_bf16 v[46:49], v[138:141], v[184:187], v[46:49]
	v_mfma_f32_16x16x32_bf16 v[42:45], v[152:155], v[184:187], v[42:45]
	v_mfma_f32_16x16x32_bf16 v[30:33], v[138:141], v[192:195], v[30:33]
	v_mfma_f32_16x16x32_bf16 v[26:29], v[152:155], v[192:195], v[26:29]
	v_mfma_f32_16x16x32_bf16 v[14:17], v[138:141], v[200:203], v[14:17]
	v_mfma_f32_16x16x32_bf16 v[10:13], v[152:155], v[200:203], v[10:13]
	v_mfma_f32_16x16x32_bf16 v[62:65], v[144:147], v[180:183], v[62:65]
	v_mfma_f32_16x16x32_bf16 v[58:61], v[156:159], v[180:183], v[58:61]
	v_mfma_f32_16x16x32_bf16 v[46:49], v[144:147], v[188:191], v[46:49]
	v_mfma_f32_16x16x32_bf16 v[42:45], v[156:159], v[188:191], v[42:45]
	v_mfma_f32_16x16x32_bf16 v[30:33], v[144:147], v[196:199], v[30:33]
	v_mfma_f32_16x16x32_bf16 v[26:29], v[156:159], v[196:199], v[26:29]
	v_mfma_f32_16x16x32_bf16 v[14:17], v[144:147], v[224:227], v[14:17]
	v_mfma_f32_16x16x32_bf16 v[10:13], v[156:159], v[224:227], v[10:13]
	s_setprio 0
	s_setprio 1
	v_mfma_f32_16x16x32_bf16 v[54:57], v[160:163], v[176:179], v[54:57]
	v_mfma_f32_16x16x32_bf16 v[50:53], v[168:171], v[176:179], v[50:53]
	v_mfma_f32_16x16x32_bf16 v[38:41], v[160:163], v[184:187], v[38:41]
	v_mfma_f32_16x16x32_bf16 v[34:37], v[168:171], v[184:187], v[34:37]
	v_mfma_f32_16x16x32_bf16 v[22:25], v[160:163], v[192:195], v[22:25]
	v_mfma_f32_16x16x32_bf16 v[18:21], v[168:171], v[192:195], v[18:21]
	v_mfma_f32_16x16x32_bf16 v[6:9], v[160:163], v[200:203], v[6:9]
	v_mfma_f32_16x16x32_bf16 v[2:5], v[168:171], v[200:203], v[2:5]
	v_mfma_f32_16x16x32_bf16 v[54:57], v[164:167], v[180:183], v[54:57]
	v_mfma_f32_16x16x32_bf16 v[50:53], v[172:175], v[180:183], v[50:53]
	v_mfma_f32_16x16x32_bf16 v[38:41], v[164:167], v[188:191], v[38:41]
	v_mfma_f32_16x16x32_bf16 v[34:37], v[172:175], v[188:191], v[34:37]
	v_mfma_f32_16x16x32_bf16 v[22:25], v[164:167], v[196:199], v[22:25]
	v_mfma_f32_16x16x32_bf16 v[18:21], v[172:175], v[196:199], v[18:21]
	v_mfma_f32_16x16x32_bf16 v[6:9], v[164:167], v[224:227], v[6:9]
	v_mfma_f32_16x16x32_bf16 v[2:5], v[172:175], v[224:227], v[2:5]
	s_setprio 0
	s_add_i32 s50, s50, 2
	s_add_u32 s22, s22, 0x100
	s_addc_u32 s23, s23, 0
	s_add_u32 s48, s48, 0x100
	s_addc_u32 s49, s49, 0
	s_add_u32 s24, s22, 0xfffc0080
	s_addc_u32 s25, s23, -1
	s_add_i32 s51, 0, 0x10000
	s_cmp_eq_u32 s50, 12
	s_cselect_b32 s27, s13, s25
	s_cselect_b32 s26, s19, s24
	s_cselect_b32 s25, s11, s49
	s_cselect_b32 s24, s21, s48
	s_add_i32 s55, 0, 0x14000
	v_add_u32_e32 v156, s51, v149
	v_add_u32_e32 v172, s55, v149
	s_cmp_gt_u32 s50, 13
	s_barrier
	s_cbranch_scc0 .LBB0_1050
	v_lshl_add_u32 v138, s20, 8, v148
	v_lshl_or_b32 v139, s18, 8, v150
	v_lshlrev_b32_e32 v138, 11, v138
	v_lshl_add_u32 v138, v139, 1, v138
	global_load_dwordx4 v[152:155], v138, s[34:35]
	global_load_dwordx4 v[156:159], v138, s[34:35] offset:256
	v_add_u32_e32 v139, 0x8000, v138
	global_load_dwordx4 v[160:163], v139, s[34:35]
	global_load_dwordx4 v[164:167], v139, s[34:35] offset:256
	v_add_u32_e32 v139, 0x10000, v138
	global_load_dwordx4 v[168:171], v139, s[34:35]
	global_load_dwordx4 v[172:175], v139, s[34:35] offset:256
	v_add_u32_e32 v139, 0x18000, v138
	global_load_dwordx4 v[176:179], v139, s[34:35]
	global_load_dwordx4 v[180:183], v139, s[34:35] offset:256
	v_add_u32_e32 v139, 0x40000, v138
	global_load_dwordx4 v[184:187], v139, s[34:35]
	global_load_dwordx4 v[188:191], v139, s[34:35] offset:256
	v_add_u32_e32 v139, 0x48000, v138
	global_load_dwordx4 v[192:195], v139, s[34:35]
	global_load_dwordx4 v[196:199], v139, s[34:35] offset:256
	v_add_u32_e32 v139, 0x50000, v138
	global_load_dwordx4 v[200:203], v139, s[34:35]
	global_load_dwordx4 v[224:227], v139, s[34:35] offset:256
	v_add_u32_e32 v139, 0x58000, v138
	global_load_dwordx4 v[228:231], v139, s[34:35]
	global_load_dwordx4 v[232:235], v139, s[34:35] offset:256
	s_and_b64 vcc, exec, s[8:9]
	s_cbranch_vccz .LBB0_1053
	s_barrier
